# row passes: 2-deep prefetch (two rows in flight, alternating register sets) + GLA-C reduction batching + pk_add removal
# baseline (speedup 1.0000x reference)
.LBB0_520:
	s_cmp_lt_i32 s88, 4
	s_cselect_b64 s[0:1], -1, 0
	s_and_b64 s[6:7], s[0:1], s[2:3]
	s_andn2_b64 vcc, exec, s[6:7]
	s_cbranch_vccnz .LBB0_526
	s_lshl_b32 s2, s66, 3
	s_lshl_b32 s0, s66, 7
	s_and_b32 s0, s0, 0xfffff000
	s_and_b32 s1, s2, 0xf8
	s_add_i32 s3, s0, 0x1000
	s_or_b32 s4, s0, s1
	s_cmpk_eq_i32 s68, 0x100
	s_cselect_b64 s[8:9], -1, 0
	s_and_b64 s[0:1], s[8:9], exec
	s_cselect_b32 s2, s4, s2
	s_cselect_b32 s12, s3, 0x8000
	s_add_i32 s13, s2, s96
	s_cmp_ge_i32 s13, s12
	s_cbranch_scc1 .LBB0_526
	v_lshlrev_b32_e32 v14, 4, v177
	global_load_dwordx4 v[2:5], v14, s[60:61]
	global_load_dwordx4 v[6:9], v14, s[60:61] offset:1024
	global_load_dwordx4 v[10:13], v14, s[60:61] offset:2048
	s_nop 0
	global_load_dwordx4 v[14:17], v14, s[60:61] offset:3072
	v_mbcnt_lo_u32_b32 v18, -1, 0
	v_mbcnt_hi_u32_b32 v18, -1, v18
	v_and_b32_e32 v19, 64, v18
	v_add_u32_e32 v19, 64, v19
	v_xor_b32_e32 v20, 1, v18
	v_cmp_lt_i32_e32 vcc, v20, v19
	v_readlane_b32 s4, v252, 2
	s_lshl_b32 s3, s68, 3
	v_cndmask_b32_e32 v20, v18, v20, vcc
	v_lshlrev_b32_e32 v26, 2, v20
	v_xor_b32_e32 v20, 2, v18
	v_cmp_lt_i32_e32 vcc, v20, v19
	v_readlane_b32 s5, v252, 3
	s_and_b64 s[0:1], s[8:9], exec
	v_cndmask_b32_e32 v20, v18, v20, vcc
	v_lshlrev_b32_e32 v27, 2, v20
	v_xor_b32_e32 v20, 4, v18
	v_cmp_lt_i32_e32 vcc, v20, v19
	s_cselect_b32 s14, 0x100, s3
	s_lshl_b32 s3, s66, 8
	v_cndmask_b32_e32 v20, v18, v20, vcc
	v_lshlrev_b32_e32 v28, 2, v20
	v_xor_b32_e32 v20, 8, v18
	v_cmp_lt_i32_e32 vcc, v20, v19
	s_and_b32 s3, s3, 0xffffe000
	s_add_i32 s3, s96, s3
	v_cndmask_b32_e32 v20, v18, v20, vcc
	v_lshlrev_b32_e32 v29, 2, v20
	v_xor_b32_e32 v20, 16, v18
	v_cmp_lt_i32_e32 vcc, v20, v19
	v_cmp_eq_u32_e64 s[0:1], 0, v177
	s_mov_b32 s16, 0xffff0000
	v_cndmask_b32_e32 v20, v18, v20, vcc
	v_lshlrev_b32_e32 v30, 2, v20
	v_xor_b32_e32 v20, 32, v18
	v_cmp_lt_i32_e32 vcc, v20, v19
	v_mov_b32_e32 v19, 0
	v_mov_b32_e32 v32, 0x358637bd
	v_cndmask_b32_e32 v18, v18, v20, vcc
	v_lshlrev_b32_e32 v31, 2, v18
	v_lshlrev_b32_e32 v18, 3, v177
	v_lshl_add_u64 v[20:21], s[4:5], 0, v[18:19]
	v_readlane_b32 s4, v253, 52
	v_readlane_b32 s5, v253, 53
	s_mov_b32 s17, 0xf800000
	v_mov_b32_e32 v33, 0x260
	v_lshl_add_u64 v[22:23], s[4:5], 0, v[18:19]
	s_and_b32 s4, s66, 31
	s_lshl_b32 s4, s4, 4
	s_add_i32 s3, s3, s4
	s_sub_i32 s2, s3, s2
	s_add_i32 s15, s2, 0xf00
	s_movk_i32 s18, 0x7fff
	s_and_b64 s[4:5], s[8:9], exec
	s_cselect_b32 s2, s15, s13
	s_ashr_i32 s3, s2, 31
	s_lshl_b64 s[4:5], s[2:3], 11
	v_lshl_add_u64 v[98:99], v[20:21], 0, s[4:5]
	v_lshl_add_u64 v[100:101], v[22:23], 0, s[4:5]
	s_lshl_b64 s[2:3], s[2:3], 2
	s_add_u32 s2, s75, s2
	s_addc_u32 s3, s69, s3
	global_load_dwordx2 v[80:81], v[98:99], off
	global_load_dwordx2 v[82:83], v[98:99], off offset:512
	global_load_dwordx2 v[84:85], v[98:99], off offset:1024
	global_load_dwordx2 v[86:87], v[98:99], off offset:1536
	global_load_dwordx2 v[88:89], v[100:101], off
	global_load_dwordx2 v[90:91], v[100:101], off offset:512
	global_load_dwordx2 v[92:93], v[100:101], off offset:1024
	global_load_dwordx2 v[94:95], v[100:101], off offset:1536
	global_load_dword v96, v19, s[2:3]
	s_waitcnt vmcnt(0)
	s_mov_b32 s3, s14
	s_add_i32 s2, s13, s3
	s_cmp_lt_i32 s2, s12
	s_cbranch_scc0 .Lrp1_pre1
	s_sub_i32 s3, s15, s3
	s_and_b64 s[4:5], s[8:9], exec
	s_cselect_b32 s2, s3, s2
	s_ashr_i32 s3, s2, 31
	s_lshl_b64 s[4:5], s[2:3], 11
	v_lshl_add_u64 v[98:99], v[20:21], 0, s[4:5]
	v_lshl_add_u64 v[100:101], v[22:23], 0, s[4:5]
	s_lshl_b64 s[2:3], s[2:3], 2
	s_add_u32 s2, s75, s2
	s_addc_u32 s3, s69, s3
	global_load_dwordx2 v[102:103], v[98:99], off
	global_load_dwordx2 v[104:105], v[98:99], off offset:512
	global_load_dwordx2 v[106:107], v[98:99], off offset:1024
	global_load_dwordx2 v[108:109], v[98:99], off offset:1536
	global_load_dwordx2 v[110:111], v[100:101], off
	global_load_dwordx2 v[112:113], v[100:101], off offset:512
	global_load_dwordx2 v[114:115], v[100:101], off offset:1024
	global_load_dwordx2 v[116:117], v[100:101], off offset:1536
	global_load_dword v118, v19, s[2:3]
.Lrp1_pre1:
	s_mov_b32 s100, 0
	s_branch .Lrp1_bodyB

.LBB0_524:
	s_add_i32 s2, s13, s14
	s_cmp_lt_i32 s2, s12
	s_cbranch_scc0 .Lrp1_w5
	s_waitcnt vmcnt(14)
	s_branch .Lrp1_sel

.Lrp1_sel:
	s_cmp_eq_u32 s100, 0
	s_cbranch_scc1 .Lrp1_bodyB
.Lrp1_bodyC:
	v_mov_b32_e32 v34, v102
	v_mov_b32_e32 v35, v103
	v_mov_b32_e32 v36, v104
	v_mov_b32_e32 v37, v105
	v_mov_b32_e32 v38, v106
	v_mov_b32_e32 v39, v107
	v_mov_b32_e32 v40, v108
	v_mov_b32_e32 v41, v109
	v_mov_b32_e32 v42, v110
	v_mov_b32_e32 v43, v111
	v_mov_b32_e32 v44, v112
	v_mov_b32_e32 v45, v113
	v_mov_b32_e32 v46, v114
	v_mov_b32_e32 v47, v115
	v_mov_b32_e32 v48, v116
	v_mov_b32_e32 v49, v117
	v_mov_b32_e32 v18, v118
	s_mov_b32 s100, 0
	s_mul_i32 s3, s14, 2
	s_add_i32 s2, s13, s3
	s_cmp_lt_i32 s2, s12
	s_cbranch_scc0 .Lrp1_compute
	s_sub_i32 s3, s15, s3
	s_and_b64 s[4:5], s[8:9], exec
	s_cselect_b32 s2, s3, s2
	s_ashr_i32 s3, s2, 31
	s_lshl_b64 s[4:5], s[2:3], 11
	v_lshl_add_u64 v[98:99], v[20:21], 0, s[4:5]
	v_lshl_add_u64 v[100:101], v[22:23], 0, s[4:5]
	s_lshl_b64 s[2:3], s[2:3], 2
	s_add_u32 s2, s75, s2
	s_addc_u32 s3, s69, s3
	global_load_dwordx2 v[102:103], v[98:99], off
	global_load_dwordx2 v[104:105], v[98:99], off offset:512
	global_load_dwordx2 v[106:107], v[98:99], off offset:1024
	global_load_dwordx2 v[108:109], v[98:99], off offset:1536
	global_load_dwordx2 v[110:111], v[100:101], off
	global_load_dwordx2 v[112:113], v[100:101], off offset:512
	global_load_dwordx2 v[114:115], v[100:101], off offset:1024
	global_load_dwordx2 v[116:117], v[100:101], off offset:1536
	global_load_dword v118, v19, s[2:3]
	s_branch .Lrp1_compute
.Lrp1_bodyB:
	v_mov_b32_e32 v34, v80
	v_mov_b32_e32 v35, v81
	v_mov_b32_e32 v36, v82
	v_mov_b32_e32 v37, v83
	v_mov_b32_e32 v38, v84
	v_mov_b32_e32 v39, v85
	v_mov_b32_e32 v40, v86
	v_mov_b32_e32 v41, v87
	v_mov_b32_e32 v42, v88
	v_mov_b32_e32 v43, v89
	v_mov_b32_e32 v44, v90
	v_mov_b32_e32 v45, v91
	v_mov_b32_e32 v46, v92
	v_mov_b32_e32 v47, v93
	v_mov_b32_e32 v48, v94
	v_mov_b32_e32 v49, v95
	v_mov_b32_e32 v18, v96
	s_mov_b32 s100, 1
	s_mul_i32 s3, s14, 2
	s_add_i32 s2, s13, s3
	s_cmp_lt_i32 s2, s12
	s_cbranch_scc0 .Lrp1_compute
	s_sub_i32 s3, s15, s3
	s_and_b64 s[4:5], s[8:9], exec
	s_cselect_b32 s2, s3, s2
	s_ashr_i32 s3, s2, 31
	s_lshl_b64 s[4:5], s[2:3], 11
	v_lshl_add_u64 v[98:99], v[20:21], 0, s[4:5]
	v_lshl_add_u64 v[100:101], v[22:23], 0, s[4:5]
	s_lshl_b64 s[2:3], s[2:3], 2
	s_add_u32 s2, s75, s2
	s_addc_u32 s3, s69, s3
	global_load_dwordx2 v[80:81], v[98:99], off
	global_load_dwordx2 v[82:83], v[98:99], off offset:512
	global_load_dwordx2 v[84:85], v[98:99], off offset:1024
	global_load_dwordx2 v[86:87], v[98:99], off offset:1536
	global_load_dwordx2 v[88:89], v[100:101], off
	global_load_dwordx2 v[90:91], v[100:101], off offset:512
	global_load_dwordx2 v[92:93], v[100:101], off offset:1024
	global_load_dwordx2 v[94:95], v[100:101], off offset:1536
	global_load_dword v96, v19, s[2:3]
.Lrp1_compute:
	s_and_b64 s[2:3], s[8:9], exec
	s_cselect_b32 s2, s15, s13
	s_ashr_i32 s3, s2, 31
	s_lshl_b64 s[4:5], s[2:3], 11
	s_lshl_b64 s[2:3], s[2:3], 2
	s_add_u32 s10, s75, s2
	v_lshl_add_u64 v[24:25], v[22:23], 0, s[4:5]
	s_addc_u32 s11, s69, s3
	v_lshlrev_b32_e32 v50, 16, v34
	v_and_b32_e32 v51, 0xffff0000, v34
	v_alignbit_b32 v34, v35, v34, 16
	v_and_b32_e32 v35, 0xffff0000, v35
	v_lshlrev_b32_e32 v52, 16, v36
	v_and_b32_e32 v53, 0xffff0000, v36
	v_alignbit_b32 v36, v37, v36, 16
	v_and_b32_e32 v37, 0xffff0000, v37
	v_lshlrev_b32_e32 v54, 16, v38
	v_and_b32_e32 v55, 0xffff0000, v38
	v_alignbit_b32 v38, v39, v38, 16
	v_and_b32_e32 v39, 0xffff0000, v39
	v_and_b32_e32 v34, 0xffff0000, v34
	v_and_b32_e32 v36, 0xffff0000, v36
	v_mul_f32_e32 v58, v51, v51
	v_mul_f32_e32 v59, v35, v35
	v_mul_f32_e32 v60, v53, v53
	v_mul_f32_e32 v61, v37, v37
	v_lshlrev_b32_e32 v56, 16, v40
	v_and_b32_e32 v57, 0xffff0000, v40
	v_alignbit_b32 v40, v41, v40, 16
	v_and_b32_e32 v41, 0xffff0000, v41
	v_and_b32_e32 v38, 0xffff0000, v38
	v_mul_f32_e32 v62, v55, v55
	v_mul_f32_e32 v63, v39, v39
	v_fmac_f32_e32 v58, v50, v50
	v_fmac_f32_e32 v59, v34, v34
	v_fmac_f32_e32 v60, v52, v52
	v_fmac_f32_e32 v61, v36, v36
	v_and_b32_e32 v40, 0xffff0000, v40
	v_mul_f32_e32 v64, v57, v57
	v_mul_f32_e32 v65, v41, v41
	v_fmac_f32_e32 v62, v54, v54
	v_fmac_f32_e32 v63, v38, v38
	v_add_f32_e32 v58, v58, v59
	v_add_f32_e32 v59, v60, v61
	v_fmac_f32_e32 v64, v56, v56
	v_fmac_f32_e32 v65, v40, v40
	v_add_f32_e32 v60, v62, v63
	v_add_f32_e32 v58, v58, v59
	v_add_f32_e32 v61, v64, v65
	v_add_f32_e32 v58, v58, v60
	v_add_f32_e32 v60, v58, v61
	ds_bpermute_b32 v61, v26, v60
	v_lshlrev_b32_e32 v58, 16, v42
	v_and_b32_e32 v59, 0xffff0000, v42
	v_alignbit_b32 v42, v43, v42, 16
	v_pk_mul_f32 v[50:51], v[2:3], v[50:51]
	s_waitcnt lgkmcnt(0)
	v_add_f32_e32 v62, v60, v61
	ds_bpermute_b32 v63, v27, v62
	v_lshlrev_b32_e32 v60, 16, v44
	v_and_b32_e32 v61, 0xffff0000, v44
	v_alignbit_b32 v44, v45, v44, 16
	v_pk_mul_f32 v[52:53], v[6:7], v[52:53]
	s_waitcnt lgkmcnt(0)
	v_add_f32_e32 v64, v62, v63
	ds_bpermute_b32 v65, v28, v64
	v_pk_mul_f32 v[34:35], v[4:5], v[34:35]
	v_pk_mul_f32 v[36:37], v[8:9], v[36:37]
	v_and_b32_e32 v43, 0xffff0000, v43
	v_and_b32_e32 v45, 0xffff0000, v45
	s_waitcnt lgkmcnt(0)
	v_add_f32_e32 v66, v64, v65
	ds_bpermute_b32 v67, v29, v66
	v_and_b32_e32 v42, 0xffff0000, v42
	v_and_b32_e32 v44, 0xffff0000, v44
	v_lshlrev_b32_e32 v62, 16, v46
	v_and_b32_e32 v63, 0xffff0000, v46
	s_waitcnt lgkmcnt(0)
	v_add_f32_e32 v66, v66, v67
	ds_bpermute_b32 v67, v30, v66
	v_alignbit_b32 v46, v47, v46, 16
	v_pk_mul_f32 v[54:55], v[10:11], v[54:55]
	v_pk_mul_f32 v[38:39], v[12:13], v[38:39]
	v_and_b32_e32 v47, 0xffff0000, v47
	s_waitcnt lgkmcnt(0)
	v_add_f32_e32 v66, v66, v67
	ds_bpermute_b32 v67, v31, v66
	v_lshlrev_b32_e32 v64, 16, v48
	v_and_b32_e32 v65, 0xffff0000, v48
	v_alignbit_b32 v48, v49, v48, 16
	v_and_b32_e32 v46, 0xffff0000, v46
	s_waitcnt lgkmcnt(0)
	v_add_f32_e32 v66, v66, v67
	v_fmamk_f32 v66, v66, 0x3a800000, v32
	v_mul_f32_e32 v67, 0x4f800000, v66
	v_cmp_gt_f32_e32 vcc, s17, v66
	v_pk_mul_f32 v[56:57], v[14:15], v[56:57]
	v_pk_mul_f32 v[40:41], v[16:17], v[40:41]
	v_cndmask_b32_e32 v66, v66, v67, vcc
	v_sqrt_f32_e32 v67, v66
	v_and_b32_e32 v49, 0xffff0000, v49
	v_and_b32_e32 v48, 0xffff0000, v48
	v_add_u32_e32 v68, -1, v67
	v_add_u32_e32 v69, 1, v67
	v_fma_f32 v70, -v68, v67, v66
	v_fma_f32 v71, -v69, v67, v66
	v_cmp_ge_f32_e64 s[4:5], 0, v70
	s_nop 1
	v_cndmask_b32_e64 v67, v67, v68, s[4:5]
	v_cmp_lt_f32_e64 s[4:5], 0, v71
	s_nop 1
	v_cndmask_b32_e64 v67, v67, v69, s[4:5]
	v_mul_f32_e32 v68, 0x37800000, v67
	v_cndmask_b32_e32 v67, v67, v68, vcc
	v_cmp_class_f32_e32 vcc, v66, v33
	s_nop 1
	v_cndmask_b32_e32 v66, v67, v66, vcc
	v_div_scale_f32 v67, s[2:3], v66, v66, 0.5
	v_rcp_f32_e32 v68, v67
	v_div_scale_f32 v69, vcc, 0.5, v66, 0.5
	v_fma_f32 v70, -v67, v68, 1.0
	v_fmac_f32_e32 v68, v70, v68
	v_mul_f32_e32 v70, v69, v68
	v_fma_f32 v71, -v67, v70, v69
	v_fmac_f32_e32 v70, v71, v68
	v_fma_f32 v67, -v67, v70, v69
	v_div_fmas_f32 v67, v67, v68, v70
	v_div_fixup_f32 v66, v67, v66, 0.5
	v_pk_mul_f32 v[50:51], v[50:51], v[66:67] op_sel_hi:[1,0]
	v_pk_mul_f32 v[34:35], v[34:35], v[66:67] op_sel_hi:[1,0]
	v_pk_mul_f32 v[52:53], v[52:53], v[66:67] op_sel_hi:[1,0]
	v_pk_mul_f32 v[36:37], v[36:37], v[66:67] op_sel_hi:[1,0]
	v_pk_fma_f32 v[34:35], v[18:19], v[42:43], v[34:35] op_sel_hi:[0,1,1]
	v_pk_fma_f32 v[42:43], v[18:19], v[58:59], v[50:51] op_sel_hi:[0,1,1]
	v_pk_fma_f32 v[36:37], v[18:19], v[44:45], v[36:37] op_sel_hi:[0,1,1]
	v_pk_fma_f32 v[44:45], v[18:19], v[60:61], v[52:53] op_sel_hi:[0,1,1]
	v_pk_mul_f32 v[54:55], v[54:55], v[66:67] op_sel_hi:[1,0]
	v_pk_mul_f32 v[38:39], v[38:39], v[66:67] op_sel_hi:[1,0]
	v_mul_f32_e32 v50, v43, v43
	v_mul_f32_e32 v51, v35, v35
	v_mul_f32_e32 v52, v45, v45
	v_mul_f32_e32 v53, v37, v37
	v_pk_mul_f32 v[56:57], v[56:57], v[66:67] op_sel_hi:[1,0]
	v_pk_fma_f32 v[38:39], v[18:19], v[46:47], v[38:39] op_sel_hi:[0,1,1]
	v_pk_fma_f32 v[46:47], v[18:19], v[62:63], v[54:55] op_sel_hi:[0,1,1]
	v_fmac_f32_e32 v50, v42, v42
	v_fmac_f32_e32 v51, v34, v34
	v_fmac_f32_e32 v52, v44, v44
	v_fmac_f32_e32 v53, v36, v36
	v_pk_mul_f32 v[40:41], v[40:41], v[66:67] op_sel_hi:[1,0]
	v_mul_f32_e32 v54, v47, v47
	v_mul_f32_e32 v55, v39, v39
	v_add_f32_e32 v50, v50, v51
	v_add_f32_e32 v51, v52, v53
	v_pk_fma_f32 v[40:41], v[18:19], v[48:49], v[40:41] op_sel_hi:[0,1,1]
	v_pk_fma_f32 v[48:49], v[18:19], v[64:65], v[56:57] op_sel_hi:[0,1,1]
	v_fmac_f32_e32 v54, v46, v46
	v_fmac_f32_e32 v55, v38, v38
	v_add_f32_e32 v50, v50, v51
	v_mul_f32_e32 v18, v49, v49
	v_mul_f32_e32 v51, v41, v41
	v_add_f32_e32 v52, v54, v55
	v_fmac_f32_e32 v18, v48, v48
	v_fmac_f32_e32 v51, v40, v40
	v_add_f32_e32 v50, v52, v50
	v_add_f32_e32 v18, v18, v51
	v_add_f32_e32 v18, v18, v50
	ds_bpermute_b32 v50, v26, v18
	s_waitcnt lgkmcnt(0)
	v_add_f32_e32 v18, v18, v50
	ds_bpermute_b32 v50, v27, v18
	s_waitcnt lgkmcnt(0)
	v_add_f32_e32 v18, v18, v50
	ds_bpermute_b32 v50, v28, v18
	s_waitcnt lgkmcnt(0)
	v_add_f32_e32 v18, v18, v50
	ds_bpermute_b32 v50, v29, v18
	s_waitcnt lgkmcnt(0)
	v_add_f32_e32 v18, v18, v50
	ds_bpermute_b32 v50, v30, v18
	s_waitcnt lgkmcnt(0)
	v_add_f32_e32 v18, v18, v50
	ds_bpermute_b32 v50, v31, v18
	s_waitcnt lgkmcnt(0)
	v_add_f32_e32 v18, v18, v50
	v_fmamk_f32 v18, v18, 0x3a800000, v32
	v_mul_f32_e32 v50, 0x4f800000, v18
	v_cmp_gt_f32_e32 vcc, s17, v18
	s_nop 1
	v_cndmask_b32_e32 v18, v18, v50, vcc
	v_sqrt_f32_e32 v50, v18
	s_nop 0
	v_add_u32_e32 v51, -1, v50
	v_add_u32_e32 v52, 1, v50
	v_fma_f32 v53, -v51, v50, v18
	v_fma_f32 v54, -v52, v50, v18
	v_cmp_ge_f32_e64 s[4:5], 0, v53
	s_nop 1
	v_cndmask_b32_e64 v50, v50, v51, s[4:5]
	v_cmp_lt_f32_e64 s[4:5], 0, v54
	s_nop 1
	v_cndmask_b32_e64 v50, v50, v52, s[4:5]
	v_mul_f32_e32 v51, 0x37800000, v50
	v_cndmask_b32_e32 v50, v50, v51, vcc
	v_cmp_class_f32_e32 vcc, v18, v33
	s_nop 1
	v_cndmask_b32_e32 v18, v50, v18, vcc
	v_div_scale_f32 v50, s[2:3], v18, v18, 1.0
	v_rcp_f32_e32 v51, v50
	v_div_scale_f32 v52, vcc, 1.0, v18, 1.0
	v_fma_f32 v53, -v50, v51, 1.0
	v_fmac_f32_e32 v51, v53, v51
	v_mul_f32_e32 v53, v52, v51
	v_fma_f32 v54, -v50, v53, v52
	v_fmac_f32_e32 v53, v54, v51
	v_fma_f32 v50, -v50, v53, v52
	v_div_fmas_f32 v50, v50, v51, v53
	v_div_fixup_f32 v50, v50, v18, 1.0
	v_mul_f32_e32 v42, v42, v50
	v_mul_f32_e32 v34, v34, v50
	v_mul_f32_e32 v43, v43, v50
	v_mul_f32_e32 v35, v35, v50
	v_bfe_u32 v51, v42, 16, 1
	v_bfe_u32 v53, v34, 16, 1
	v_bfe_u32 v52, v43, 16, 1
	v_bfe_u32 v54, v35, 16, 1
	v_add3_u32 v42, v42, v51, s18
	v_add3_u32 v34, v34, v53, s18
	v_add3_u32 v43, v43, v52, s18
	v_add3_u32 v35, v35, v54, s18
	v_lshrrev_b32_e32 v42, 16, v42
	v_lshrrev_b32_e32 v51, 16, v34
	v_mul_f32_e32 v44, v44, v50
	v_and_or_b32 v34, v43, s16, v42
	v_and_or_b32 v35, v35, s16, v51
	global_store_dwordx2 v[24:25], v[34:35], off
	v_mul_f32_e32 v34, v45, v50
	v_bfe_u32 v35, v44, 16, 1
	v_add3_u32 v35, v44, v35, s18
	v_bfe_u32 v42, v34, 16, 1
	v_lshrrev_b32_e32 v35, 16, v35
	v_add3_u32 v34, v34, v42, s18
	v_and_or_b32 v34, v34, s16, v35
	v_mul_f32_e32 v35, v36, v50
	v_mul_f32_e32 v36, v37, v50
	v_bfe_u32 v37, v35, 16, 1
	v_add3_u32 v35, v35, v37, s18
	v_bfe_u32 v37, v36, 16, 1
	v_lshrrev_b32_e32 v35, 16, v35
	v_add3_u32 v36, v36, v37, s18
	v_and_or_b32 v35, v36, s16, v35
	global_store_dwordx2 v[24:25], v[34:35], off offset:512
	v_mul_f32_e32 v34, v46, v50
	v_mul_f32_e32 v35, v47, v50
	v_bfe_u32 v36, v34, 16, 1
	v_add3_u32 v34, v34, v36, s18
	v_bfe_u32 v36, v35, 16, 1
	v_lshrrev_b32_e32 v34, 16, v34
	v_add3_u32 v35, v35, v36, s18
	v_and_or_b32 v34, v35, s16, v34
	v_mul_f32_e32 v35, v38, v50
	v_mul_f32_e32 v36, v39, v50
	v_bfe_u32 v37, v35, 16, 1
	v_add3_u32 v35, v35, v37, s18
	v_bfe_u32 v37, v36, 16, 1
	v_lshrrev_b32_e32 v35, 16, v35
	v_add3_u32 v36, v36, v37, s18
	v_and_or_b32 v35, v36, s16, v35
	global_store_dwordx2 v[24:25], v[34:35], off offset:1024
	v_mul_f32_e32 v34, v48, v50
	v_mul_f32_e32 v35, v49, v50
	v_bfe_u32 v36, v34, 16, 1
	v_add3_u32 v34, v34, v36, s18
	v_bfe_u32 v36, v35, 16, 1
	v_lshrrev_b32_e32 v34, 16, v34
	v_add3_u32 v35, v35, v36, s18
	v_and_or_b32 v34, v35, s16, v34
	v_mul_f32_e32 v35, v40, v50
	v_mul_f32_e32 v36, v41, v50
	v_bfe_u32 v37, v35, 16, 1
	v_add3_u32 v35, v35, v37, s18
	v_bfe_u32 v37, v36, 16, 1
	v_lshrrev_b32_e32 v35, 16, v35
	v_add3_u32 v36, v36, v37, s18
	v_and_or_b32 v35, v36, s16, v35
	global_store_dwordx2 v[24:25], v[34:35], off offset:1536
	s_and_saveexec_b64 s[2:3], s[0:1]
	s_cbranch_execz .LBB0_523
	global_store_dword v19, v18, s[10:11]
	s_branch .LBB0_523

.LBB0_761:
	s_waitcnt lgkmcnt(3)
	v_mul_f32_e32 v66, v18, v18
	s_nop 8
	v_mul_f32_e32 v67, v50, v50
	v_fmac_f32_e32 v66, v2, v2
	v_fmac_f32_e32 v67, v34, v34
	v_add_f32_e32 v67, v66, v67
	v_mul_f32_e32 v66, v19, v19
	s_waitcnt lgkmcnt(2)
	v_mul_f32_e32 v68, v51, v51
	v_fmac_f32_e32 v66, v3, v3
	v_fmac_f32_e32 v68, v35, v35
	v_add_f32_e32 v68, v66, v68
	v_mul_f32_e32 v66, v20, v20
	v_mul_f32_e32 v69, v52, v52
	v_fmac_f32_e32 v66, v4, v4
	v_fmac_f32_e32 v69, v36, v36
	v_add_f32_e32 v69, v66, v69
	v_mul_f32_e32 v66, v21, v21
	s_waitcnt lgkmcnt(1)
	v_mul_f32_e32 v70, v53, v53
	v_fmac_f32_e32 v66, v5, v5
	v_fmac_f32_e32 v70, v37, v37
	v_add_f32_e32 v70, v66, v70
	v_mul_f32_e32 v66, v22, v22
	v_mul_f32_e32 v71, v54, v54
	v_fmac_f32_e32 v66, v6, v6
	v_fmac_f32_e32 v71, v38, v38
	v_add_f32_e32 v71, v66, v71
	v_mul_f32_e32 v66, v23, v23
	s_waitcnt lgkmcnt(0)
	v_mul_f32_e32 v72, v55, v55
	v_fmac_f32_e32 v66, v7, v7
	v_fmac_f32_e32 v72, v39, v39
	v_add_f32_e32 v72, v66, v72
	v_mul_f32_e32 v66, v24, v24
	v_mul_f32_e32 v73, v56, v56
	v_fmac_f32_e32 v66, v8, v8
	v_fmac_f32_e32 v73, v40, v40
	v_add_f32_e32 v73, v66, v73
	v_mul_f32_e32 v66, v25, v25
	v_mul_f32_e32 v74, v57, v57
	v_fmac_f32_e32 v66, v9, v9
	v_fmac_f32_e32 v74, v41, v41
	v_add_f32_e32 v74, v66, v74
	v_mul_f32_e32 v66, v26, v26
	v_mul_f32_e32 v75, v58, v58
	v_fmac_f32_e32 v66, v10, v10
	v_fmac_f32_e32 v75, v42, v42
	v_add_f32_e32 v75, v66, v75
	v_mul_f32_e32 v66, v27, v27
	v_mul_f32_e32 v76, v59, v59
	v_fmac_f32_e32 v66, v11, v11
	v_fmac_f32_e32 v76, v43, v43
	v_add_f32_e32 v76, v66, v76
	v_mul_f32_e32 v66, v28, v28
	v_mul_f32_e32 v77, v60, v60
	v_fmac_f32_e32 v66, v12, v12
	v_fmac_f32_e32 v77, v44, v44
	v_add_f32_e32 v77, v66, v77
	v_mul_f32_e32 v66, v29, v29
	v_mul_f32_e32 v78, v61, v61
	v_fmac_f32_e32 v66, v13, v13
	v_fmac_f32_e32 v78, v45, v45
	v_add_f32_e32 v78, v66, v78
	v_mul_f32_e32 v66, v30, v30
	v_mul_f32_e32 v79, v62, v62
	v_fmac_f32_e32 v66, v14, v14
	v_fmac_f32_e32 v79, v46, v46
	v_add_f32_e32 v79, v66, v79
	v_mul_f32_e32 v66, v31, v31
	v_mul_f32_e32 v80, v63, v63
	v_fmac_f32_e32 v66, v15, v15
	v_fmac_f32_e32 v80, v47, v47
	v_add_f32_e32 v80, v66, v80
	v_mul_f32_e32 v66, v32, v32
	v_mul_f32_e32 v81, v64, v64
	v_fmac_f32_e32 v66, v16, v16
	v_fmac_f32_e32 v81, v48, v48
	v_add_f32_e32 v81, v66, v81
	v_mul_f32_e32 v66, v33, v33
	v_mul_f32_e32 v82, v65, v65
	v_fmac_f32_e32 v66, v17, v17
	v_fmac_f32_e32 v82, v49, v49
	v_add_f32_e32 v82, v66, v82
	v_and_b32_e32 v66, 64, v113
	v_add_u32_e32 v66, 64, v66
	v_xor_b32_e32 v83, 1, v113
	v_cmp_lt_i32_e32 vcc, v83, v66
	v_mov_b32_e32 v135, v103
	v_readlane_b32 s40, v253, 59
	v_cndmask_b32_e32 v83, v113, v83, vcc
	v_lshlrev_b32_e32 v83, 2, v83
	v_readlane_b32 s42, v253, 61
	v_readlane_b32 s43, v253, 62
	s_add_i32 s58, s58, s59
	s_add_i32 s72, s72, s73
	s_add_i32 s74, s74, s75
	v_readlane_b32 s41, v253, 60
	ds_bpermute_b32 v180, v83, v67
	ds_bpermute_b32 v181, v83, v68
	ds_bpermute_b32 v182, v83, v69
	ds_bpermute_b32 v183, v83, v70
	ds_bpermute_b32 v184, v83, v71
	ds_bpermute_b32 v185, v83, v72
	ds_bpermute_b32 v186, v83, v73
	ds_bpermute_b32 v187, v83, v74
	s_waitcnt lgkmcnt(0)
	v_add_f32_e32 v67, v67, v180
	v_add_f32_e32 v68, v68, v181
	v_add_f32_e32 v69, v69, v182
	v_add_f32_e32 v70, v70, v183
	v_add_f32_e32 v71, v71, v184
	v_add_f32_e32 v72, v72, v185
	v_add_f32_e32 v73, v73, v186
	v_add_f32_e32 v74, v74, v187
	ds_bpermute_b32 v180, v83, v75
	ds_bpermute_b32 v181, v83, v76
	ds_bpermute_b32 v182, v83, v77
	ds_bpermute_b32 v183, v83, v78
	ds_bpermute_b32 v184, v83, v79
	ds_bpermute_b32 v185, v83, v80
	ds_bpermute_b32 v186, v83, v81
	ds_bpermute_b32 v187, v83, v82
	s_waitcnt lgkmcnt(0)
	v_add_f32_e32 v75, v75, v180
	v_add_f32_e32 v76, v76, v181
	v_add_f32_e32 v77, v77, v182
	v_add_f32_e32 v78, v78, v183
	v_add_f32_e32 v79, v79, v184
	v_add_f32_e32 v80, v80, v185
	v_add_f32_e32 v81, v81, v186
	v_add_f32_e32 v82, v82, v187
	v_xor_b32_e32 v83, 2, v113
	v_cmp_lt_i32_e32 vcc, v83, v66
	s_nop 1
	v_cndmask_b32_e32 v83, v113, v83, vcc
	v_lshlrev_b32_e32 v83, 2, v83
	ds_bpermute_b32 v180, v83, v67
	ds_bpermute_b32 v181, v83, v68
	ds_bpermute_b32 v182, v83, v69
	ds_bpermute_b32 v183, v83, v70
	ds_bpermute_b32 v184, v83, v71
	ds_bpermute_b32 v185, v83, v72
	ds_bpermute_b32 v186, v83, v73
	ds_bpermute_b32 v187, v83, v74
	s_waitcnt lgkmcnt(0)
	v_add_f32_e32 v67, v67, v180
	v_add_f32_e32 v68, v68, v181
	v_add_f32_e32 v69, v69, v182
	v_add_f32_e32 v70, v70, v183
	v_add_f32_e32 v71, v71, v184
	v_add_f32_e32 v72, v72, v185
	v_add_f32_e32 v73, v73, v186
	v_add_f32_e32 v74, v74, v187
	ds_bpermute_b32 v180, v83, v75
	ds_bpermute_b32 v181, v83, v76
	ds_bpermute_b32 v182, v83, v77
	ds_bpermute_b32 v183, v83, v78
	ds_bpermute_b32 v184, v83, v79
	ds_bpermute_b32 v185, v83, v80
	ds_bpermute_b32 v186, v83, v81
	ds_bpermute_b32 v187, v83, v82
	s_waitcnt lgkmcnt(0)
	v_add_f32_e32 v75, v75, v180
	v_add_f32_e32 v76, v76, v181
	v_add_f32_e32 v77, v77, v182
	v_add_f32_e32 v78, v78, v183
	v_add_f32_e32 v79, v79, v184
	v_add_f32_e32 v80, v80, v185
	v_add_f32_e32 v81, v81, v186
	v_add_f32_e32 v82, v82, v187
	v_xor_b32_e32 v83, 4, v113
	v_cmp_lt_i32_e32 vcc, v83, v66
	s_nop 1
	v_cndmask_b32_e32 v83, v113, v83, vcc
	v_lshlrev_b32_e32 v83, 2, v83
	ds_bpermute_b32 v180, v83, v67
	ds_bpermute_b32 v181, v83, v68
	ds_bpermute_b32 v182, v83, v69
	ds_bpermute_b32 v183, v83, v70
	ds_bpermute_b32 v184, v83, v71
	ds_bpermute_b32 v185, v83, v72
	ds_bpermute_b32 v186, v83, v73
	ds_bpermute_b32 v187, v83, v74
	s_waitcnt lgkmcnt(0)
	v_add_f32_e32 v67, v67, v180
	v_add_f32_e32 v68, v68, v181
	v_add_f32_e32 v69, v69, v182
	v_add_f32_e32 v70, v70, v183
	v_add_f32_e32 v71, v71, v184
	v_add_f32_e32 v72, v72, v185
	v_add_f32_e32 v73, v73, v186
	v_add_f32_e32 v74, v74, v187
	ds_bpermute_b32 v180, v83, v75
	ds_bpermute_b32 v181, v83, v76
	ds_bpermute_b32 v182, v83, v77
	ds_bpermute_b32 v183, v83, v78
	ds_bpermute_b32 v184, v83, v79
	ds_bpermute_b32 v185, v83, v80
	ds_bpermute_b32 v186, v83, v81
	ds_bpermute_b32 v187, v83, v82
	s_waitcnt lgkmcnt(0)
	v_add_f32_e32 v75, v75, v180
	v_add_f32_e32 v76, v76, v181
	v_add_f32_e32 v77, v77, v182
	v_add_f32_e32 v78, v78, v183
	v_add_f32_e32 v79, v79, v184
	v_add_f32_e32 v80, v80, v185
	v_add_f32_e32 v81, v81, v186
	v_add_f32_e32 v82, v82, v187
	v_xor_b32_e32 v83, 8, v113
	v_cmp_lt_i32_e32 vcc, v83, v66
	s_nop 1
	v_cndmask_b32_e32 v83, v113, v83, vcc
	v_lshlrev_b32_e32 v83, 2, v83
	ds_bpermute_b32 v84, v83, v67
	s_waitcnt lgkmcnt(0)
	v_add_f32_e32 v67, v67, v84
	ds_bpermute_b32 v84, v83, v68
	s_waitcnt lgkmcnt(0)
	v_add_f32_e32 v68, v68, v84
	ds_bpermute_b32 v84, v83, v69
	s_waitcnt lgkmcnt(0)
	v_add_f32_e32 v69, v69, v84
	ds_bpermute_b32 v84, v83, v70
	s_waitcnt lgkmcnt(0)
	v_add_f32_e32 v70, v70, v84
	ds_bpermute_b32 v84, v83, v71
	s_waitcnt lgkmcnt(0)
	v_add_f32_e32 v71, v71, v84
	ds_bpermute_b32 v84, v83, v72
	s_waitcnt lgkmcnt(0)
	v_add_f32_e32 v72, v72, v84
	ds_bpermute_b32 v84, v83, v73
	s_waitcnt lgkmcnt(0)
	v_add_f32_e32 v73, v73, v84
	ds_bpermute_b32 v84, v83, v74
	s_waitcnt lgkmcnt(0)
	v_add_f32_e32 v74, v74, v84
	ds_bpermute_b32 v84, v83, v75
	s_waitcnt lgkmcnt(0)
	v_add_f32_e32 v84, v75, v84
	ds_bpermute_b32 v75, v83, v76
	s_waitcnt lgkmcnt(0)
	v_add_f32_e32 v85, v76, v75
	ds_bpermute_b32 v75, v83, v77
	s_waitcnt lgkmcnt(0)
	v_add_f32_e32 v86, v77, v75
	ds_bpermute_b32 v75, v83, v78
	s_waitcnt lgkmcnt(0)
	v_add_f32_e32 v78, v78, v75
	ds_bpermute_b32 v75, v83, v79
	s_waitcnt lgkmcnt(0)
	v_add_f32_e32 v79, v79, v75
	ds_bpermute_b32 v75, v83, v80
	s_waitcnt lgkmcnt(0)
	v_add_f32_e32 v80, v80, v75
	ds_bpermute_b32 v75, v83, v81
	s_waitcnt lgkmcnt(0)
	v_add_f32_e32 v81, v81, v75
	ds_bpermute_b32 v75, v83, v82
	s_waitcnt lgkmcnt(0)
	v_add_f32_e32 v82, v82, v75
	v_xor_b32_e32 v75, 16, v113
	v_cmp_lt_i32_e32 vcc, v75, v66
	s_nop 1
	v_cndmask_b32_e32 v66, v113, v75, vcc
	v_lshlrev_b32_e32 v66, 2, v66
	ds_bpermute_b32 v75, v66, v67
	s_waitcnt lgkmcnt(0)
	v_add_f32_e32 v83, v67, v75
	ds_bpermute_b32 v67, v66, v68
	s_waitcnt lgkmcnt(0)
	v_add_f32_e32 v87, v68, v67
	ds_bpermute_b32 v67, v66, v69
	s_waitcnt lgkmcnt(0)
	v_add_f32_e32 v88, v69, v67
	ds_bpermute_b32 v67, v66, v70
	s_waitcnt lgkmcnt(0)
	v_add_f32_e32 v89, v70, v67
	ds_bpermute_b32 v67, v66, v71
	s_waitcnt lgkmcnt(0)
	v_add_f32_e32 v77, v71, v67
	ds_bpermute_b32 v67, v66, v72
	s_waitcnt lgkmcnt(0)
	v_add_f32_e32 v76, v72, v67
	ds_bpermute_b32 v67, v66, v73
	s_waitcnt lgkmcnt(0)
	v_add_f32_e32 v75, v73, v67
	ds_bpermute_b32 v67, v66, v74
	s_waitcnt lgkmcnt(0)
	v_add_f32_e32 v74, v74, v67
	ds_bpermute_b32 v67, v66, v84
	s_waitcnt lgkmcnt(0)
	v_add_f32_e32 v73, v84, v67
	ds_bpermute_b32 v67, v66, v85
	s_waitcnt lgkmcnt(0)
	v_add_f32_e32 v72, v85, v67
	ds_bpermute_b32 v67, v66, v86
	s_waitcnt lgkmcnt(0)
	v_add_f32_e32 v71, v86, v67
	ds_bpermute_b32 v67, v66, v78
	s_waitcnt lgkmcnt(0)
	v_add_f32_e32 v70, v78, v67
	ds_bpermute_b32 v67, v66, v79
	v_fmamk_f32 v78, v83, 0x3c000000, v115
	v_cmp_gt_f32_e32 vcc, s80, v78
	s_waitcnt lgkmcnt(0)
	v_add_f32_e32 v69, v79, v67
	ds_bpermute_b32 v67, v66, v80
	v_mul_f32_e32 v79, 0x4f800000, v78
	v_cndmask_b32_e32 v78, v78, v79, vcc
	v_sqrt_f32_e32 v79, v78
	s_waitcnt lgkmcnt(0)
	v_add_f32_e32 v68, v80, v67
	ds_bpermute_b32 v67, v66, v81
	v_add_u32_e32 v80, -1, v79
	ds_bpermute_b32 v66, v66, v82
	s_waitcnt lgkmcnt(1)
	v_add_f32_e32 v67, v81, v67
	v_fma_f32 v81, -v80, v79, v78
	v_cmp_ge_f32_e64 s[34:35], 0, v81
	v_add_u32_e32 v81, 1, v79
	s_waitcnt lgkmcnt(0)
	v_add_f32_e32 v66, v82, v66
	v_cndmask_b32_e64 v80, v79, v80, s[34:35]
	v_fma_f32 v79, -v81, v79, v78
	v_cmp_lt_f32_e64 s[34:35], 0, v79
	s_nop 1
	v_cndmask_b32_e64 v79, v80, v81, s[34:35]
	v_mul_f32_e32 v80, 0x37800000, v79
	v_cndmask_b32_e32 v79, v79, v80, vcc
	v_cmp_class_f32_e32 vcc, v78, v117
	s_nop 1
	v_cndmask_b32_e32 v78, v79, v78, vcc
	v_div_scale_f32 v79, s[2:3], v78, v78, 1.0
	v_rcp_f32_e32 v80, v79
	s_nop 0
	v_fma_f32 v81, -v79, v80, 1.0
	v_fmac_f32_e32 v80, v81, v80
	v_div_scale_f32 v81, vcc, 1.0, v78, 1.0
	v_mul_f32_e32 v82, v81, v80
	v_fma_f32 v83, -v79, v82, v81
	v_fmac_f32_e32 v82, v83, v80
	v_fma_f32 v79, -v79, v82, v81
	v_div_fmas_f32 v79, v79, v80, v82
	v_div_fixup_f32 v78, v79, v78, 1.0
	v_mul_f32_e32 v2, v2, v78
	v_bfe_u32 v79, v2, 16, 1
	v_add3_u32 v2, v2, v79, s81
	ds_write_b16_d16_hi v1, v2
	v_mul_f32_e32 v2, v18, v78
	v_bfe_u32 v18, v2, 16, 1
	v_add3_u32 v2, v2, v18, s81
	ds_write_b16_d16_hi v1, v2 offset:64
	v_mul_f32_e32 v2, v34, v78
	v_bfe_u32 v18, v2, 16, 1
	v_add3_u32 v2, v2, v18, s81
	ds_write_b16_d16_hi v1, v2 offset:128
	v_mul_f32_e32 v2, v50, v78
	v_bfe_u32 v18, v2, 16, 1
	v_add3_u32 v2, v2, v18, s81
	ds_write_b16_d16_hi v1, v2 offset:192
	v_fmamk_f32 v2, v87, 0x3c000000, v115
	v_cmp_gt_f32_e32 vcc, s80, v2
	v_mul_f32_e32 v18, 0x4f800000, v2
	s_nop 0
	v_cndmask_b32_e32 v2, v2, v18, vcc
	v_sqrt_f32_e32 v18, v2
	s_nop 0
	v_add_u32_e32 v34, -1, v18
	v_fma_f32 v50, -v34, v18, v2
	v_cmp_ge_f32_e64 s[34:35], 0, v50
	v_add_u32_e32 v50, 1, v18
	s_nop 0
	v_cndmask_b32_e64 v34, v18, v34, s[34:35]
	v_fma_f32 v18, -v50, v18, v2
	v_cmp_lt_f32_e64 s[34:35], 0, v18
	s_nop 1
	v_cndmask_b32_e64 v18, v34, v50, s[34:35]
	v_mul_f32_e32 v34, 0x37800000, v18
	v_cndmask_b32_e32 v18, v18, v34, vcc
	v_cmp_class_f32_e32 vcc, v2, v117
	s_nop 1
	v_cndmask_b32_e32 v2, v18, v2, vcc
	v_div_scale_f32 v18, s[2:3], v2, v2, 1.0
	v_rcp_f32_e32 v34, v18
	s_nop 0
	v_fma_f32 v50, -v18, v34, 1.0
	v_fmac_f32_e32 v34, v50, v34
	v_div_scale_f32 v50, vcc, 1.0, v2, 1.0
	v_mul_f32_e32 v78, v50, v34
	v_fma_f32 v79, -v18, v78, v50
	v_fmac_f32_e32 v78, v79, v34
	v_fma_f32 v18, -v18, v78, v50
	v_div_fmas_f32 v18, v18, v34, v78
	v_div_fixup_f32 v2, v18, v2, 1.0
	v_mul_f32_e32 v3, v3, v2
	v_bfe_u32 v18, v3, 16, 1
	v_add3_u32 v3, v3, v18, s81
	ds_write_b16_d16_hi v1, v3 offset:256
	v_mul_f32_e32 v3, v19, v2
	v_bfe_u32 v18, v3, 16, 1
	v_add3_u32 v3, v3, v18, s81
	ds_write_b16_d16_hi v1, v3 offset:320
	v_mul_f32_e32 v3, v35, v2
	v_bfe_u32 v18, v3, 16, 1
	v_add3_u32 v3, v3, v18, s81
	v_mul_f32_e32 v2, v51, v2
	ds_write_b16_d16_hi v1, v3 offset:384
	v_bfe_u32 v3, v2, 16, 1
	v_add3_u32 v2, v2, v3, s81
	ds_write_b16_d16_hi v1, v2 offset:448
	v_fmamk_f32 v2, v88, 0x3c000000, v115
	v_cmp_gt_f32_e32 vcc, s80, v2
	v_mul_f32_e32 v3, 0x4f800000, v2
	s_nop 0
	v_cndmask_b32_e32 v2, v2, v3, vcc
	v_sqrt_f32_e32 v3, v2
	s_nop 0
	v_add_u32_e32 v18, -1, v3
	v_fma_f32 v19, -v18, v3, v2
	v_cmp_ge_f32_e64 s[34:35], 0, v19
	v_add_u32_e32 v19, 1, v3
	s_nop 0
	v_cndmask_b32_e64 v18, v3, v18, s[34:35]
	v_fma_f32 v3, -v19, v3, v2
	v_cmp_lt_f32_e64 s[34:35], 0, v3
	s_nop 1
	v_cndmask_b32_e64 v3, v18, v19, s[34:35]
	v_mul_f32_e32 v18, 0x37800000, v3
	v_cndmask_b32_e32 v3, v3, v18, vcc
	v_cmp_class_f32_e32 vcc, v2, v117
	s_nop 1
	v_cndmask_b32_e32 v2, v3, v2, vcc
	v_div_scale_f32 v3, s[2:3], v2, v2, 1.0
	v_rcp_f32_e32 v18, v3
	s_nop 0
	v_fma_f32 v19, -v3, v18, 1.0
	v_fmac_f32_e32 v18, v19, v18
	v_div_scale_f32 v19, vcc, 1.0, v2, 1.0
	v_mul_f32_e32 v34, v19, v18
	v_fma_f32 v35, -v3, v34, v19
	v_fmac_f32_e32 v34, v35, v18
	v_fma_f32 v3, -v3, v34, v19
	v_div_fmas_f32 v3, v3, v18, v34
	v_div_fixup_f32 v2, v3, v2, 1.0
	v_mul_f32_e32 v3, v4, v2
	v_bfe_u32 v4, v3, 16, 1
	v_add3_u32 v3, v3, v4, s81
	ds_write_b16_d16_hi v1, v3 offset:512
	v_mul_f32_e32 v3, v20, v2
	v_bfe_u32 v4, v3, 16, 1
	v_add3_u32 v3, v3, v4, s81
	ds_write_b16_d16_hi v1, v3 offset:576
	v_mul_f32_e32 v3, v36, v2
	v_bfe_u32 v4, v3, 16, 1
	v_add3_u32 v3, v3, v4, s81
	v_mul_f32_e32 v2, v52, v2
	ds_write_b16_d16_hi v1, v3 offset:640
	v_bfe_u32 v3, v2, 16, 1
	v_add3_u32 v2, v2, v3, s81
	ds_write_b16_d16_hi v1, v2 offset:704
	v_fmamk_f32 v2, v89, 0x3c000000, v115
	v_cmp_gt_f32_e32 vcc, s80, v2
	v_mul_f32_e32 v3, 0x4f800000, v2
	s_nop 0
	v_cndmask_b32_e32 v2, v2, v3, vcc
	v_sqrt_f32_e32 v3, v2
	s_nop 0
	v_add_u32_e32 v4, -1, v3
	v_fma_f32 v18, -v4, v3, v2
	v_cmp_ge_f32_e64 s[34:35], 0, v18
	v_add_u32_e32 v18, 1, v3
	s_nop 0
	v_cndmask_b32_e64 v4, v3, v4, s[34:35]
	v_fma_f32 v3, -v18, v3, v2
	v_cmp_lt_f32_e64 s[34:35], 0, v3
	s_nop 1
	v_cndmask_b32_e64 v3, v4, v18, s[34:35]
	v_mul_f32_e32 v4, 0x37800000, v3
	v_cndmask_b32_e32 v3, v3, v4, vcc
	v_cmp_class_f32_e32 vcc, v2, v117
	s_nop 1
	v_cndmask_b32_e32 v2, v3, v2, vcc
	v_div_scale_f32 v3, s[2:3], v2, v2, 1.0
	v_rcp_f32_e32 v4, v3
	s_nop 0
	v_fma_f32 v18, -v3, v4, 1.0
	v_fmac_f32_e32 v4, v18, v4
	v_div_scale_f32 v18, vcc, 1.0, v2, 1.0
	v_mul_f32_e32 v19, v18, v4
	v_fma_f32 v20, -v3, v19, v18
	v_fmac_f32_e32 v19, v20, v4
	v_fma_f32 v3, -v3, v19, v18
	v_div_fmas_f32 v3, v3, v4, v19
	v_div_fixup_f32 v2, v3, v2, 1.0
	v_mul_f32_e32 v3, v5, v2
	v_bfe_u32 v4, v3, 16, 1
	v_add3_u32 v3, v3, v4, s81
	ds_write_b16_d16_hi v1, v3 offset:768
	v_mul_f32_e32 v3, v21, v2
	v_bfe_u32 v4, v3, 16, 1
	v_add3_u32 v3, v3, v4, s81
	ds_write_b16_d16_hi v1, v3 offset:832
	v_mul_f32_e32 v3, v37, v2
	v_bfe_u32 v4, v3, 16, 1
	v_add3_u32 v3, v3, v4, s81
	v_mul_f32_e32 v2, v53, v2
	ds_write_b16_d16_hi v1, v3 offset:896
	v_bfe_u32 v3, v2, 16, 1
	v_add3_u32 v2, v2, v3, s81
	ds_write_b16_d16_hi v1, v2 offset:960
	v_fmamk_f32 v2, v77, 0x3c000000, v115
	v_cmp_gt_f32_e32 vcc, s80, v2
	v_mul_f32_e32 v3, 0x4f800000, v2
	s_nop 0
	v_cndmask_b32_e32 v2, v2, v3, vcc
	v_sqrt_f32_e32 v3, v2
	s_nop 0
	v_add_u32_e32 v4, -1, v3
	v_fma_f32 v5, -v4, v3, v2
	v_cmp_ge_f32_e64 s[34:35], 0, v5
	v_add_u32_e32 v5, 1, v3
	s_nop 0
	v_cndmask_b32_e64 v4, v3, v4, s[34:35]
	v_fma_f32 v3, -v5, v3, v2
	v_cmp_lt_f32_e64 s[34:35], 0, v3
	s_nop 1
	v_cndmask_b32_e64 v3, v4, v5, s[34:35]
	v_mul_f32_e32 v4, 0x37800000, v3
	v_cndmask_b32_e32 v3, v3, v4, vcc
	v_cmp_class_f32_e32 vcc, v2, v117
	s_nop 1
	v_cndmask_b32_e32 v2, v3, v2, vcc
	v_div_scale_f32 v3, s[2:3], v2, v2, 1.0
	v_rcp_f32_e32 v4, v3
	s_nop 0
	v_fma_f32 v5, -v3, v4, 1.0
	v_fmac_f32_e32 v4, v5, v4
	v_div_scale_f32 v5, vcc, 1.0, v2, 1.0
	v_mul_f32_e32 v18, v5, v4
	v_fma_f32 v19, -v3, v18, v5
	v_fmac_f32_e32 v18, v19, v4
	v_fma_f32 v3, -v3, v18, v5
	v_div_fmas_f32 v3, v3, v4, v18
	v_div_fixup_f32 v2, v3, v2, 1.0
	v_mul_f32_e32 v3, v6, v2
	v_bfe_u32 v4, v3, 16, 1
	v_add3_u32 v3, v3, v4, s81
	ds_write_b16_d16_hi v1, v3 offset:2048
	v_mul_f32_e32 v3, v22, v2
	v_bfe_u32 v4, v3, 16, 1
	v_add3_u32 v3, v3, v4, s81
	ds_write_b16_d16_hi v1, v3 offset:2112
	v_mul_f32_e32 v3, v38, v2
	v_bfe_u32 v4, v3, 16, 1
	v_add3_u32 v3, v3, v4, s81
	v_mul_f32_e32 v2, v54, v2
	ds_write_b16_d16_hi v1, v3 offset:2176
	v_bfe_u32 v3, v2, 16, 1
	v_add3_u32 v2, v2, v3, s81
	ds_write_b16_d16_hi v1, v2 offset:2240
	v_fmamk_f32 v2, v76, 0x3c000000, v115
	v_cmp_gt_f32_e32 vcc, s80, v2
	v_mul_f32_e32 v3, 0x4f800000, v2
	s_nop 0
	v_cndmask_b32_e32 v2, v2, v3, vcc
	v_sqrt_f32_e32 v3, v2
	s_nop 0
	v_add_u32_e32 v4, -1, v3
	v_fma_f32 v5, -v4, v3, v2
	v_cmp_ge_f32_e64 s[34:35], 0, v5
	v_add_u32_e32 v5, 1, v3
	s_nop 0
	v_cndmask_b32_e64 v4, v3, v4, s[34:35]
	v_fma_f32 v3, -v5, v3, v2
	v_cmp_lt_f32_e64 s[34:35], 0, v3
	s_nop 1
	v_cndmask_b32_e64 v3, v4, v5, s[34:35]
	v_mul_f32_e32 v4, 0x37800000, v3
	v_cndmask_b32_e32 v3, v3, v4, vcc
	v_cmp_class_f32_e32 vcc, v2, v117
	s_nop 1
	v_cndmask_b32_e32 v2, v3, v2, vcc
	v_div_scale_f32 v3, s[2:3], v2, v2, 1.0
	v_rcp_f32_e32 v4, v3
	s_nop 0
	v_fma_f32 v5, -v3, v4, 1.0
	v_fmac_f32_e32 v4, v5, v4
	v_div_scale_f32 v5, vcc, 1.0, v2, 1.0
	v_mul_f32_e32 v6, v5, v4
	v_fma_f32 v18, -v3, v6, v5
	v_fmac_f32_e32 v6, v18, v4
	v_fma_f32 v3, -v3, v6, v5
	v_div_fmas_f32 v3, v3, v4, v6
	v_div_fixup_f32 v2, v3, v2, 1.0
	v_mul_f32_e32 v3, v7, v2
	v_bfe_u32 v4, v3, 16, 1
	v_add3_u32 v3, v3, v4, s81
	ds_write_b16_d16_hi v1, v3 offset:2304
	v_mul_f32_e32 v3, v23, v2
	v_bfe_u32 v4, v3, 16, 1
	v_add3_u32 v3, v3, v4, s81
	ds_write_b16_d16_hi v1, v3 offset:2368
	v_mul_f32_e32 v3, v39, v2
	v_bfe_u32 v4, v3, 16, 1
	v_add3_u32 v3, v3, v4, s81
	v_mul_f32_e32 v2, v55, v2
	ds_write_b16_d16_hi v1, v3 offset:2432
	v_bfe_u32 v3, v2, 16, 1
	v_add3_u32 v2, v2, v3, s81
	ds_write_b16_d16_hi v1, v2 offset:2496
	v_fmamk_f32 v2, v75, 0x3c000000, v115
	v_cmp_gt_f32_e32 vcc, s80, v2
	v_mul_f32_e32 v3, 0x4f800000, v2
	s_nop 0
	v_cndmask_b32_e32 v2, v2, v3, vcc
	v_sqrt_f32_e32 v3, v2
	s_nop 0
	v_add_u32_e32 v4, -1, v3
	v_fma_f32 v5, -v4, v3, v2
	v_cmp_ge_f32_e64 s[34:35], 0, v5
	v_add_u32_e32 v5, 1, v3
	s_nop 0
	v_cndmask_b32_e64 v4, v3, v4, s[34:35]
	v_fma_f32 v3, -v5, v3, v2
	v_cmp_lt_f32_e64 s[34:35], 0, v3
	s_nop 1
	v_cndmask_b32_e64 v3, v4, v5, s[34:35]
	v_mul_f32_e32 v4, 0x37800000, v3
	v_cndmask_b32_e32 v3, v3, v4, vcc
	v_cmp_class_f32_e32 vcc, v2, v117
	s_nop 1
	v_cndmask_b32_e32 v2, v3, v2, vcc
	v_div_scale_f32 v3, s[2:3], v2, v2, 1.0
	v_rcp_f32_e32 v4, v3
	s_nop 0
	v_fma_f32 v5, -v3, v4, 1.0
	v_fmac_f32_e32 v4, v5, v4
	v_div_scale_f32 v5, vcc, 1.0, v2, 1.0
	v_mul_f32_e32 v6, v5, v4
	v_fma_f32 v7, -v3, v6, v5
	v_fmac_f32_e32 v6, v7, v4
	v_fma_f32 v3, -v3, v6, v5
	v_div_fmas_f32 v3, v3, v4, v6
	v_div_fixup_f32 v2, v3, v2, 1.0
	v_mul_f32_e32 v3, v8, v2
	v_bfe_u32 v4, v3, 16, 1
	v_add3_u32 v3, v3, v4, s81
	ds_write_b16_d16_hi v1, v3 offset:2560
	v_mul_f32_e32 v3, v24, v2
	v_bfe_u32 v4, v3, 16, 1
	v_add3_u32 v3, v3, v4, s81
	ds_write_b16_d16_hi v1, v3 offset:2624
	v_mul_f32_e32 v3, v40, v2
	v_bfe_u32 v4, v3, 16, 1
	v_add3_u32 v3, v3, v4, s81
	v_mul_f32_e32 v2, v56, v2
	ds_write_b16_d16_hi v1, v3 offset:2688
	v_bfe_u32 v3, v2, 16, 1
	v_add3_u32 v2, v2, v3, s81
	ds_write_b16_d16_hi v1, v2 offset:2752
	v_fmamk_f32 v2, v74, 0x3c000000, v115
	v_cmp_gt_f32_e32 vcc, s80, v2
	v_mul_f32_e32 v3, 0x4f800000, v2
	s_nop 0
	v_cndmask_b32_e32 v2, v2, v3, vcc
	v_sqrt_f32_e32 v3, v2
	s_nop 0
	v_add_u32_e32 v4, -1, v3
	v_fma_f32 v5, -v4, v3, v2
	v_cmp_ge_f32_e64 s[34:35], 0, v5
	v_add_u32_e32 v5, 1, v3
	s_nop 0
	v_cndmask_b32_e64 v4, v3, v4, s[34:35]
	v_fma_f32 v3, -v5, v3, v2
	v_cmp_lt_f32_e64 s[34:35], 0, v3
	s_nop 1
	v_cndmask_b32_e64 v3, v4, v5, s[34:35]
	v_mul_f32_e32 v4, 0x37800000, v3
	v_cndmask_b32_e32 v3, v3, v4, vcc
	v_cmp_class_f32_e32 vcc, v2, v117
	s_nop 1
	v_cndmask_b32_e32 v2, v3, v2, vcc
	v_div_scale_f32 v3, s[2:3], v2, v2, 1.0
	v_rcp_f32_e32 v4, v3
	s_nop 0
	v_fma_f32 v5, -v3, v4, 1.0
	v_fmac_f32_e32 v4, v5, v4
	v_div_scale_f32 v5, vcc, 1.0, v2, 1.0
	v_mul_f32_e32 v6, v5, v4
	v_fma_f32 v7, -v3, v6, v5
	v_fmac_f32_e32 v6, v7, v4
	v_fma_f32 v3, -v3, v6, v5
	v_div_fmas_f32 v3, v3, v4, v6
	v_div_fixup_f32 v2, v3, v2, 1.0
	v_mul_f32_e32 v3, v9, v2
	v_bfe_u32 v4, v3, 16, 1
	v_add3_u32 v3, v3, v4, s81
	ds_write_b16_d16_hi v1, v3 offset:2816
	v_mul_f32_e32 v3, v25, v2
	v_bfe_u32 v4, v3, 16, 1
	v_add3_u32 v3, v3, v4, s81
	ds_write_b16_d16_hi v1, v3 offset:2880
	v_mul_f32_e32 v3, v41, v2
	v_bfe_u32 v4, v3, 16, 1
	v_add3_u32 v3, v3, v4, s81
	v_mul_f32_e32 v2, v57, v2
	ds_write_b16_d16_hi v1, v3 offset:2944
	v_bfe_u32 v3, v2, 16, 1
	v_add3_u32 v2, v2, v3, s81
	ds_write_b16_d16_hi v1, v2 offset:3008
	v_fmamk_f32 v2, v73, 0x3c000000, v115
	v_cmp_gt_f32_e32 vcc, s80, v2
	v_mul_f32_e32 v3, 0x4f800000, v2
	s_nop 0
	v_cndmask_b32_e32 v2, v2, v3, vcc
	v_sqrt_f32_e32 v3, v2
	s_nop 0
	v_add_u32_e32 v4, -1, v3
	v_fma_f32 v5, -v4, v3, v2
	v_cmp_ge_f32_e64 s[34:35], 0, v5
	v_add_u32_e32 v5, 1, v3
	s_nop 0
	v_cndmask_b32_e64 v4, v3, v4, s[34:35]
	v_fma_f32 v3, -v5, v3, v2
	v_cmp_lt_f32_e64 s[34:35], 0, v3
	s_nop 1
	v_cndmask_b32_e64 v3, v4, v5, s[34:35]
	v_mul_f32_e32 v4, 0x37800000, v3
	v_cndmask_b32_e32 v3, v3, v4, vcc
	v_cmp_class_f32_e32 vcc, v2, v117
	s_nop 1
	v_cndmask_b32_e32 v2, v3, v2, vcc
	v_div_scale_f32 v3, s[2:3], v2, v2, 1.0
	v_rcp_f32_e32 v4, v3
	s_nop 0
	v_fma_f32 v5, -v3, v4, 1.0
	v_fmac_f32_e32 v4, v5, v4
	v_div_scale_f32 v5, vcc, 1.0, v2, 1.0
	v_mul_f32_e32 v6, v5, v4
	v_fma_f32 v7, -v3, v6, v5
	v_fmac_f32_e32 v6, v7, v4
	v_fma_f32 v3, -v3, v6, v5
	v_div_fmas_f32 v3, v3, v4, v6
	v_div_fixup_f32 v2, v3, v2, 1.0
	v_mul_f32_e32 v3, v10, v2
	v_bfe_u32 v4, v3, 16, 1
	v_add3_u32 v3, v3, v4, s81
	ds_write_b16_d16_hi v1, v3 offset:4096
	v_mul_f32_e32 v3, v26, v2
	v_bfe_u32 v4, v3, 16, 1
	v_add3_u32 v3, v3, v4, s81
	ds_write_b16_d16_hi v1, v3 offset:4160
	v_mul_f32_e32 v3, v42, v2
	v_bfe_u32 v4, v3, 16, 1
	v_add3_u32 v3, v3, v4, s81
	v_mul_f32_e32 v2, v58, v2
	ds_write_b16_d16_hi v1, v3 offset:4224
	v_bfe_u32 v3, v2, 16, 1
	v_add3_u32 v2, v2, v3, s81
	ds_write_b16_d16_hi v1, v2 offset:4288
	v_fmamk_f32 v2, v72, 0x3c000000, v115
	v_cmp_gt_f32_e32 vcc, s80, v2
	v_mul_f32_e32 v3, 0x4f800000, v2
	s_nop 0
	v_cndmask_b32_e32 v2, v2, v3, vcc
	v_sqrt_f32_e32 v3, v2
	s_nop 0
	v_add_u32_e32 v4, -1, v3
	v_fma_f32 v5, -v4, v3, v2
	v_cmp_ge_f32_e64 s[34:35], 0, v5
	v_add_u32_e32 v5, 1, v3
	s_nop 0
	v_cndmask_b32_e64 v4, v3, v4, s[34:35]
	v_fma_f32 v3, -v5, v3, v2
	v_cmp_lt_f32_e64 s[34:35], 0, v3
	s_nop 1
	v_cndmask_b32_e64 v3, v4, v5, s[34:35]
	v_mul_f32_e32 v4, 0x37800000, v3
	v_cndmask_b32_e32 v3, v3, v4, vcc
	v_cmp_class_f32_e32 vcc, v2, v117
	s_nop 1
	v_cndmask_b32_e32 v2, v3, v2, vcc
	v_div_scale_f32 v3, s[2:3], v2, v2, 1.0
	v_rcp_f32_e32 v4, v3
	s_nop 0
	v_fma_f32 v5, -v3, v4, 1.0
	v_fmac_f32_e32 v4, v5, v4
	v_div_scale_f32 v5, vcc, 1.0, v2, 1.0
	v_mul_f32_e32 v6, v5, v4
	v_fma_f32 v7, -v3, v6, v5
	v_fmac_f32_e32 v6, v7, v4
	v_fma_f32 v3, -v3, v6, v5
	v_div_fmas_f32 v3, v3, v4, v6
	v_div_fixup_f32 v2, v3, v2, 1.0
	v_mul_f32_e32 v3, v11, v2
	v_bfe_u32 v4, v3, 16, 1
	v_add3_u32 v3, v3, v4, s81
	ds_write_b16_d16_hi v1, v3 offset:4352
	v_mul_f32_e32 v3, v27, v2
	v_bfe_u32 v4, v3, 16, 1
	v_add3_u32 v3, v3, v4, s81
	ds_write_b16_d16_hi v1, v3 offset:4416
	v_mul_f32_e32 v3, v43, v2
	v_bfe_u32 v4, v3, 16, 1
	v_add3_u32 v3, v3, v4, s81
	v_mul_f32_e32 v2, v59, v2
	ds_write_b16_d16_hi v1, v3 offset:4480
	v_bfe_u32 v3, v2, 16, 1
	v_add3_u32 v2, v2, v3, s81
	ds_write_b16_d16_hi v1, v2 offset:4544
	v_fmamk_f32 v2, v71, 0x3c000000, v115
	v_cmp_gt_f32_e32 vcc, s80, v2
	v_mul_f32_e32 v3, 0x4f800000, v2
	v_lshl_add_u64 v[10:11], s[68:69], 0, v[110:111]
	v_cndmask_b32_e32 v2, v2, v3, vcc
	v_sqrt_f32_e32 v3, v2
	v_readlane_b32 s68, v253, 57
	s_add_i32 s84, s84, s68
	v_add_u32_e32 v4, -1, v3
	v_fma_f32 v5, -v4, v3, v2
	v_cmp_ge_f32_e64 s[34:35], 0, v5
	v_add_u32_e32 v5, 1, v3
	s_nop 0
	v_cndmask_b32_e64 v4, v3, v4, s[34:35]
	v_fma_f32 v3, -v5, v3, v2
	v_cmp_lt_f32_e64 s[34:35], 0, v3
	s_nop 1
	v_cndmask_b32_e64 v3, v4, v5, s[34:35]
	v_mul_f32_e32 v4, 0x37800000, v3
	v_cndmask_b32_e32 v3, v3, v4, vcc
	v_cmp_class_f32_e32 vcc, v2, v117
	s_nop 1
	v_cndmask_b32_e32 v2, v3, v2, vcc
	v_div_scale_f32 v3, s[2:3], v2, v2, 1.0
	v_rcp_f32_e32 v4, v3
	s_nop 0
	v_fma_f32 v5, -v3, v4, 1.0
	v_fmac_f32_e32 v4, v5, v4
	v_div_scale_f32 v5, vcc, 1.0, v2, 1.0
	v_mul_f32_e32 v6, v5, v4
	v_fma_f32 v7, -v3, v6, v5
	v_fmac_f32_e32 v6, v7, v4
	v_fma_f32 v3, -v3, v6, v5
	v_div_fmas_f32 v3, v3, v4, v6
	v_div_fixup_f32 v2, v3, v2, 1.0
	v_mul_f32_e32 v3, v12, v2
	v_bfe_u32 v4, v3, 16, 1
	v_add3_u32 v3, v3, v4, s81
	ds_write_b16_d16_hi v1, v3 offset:4608
	v_mul_f32_e32 v3, v28, v2
	v_bfe_u32 v4, v3, 16, 1
	v_add3_u32 v3, v3, v4, s81
	ds_write_b16_d16_hi v1, v3 offset:4672
	v_mul_f32_e32 v3, v44, v2
	v_bfe_u32 v4, v3, 16, 1
	v_add3_u32 v3, v3, v4, s81
	v_mul_f32_e32 v2, v60, v2
	ds_write_b16_d16_hi v1, v3 offset:4736
	v_bfe_u32 v3, v2, 16, 1
	v_add3_u32 v2, v2, v3, s81
	ds_write_b16_d16_hi v1, v2 offset:4800
	v_fmamk_f32 v2, v70, 0x3c000000, v115
	v_cmp_gt_f32_e32 vcc, s80, v2
	v_mul_f32_e32 v3, 0x4f800000, v2
	s_nop 0
	v_cndmask_b32_e32 v2, v2, v3, vcc
	v_sqrt_f32_e32 v3, v2
	s_nop 0
	v_add_u32_e32 v4, -1, v3
	v_fma_f32 v5, -v4, v3, v2
	v_cmp_ge_f32_e64 s[34:35], 0, v5
	v_add_u32_e32 v5, 1, v3
	s_nop 0
	v_cndmask_b32_e64 v4, v3, v4, s[34:35]
	v_fma_f32 v3, -v5, v3, v2
	v_cmp_lt_f32_e64 s[34:35], 0, v3
	s_nop 1
	v_cndmask_b32_e64 v3, v4, v5, s[34:35]
	v_mul_f32_e32 v4, 0x37800000, v3
	v_cndmask_b32_e32 v3, v3, v4, vcc
	v_cmp_class_f32_e32 vcc, v2, v117
	s_nop 1
	v_cndmask_b32_e32 v2, v3, v2, vcc
	v_div_scale_f32 v3, s[2:3], v2, v2, 1.0
	v_rcp_f32_e32 v4, v3
	s_nop 0
	v_fma_f32 v5, -v3, v4, 1.0
	v_fmac_f32_e32 v4, v5, v4
	v_div_scale_f32 v5, vcc, 1.0, v2, 1.0
	v_mul_f32_e32 v6, v5, v4
	v_fma_f32 v7, -v3, v6, v5
	v_fmac_f32_e32 v6, v7, v4
	v_fma_f32 v3, -v3, v6, v5
	v_div_fmas_f32 v3, v3, v4, v6
	v_div_fixup_f32 v2, v3, v2, 1.0
	v_mul_f32_e32 v3, v13, v2
	v_bfe_u32 v4, v3, 16, 1
	v_add3_u32 v3, v3, v4, s81
	ds_write_b16_d16_hi v1, v3 offset:4864
	v_mul_f32_e32 v3, v29, v2
	v_bfe_u32 v4, v3, 16, 1
	v_add3_u32 v3, v3, v4, s81
	ds_write_b16_d16_hi v1, v3 offset:4928
	v_mul_f32_e32 v3, v45, v2
	v_bfe_u32 v4, v3, 16, 1
	v_add3_u32 v3, v3, v4, s81
	v_mul_f32_e32 v2, v61, v2
	ds_write_b16_d16_hi v1, v3 offset:4992
	v_bfe_u32 v3, v2, 16, 1
	v_add3_u32 v2, v2, v3, s81
	ds_write_b16_d16_hi v1, v2 offset:5056
	v_fmamk_f32 v2, v69, 0x3c000000, v115
	v_cmp_gt_f32_e32 vcc, s80, v2
	v_mul_f32_e32 v3, 0x4f800000, v2
	s_nop 0
	v_cndmask_b32_e32 v2, v2, v3, vcc
	v_sqrt_f32_e32 v3, v2
	s_nop 0
	v_add_u32_e32 v4, -1, v3
	v_fma_f32 v5, -v4, v3, v2
	v_cmp_ge_f32_e64 s[34:35], 0, v5
	v_add_u32_e32 v5, 1, v3
	s_nop 0
	v_cndmask_b32_e64 v4, v3, v4, s[34:35]
	v_fma_f32 v3, -v5, v3, v2
	v_cmp_lt_f32_e64 s[34:35], 0, v3
	s_nop 1
	v_cndmask_b32_e64 v3, v4, v5, s[34:35]
	v_mul_f32_e32 v4, 0x37800000, v3
	v_cndmask_b32_e32 v3, v3, v4, vcc
	v_cmp_class_f32_e32 vcc, v2, v117
	s_nop 1
	v_cndmask_b32_e32 v2, v3, v2, vcc
	v_div_scale_f32 v3, s[2:3], v2, v2, 1.0
	v_rcp_f32_e32 v4, v3
	s_nop 0
	v_fma_f32 v5, -v3, v4, 1.0
	v_fmac_f32_e32 v4, v5, v4
	v_div_scale_f32 v5, vcc, 1.0, v2, 1.0
	v_mul_f32_e32 v6, v5, v4
	v_fma_f32 v7, -v3, v6, v5
	v_fmac_f32_e32 v6, v7, v4
	v_fma_f32 v3, -v3, v6, v5
	v_div_fmas_f32 v3, v3, v4, v6
	v_div_fixup_f32 v2, v3, v2, 1.0
	v_mul_f32_e32 v3, v14, v2
	v_bfe_u32 v4, v3, 16, 1
	v_add3_u32 v3, v3, v4, s81
	ds_write_b16_d16_hi v1, v3 offset:6144
	v_mul_f32_e32 v3, v30, v2
	v_bfe_u32 v4, v3, 16, 1
	v_add3_u32 v3, v3, v4, s81
	ds_write_b16_d16_hi v1, v3 offset:6208
	v_mul_f32_e32 v3, v46, v2
	v_bfe_u32 v4, v3, 16, 1
	v_add3_u32 v3, v3, v4, s81
	v_mul_f32_e32 v2, v62, v2
	ds_write_b16_d16_hi v1, v3 offset:6272
	v_bfe_u32 v3, v2, 16, 1
	v_add3_u32 v2, v2, v3, s81
	ds_write_b16_d16_hi v1, v2 offset:6336
	v_fmamk_f32 v2, v68, 0x3c000000, v115
	v_cmp_gt_f32_e32 vcc, s80, v2
	v_mul_f32_e32 v3, 0x4f800000, v2
	s_nop 0
	v_cndmask_b32_e32 v2, v2, v3, vcc
	v_sqrt_f32_e32 v3, v2
	s_nop 0
	v_add_u32_e32 v4, -1, v3
	v_fma_f32 v5, -v4, v3, v2
	v_cmp_ge_f32_e64 s[34:35], 0, v5
	v_add_u32_e32 v5, 1, v3
	s_nop 0
	v_cndmask_b32_e64 v4, v3, v4, s[34:35]
	v_fma_f32 v3, -v5, v3, v2
	v_cmp_lt_f32_e64 s[34:35], 0, v3
	s_nop 1
	v_cndmask_b32_e64 v3, v4, v5, s[34:35]
	v_mul_f32_e32 v4, 0x37800000, v3
	v_cndmask_b32_e32 v3, v3, v4, vcc
	v_cmp_class_f32_e32 vcc, v2, v117
	s_nop 1
	v_cndmask_b32_e32 v2, v3, v2, vcc
	v_div_scale_f32 v3, s[2:3], v2, v2, 1.0
	v_rcp_f32_e32 v4, v3
	s_nop 0
	v_fma_f32 v5, -v3, v4, 1.0
	v_fmac_f32_e32 v4, v5, v4
	v_div_scale_f32 v5, vcc, 1.0, v2, 1.0
	v_mul_f32_e32 v6, v5, v4
	v_fma_f32 v7, -v3, v6, v5
	v_fmac_f32_e32 v6, v7, v4
	v_fma_f32 v3, -v3, v6, v5
	v_div_fmas_f32 v3, v3, v4, v6
	v_div_fixup_f32 v2, v3, v2, 1.0
	v_mul_f32_e32 v3, v15, v2
	v_bfe_u32 v4, v3, 16, 1
	v_add3_u32 v3, v3, v4, s81
	ds_write_b16_d16_hi v1, v3 offset:6400
	v_mul_f32_e32 v3, v31, v2
	v_bfe_u32 v4, v3, 16, 1
	v_add3_u32 v3, v3, v4, s81
	ds_write_b16_d16_hi v1, v3 offset:6464
	v_mul_f32_e32 v3, v47, v2
	v_bfe_u32 v4, v3, 16, 1
	v_add3_u32 v3, v3, v4, s81
	v_mul_f32_e32 v2, v63, v2
	ds_write_b16_d16_hi v1, v3 offset:6528
	v_bfe_u32 v3, v2, 16, 1
	v_add3_u32 v2, v2, v3, s81
	ds_write_b16_d16_hi v1, v2 offset:6592
	v_fmamk_f32 v2, v67, 0x3c000000, v115
	v_cmp_gt_f32_e32 vcc, s80, v2
	v_mul_f32_e32 v3, 0x4f800000, v2
	s_nop 0
	v_cndmask_b32_e32 v2, v2, v3, vcc
	v_sqrt_f32_e32 v3, v2
	s_nop 0
	v_add_u32_e32 v4, -1, v3
	v_fma_f32 v5, -v4, v3, v2
	v_cmp_ge_f32_e64 s[34:35], 0, v5
	v_add_u32_e32 v5, 1, v3
	s_nop 0
	v_cndmask_b32_e64 v4, v3, v4, s[34:35]
	v_fma_f32 v3, -v5, v3, v2
	v_cmp_lt_f32_e64 s[34:35], 0, v3
	s_nop 1
	v_cndmask_b32_e64 v3, v4, v5, s[34:35]
	v_mul_f32_e32 v4, 0x37800000, v3
	v_cndmask_b32_e32 v3, v3, v4, vcc
	v_cmp_class_f32_e32 vcc, v2, v117
	s_nop 1
	v_cndmask_b32_e32 v2, v3, v2, vcc
	v_div_scale_f32 v3, s[2:3], v2, v2, 1.0
	v_rcp_f32_e32 v4, v3
	s_nop 0
	v_fma_f32 v5, -v3, v4, 1.0
	v_fmac_f32_e32 v4, v5, v4
	v_div_scale_f32 v5, vcc, 1.0, v2, 1.0
	v_mul_f32_e32 v6, v5, v4
	v_fma_f32 v7, -v3, v6, v5
	v_fmac_f32_e32 v6, v7, v4
	v_fma_f32 v3, -v3, v6, v5
	v_div_fmas_f32 v3, v3, v4, v6
	v_div_fixup_f32 v2, v3, v2, 1.0
	v_mul_f32_e32 v3, v16, v2
	v_bfe_u32 v4, v3, 16, 1
	v_add3_u32 v3, v3, v4, s81
	ds_write_b16_d16_hi v1, v3 offset:6656
	v_mul_f32_e32 v3, v32, v2
	v_bfe_u32 v4, v3, 16, 1
	v_add3_u32 v3, v3, v4, s81
	ds_write_b16_d16_hi v1, v3 offset:6720
	v_mul_f32_e32 v3, v48, v2
	v_bfe_u32 v4, v3, 16, 1
	v_add3_u32 v3, v3, v4, s81
	v_mul_f32_e32 v2, v64, v2
	ds_write_b16_d16_hi v1, v3 offset:6784
	v_bfe_u32 v3, v2, 16, 1
	v_add3_u32 v2, v2, v3, s81
	ds_write_b16_d16_hi v1, v2 offset:6848
	v_fmamk_f32 v2, v66, 0x3c000000, v115
	v_cmp_gt_f32_e32 vcc, s80, v2
	v_mul_f32_e32 v3, 0x4f800000, v2
	s_nop 0
	v_cndmask_b32_e32 v2, v2, v3, vcc
	v_sqrt_f32_e32 v3, v2
	s_nop 0
	v_add_u32_e32 v4, -1, v3
	v_fma_f32 v5, -v4, v3, v2
	v_cmp_ge_f32_e64 s[34:35], 0, v5
	v_add_u32_e32 v5, 1, v3
	s_nop 0
	v_cndmask_b32_e64 v4, v3, v4, s[34:35]
	v_fma_f32 v3, -v5, v3, v2
	v_cmp_lt_f32_e64 s[34:35], 0, v3
	s_nop 1
	v_cndmask_b32_e64 v3, v4, v5, s[34:35]
	v_mul_f32_e32 v4, 0x37800000, v3
	v_cndmask_b32_e32 v3, v3, v4, vcc
	v_cmp_class_f32_e32 vcc, v2, v117
	s_or_b64 s[34:35], s[66:67], s[60:61]
	s_nop 0
	v_cndmask_b32_e32 v2, v3, v2, vcc
	v_div_scale_f32 v3, s[2:3], v2, v2, 1.0
	v_rcp_f32_e32 v4, v3
	s_lshl_b32 s2, s56, 2
	s_lshl_b32 s56, s56, 1
	v_lshl_add_u64 v[10:11], v[10:11], 0, s[56:57]
	v_fma_f32 v5, -v3, v4, 1.0
	v_fmac_f32_e32 v4, v5, v4
	v_div_scale_f32 v5, vcc, 1.0, v2, 1.0
	v_mul_f32_e32 v6, v5, v4
	v_fma_f32 v7, -v3, v6, v5
	v_fmac_f32_e32 v6, v7, v4
	v_fma_f32 v3, -v3, v6, v5
	v_div_fmas_f32 v3, v3, v4, v6
	v_div_fixup_f32 v2, v3, v2, 1.0
	v_mul_f32_e32 v3, v17, v2
	v_bfe_u32 v4, v3, 16, 1
	v_add3_u32 v3, v3, v4, s81
	ds_write_b16_d16_hi v1, v3 offset:6912
	v_mul_f32_e32 v3, v33, v2
	v_bfe_u32 v4, v3, 16, 1
	v_add3_u32 v3, v3, v4, s81
	ds_write_b16_d16_hi v1, v3 offset:6976
	v_mul_f32_e32 v3, v49, v2
	v_bfe_u32 v4, v3, 16, 1
	v_add3_u32 v3, v3, v4, s81
	v_mul_f32_e32 v2, v65, v2
	ds_write_b16_d16_hi v1, v3 offset:7040
	v_bfe_u32 v3, v2, 16, 1
	v_add3_u32 v2, v2, v3, s81
	v_lshl_add_u64 v[10:11], v[10:11], 0, v[134:135]
	ds_write_b16_d16_hi v1, v2 offset:7104
	s_mov_b32 s3, s57
	v_add_co_u32_e32 v16, vcc, s76, v10
	s_waitcnt lgkmcnt(0)
	v_lshl_add_u64 v[6:7], v[108:109], 0, s[2:3]
	s_nop 0
	v_addc_co_u32_e32 v17, vcc, 0, v11, vcc
	global_load_dwordx4 v[2:5], v[6:7], off offset:16
	s_nop 0
	global_load_dwordx4 v[6:9], v[6:7], off
	ds_read_b128 v[12:15], v119
	global_load_dwordx4 v[16:19], v[16:17], off offset:1024
	s_movk_i32 s2, 0x7000
	s_cmpk_lt_i32 s84, 0x200
	s_waitcnt lgkmcnt(0)
	v_lshlrev_b32_e32 v21, 16, v13
	v_lshlrev_b32_e32 v20, 16, v12
	v_and_b32_e32 v13, 0xffff0000, v13
	v_and_b32_e32 v12, 0xffff0000, v12
	s_waitcnt vmcnt(1)
	v_mov_b32_e32 v42, v6
	v_mov_b32_e32 v43, v8
	s_waitcnt vmcnt(0)
	v_lshlrev_b32_e32 v23, 16, v17
	v_lshlrev_b32_e32 v22, 16, v16
	v_and_b32_e32 v16, 0xffff0000, v16
	v_mul_f32_e32 v25, 0xbfb8aa3b, v16
	v_mul_f32_e32 v6, 0xbfb8aa3b, v23
	v_exp_f32_e32 v25, v25
	v_exp_f32_e32 v6, v6
	v_and_b32_e32 v17, 0xffff0000, v17
	v_mov_b32_e32 v8, v7
	v_add_f32_e32 v25, 1.0, v25
	v_add_f32_e32 v6, 1.0, v6
	v_rcp_f32_e32 v26, v25
	v_rcp_f32_e32 v25, v6
	v_pk_mul_f32 v[6:7], v[8:9], v[12:13]
	v_mul_f32_e32 v12, 0xbfb8aa3b, v17
	v_exp_f32_e32 v12, v12
	v_mul_f32_e32 v24, 0xbfb8aa3b, v22
	v_exp_f32_e32 v24, v24
	v_pk_mul_f32 v[20:21], v[42:43], v[20:21]
	v_add_f32_e32 v12, 1.0, v12
	v_rcp_f32_e32 v27, v12
	v_pk_mul_f32 v[20:21], v[20:21], v[22:23]
	v_pk_mul_f32 v[6:7], v[6:7], v[16:17]
	v_lshlrev_b32_e32 v22, 16, v18
	v_pk_mul_f32 v[12:13], v[26:27], v[6:7]
	v_mul_f32_e32 v6, 0xbfb8aa3b, v22
	v_add_f32_e32 v24, 1.0, v24
	v_exp_f32_e32 v6, v6
	v_rcp_f32_e32 v24, v24
	v_and_b32_e32 v18, 0xffff0000, v18
	v_lshlrev_b32_e32 v23, 16, v19
	v_add_f32_e32 v6, 1.0, v6
	v_pk_mul_f32 v[20:21], v[24:25], v[20:21]
	v_rcp_f32_e32 v24, v6
	v_mul_f32_e32 v6, 0xbfb8aa3b, v18
	v_exp_f32_e32 v6, v6
	v_lshlrev_b32_e32 v17, 16, v15
	v_lshlrev_b32_e32 v16, 16, v14
	v_and_b32_e32 v15, 0xffff0000, v15
	v_add_f32_e32 v6, 1.0, v6
	v_rcp_f32_e32 v26, v6
	v_mov_b32_e32 v6, v2
	v_mul_f32_e32 v2, 0xbfb8aa3b, v23
	v_exp_f32_e32 v2, v2
	v_and_b32_e32 v14, 0xffff0000, v14
	v_and_b32_e32 v19, 0xffff0000, v19
	v_mov_b32_e32 v7, v4
	v_add_f32_e32 v2, 1.0, v2
	v_mov_b32_e32 v4, v3
	v_rcp_f32_e32 v25, v2
	v_pk_mul_f32 v[2:3], v[4:5], v[14:15]
	v_mul_f32_e32 v14, 0xbfb8aa3b, v19
	v_exp_f32_e32 v14, v14
	v_pk_mul_f32 v[16:17], v[6:7], v[16:17]
	v_pk_mul_f32 v[2:3], v[2:3], v[18:19]
	v_pk_mul_f32 v[16:17], v[16:17], v[22:23]
	v_add_f32_e32 v14, 1.0, v14
	v_rcp_f32_e32 v27, v14
	v_pk_mul_f32 v[16:17], v[24:25], v[16:17]
	v_bfe_u32 v18, v13, 16, 1
	v_bfe_u32 v19, v12, 16, 1
	v_pk_mul_f32 v[2:3], v[26:27], v[2:3]
	v_add3_u32 v12, v12, v19, s81
	v_add3_u32 v13, v13, v18, s81
	v_bfe_u32 v18, v16, 16, 1
	v_bfe_u32 v19, v17, 16, 1
	v_bfe_u32 v14, v3, 16, 1
	v_bfe_u32 v15, v2, 16, 1
	v_add3_u32 v17, v17, v19, s81
	v_add3_u32 v16, v16, v18, s81
	v_add3_u32 v2, v2, v15, s81
	v_add3_u32 v3, v3, v14, s81
	v_lshrrev_b32_e32 v16, 16, v16
	v_lshrrev_b32_e32 v17, 16, v17
	v_and_or_b32 v37, v3, s82, v17
	v_and_or_b32 v36, v2, s82, v16
	v_mov_b32_e32 v3, s35
	v_or_b32_e32 v2, s34, v106
	v_lshlrev_b64 v[2:3], 11, v[2:3]
	v_lshl_add_u64 v[2:3], s[42:43], 0, v[2:3]
	v_lshl_add_u64 v[2:3], v[2:3], 0, s[56:57]
	v_bfe_u32 v14, v20, 16, 1
	v_lshl_add_u64 v[2:3], v[2:3], 0, v[134:135]
	v_bfe_u32 v15, v21, 16, 1
	v_add3_u32 v14, v20, v14, s81
	v_add_co_u32_e32 v2, vcc, s83, v2
	v_add3_u32 v15, v21, v15, s81
	v_lshrrev_b32_e32 v14, 16, v14
	v_addc_co_u32_e32 v3, vcc, 0, v3, vcc
	v_lshrrev_b32_e32 v15, 16, v15
	v_and_or_b32 v34, v12, s82, v14
	v_add_co_u32_e32 v12, vcc, s2, v10
	v_and_or_b32 v35, v13, s82, v15
	s_nop 0
	v_addc_co_u32_e32 v13, vcc, 0, v11, vcc
	global_load_dwordx4 v[38:41], v[12:13], off offset:1024
	v_add_co_u32_e32 v12, vcc, s77, v10
	s_mov_b32 s2, 0x13000
	s_nop 0
	v_addc_co_u32_e32 v13, vcc, 0, v11, vcc
	global_load_dwordx4 v[30:33], v[12:13], off offset:1024
	v_add_co_u32_e32 v12, vcc, s2, v10
	s_mov_b32 s2, 0x1f000
	s_nop 0
	v_addc_co_u32_e32 v13, vcc, 0, v11, vcc
	global_load_dwordx4 v[26:29], v[12:13], off offset:1024
	v_add_co_u32_e32 v12, vcc, s78, v10
	s_waitcnt vmcnt(2)
	v_lshlrev_b32_e32 v45, 16, v39
	v_addc_co_u32_e32 v13, vcc, 0, v11, vcc
	global_load_dwordx4 v[22:25], v[12:13], off offset:1024
	v_add_co_u32_e32 v12, vcc, s2, v10
	s_mov_b32 s2, 0x2b000
	s_nop 0
	v_addc_co_u32_e32 v13, vcc, 0, v11, vcc
	global_load_dwordx4 v[18:21], v[12:13], off offset:1024
	v_add_co_u32_e32 v12, vcc, s79, v10
	v_lshlrev_b32_e32 v44, 16, v38
	s_nop 0
	v_addc_co_u32_e32 v13, vcc, 0, v11, vcc
	v_add_co_u32_e32 v10, vcc, s2, v10
	global_load_dwordx4 v[14:17], v[12:13], off offset:1024
	s_nop 0
	v_addc_co_u32_e32 v11, vcc, 0, v11, vcc
	global_load_dwordx4 v[10:13], v[10:11], off offset:1024
	v_and_b32_e32 v38, 0xffff0000, v38
	global_store_dwordx4 v[2:3], v[34:37], off offset:1024
	ds_read_b128 v[34:37], v121
	v_mul_f32_e32 v46, 0xbfb8aa3b, v44
	v_mul_f32_e32 v47, 0xbfb8aa3b, v38
	v_and_b32_e32 v39, 0xffff0000, v39
	v_exp_f32_e32 v46, v46
	s_waitcnt lgkmcnt(0)
	v_lshlrev_b32_e32 v3, 16, v35
	v_lshlrev_b32_e32 v2, 16, v34
	v_pk_mul_f32 v[2:3], v[42:43], v[2:3]
	v_and_b32_e32 v35, 0xffff0000, v35
	v_and_b32_e32 v34, 0xffff0000, v34
	v_pk_mul_f32 v[2:3], v[2:3], v[44:45]
	v_mul_f32_e32 v44, 0xbfb8aa3b, v45
	v_exp_f32_e32 v47, v47
	v_exp_f32_e32 v44, v44
	v_pk_mul_f32 v[34:35], v[8:9], v[34:35]
	v_add_f32_e32 v46, 1.0, v46
	v_pk_mul_f32 v[34:35], v[34:35], v[38:39]
	v_mul_f32_e32 v38, 0xbfb8aa3b, v39
	v_exp_f32_e32 v38, v38
	v_add_f32_e32 v47, 1.0, v47
	v_add_f32_e32 v44, 1.0, v44
	v_rcp_f32_e32 v46, v46
	v_rcp_f32_e32 v48, v47
	v_rcp_f32_e32 v47, v44
	v_add_f32_e32 v38, 1.0, v38
	v_rcp_f32_e32 v49, v38
	v_lshlrev_b32_e32 v39, 16, v37
	v_lshlrev_b32_e32 v38, 16, v36
	v_and_b32_e32 v37, 0xffff0000, v37
	v_and_b32_e32 v36, 0xffff0000, v36
	v_lshlrev_b32_e32 v45, 16, v41
	v_lshlrev_b32_e32 v44, 16, v40
	v_and_b32_e32 v41, 0xffff0000, v41
	v_and_b32_e32 v40, 0xffff0000, v40
	v_pk_mul_f32 v[36:37], v[4:5], v[36:37]
	v_pk_mul_f32 v[2:3], v[46:47], v[2:3]
	v_mul_f32_e32 v47, 0xbfb8aa3b, v40
	v_pk_mul_f32 v[36:37], v[36:37], v[40:41]
	v_mul_f32_e32 v40, 0xbfb8aa3b, v41
	v_exp_f32_e32 v47, v47
	v_exp_f32_e32 v40, v40
	v_pk_mul_f32 v[34:35], v[48:49], v[34:35]
	v_pk_mul_f32 v[38:39], v[6:7], v[38:39]
	v_add_f32_e32 v47, 1.0, v47
	v_add_f32_e32 v40, 1.0, v40
	v_rcp_f32_e32 v48, v47
	v_rcp_f32_e32 v49, v40
	v_mul_f32_e32 v46, 0xbfb8aa3b, v44
	v_pk_mul_f32 v[38:39], v[38:39], v[44:45]
	v_mul_f32_e32 v44, 0xbfb8aa3b, v45
	v_exp_f32_e32 v46, v46
	v_exp_f32_e32 v44, v44
	v_pk_mul_f32 v[36:37], v[48:49], v[36:37]
	v_bfe_u32 v45, v34, 16, 1
	v_bfe_u32 v40, v37, 16, 1
	v_bfe_u32 v41, v36, 16, 1
	v_add_f32_e32 v46, 1.0, v46
	v_add_f32_e32 v44, 1.0, v44
	v_add3_u32 v36, v36, v41, s81
	v_add3_u32 v37, v37, v40, s81
	v_bfe_u32 v40, v2, 16, 1
	v_bfe_u32 v41, v3, 16, 1
	v_rcp_f32_e32 v46, v46
	v_rcp_f32_e32 v47, v44
	v_bfe_u32 v44, v35, 16, 1
	v_add3_u32 v3, v3, v41, s81
	v_add3_u32 v2, v2, v40, s81
	v_add3_u32 v34, v34, v45, s81
	v_add3_u32 v35, v35, v44, s81
	v_lshrrev_b32_e32 v2, 16, v2
	v_lshrrev_b32_e32 v3, 16, v3
	v_and_or_b32 v35, v35, s82, v3
	v_and_or_b32 v34, v34, s82, v2
	v_mov_b32_e32 v3, s35
	v_or_b32_e32 v2, s34, v112
	v_lshlrev_b64 v[2:3], 11, v[2:3]
	v_pk_mul_f32 v[38:39], v[46:47], v[38:39]
	v_lshl_add_u64 v[2:3], s[42:43], 0, v[2:3]
	v_bfe_u32 v44, v38, 16, 1
	v_bfe_u32 v45, v39, 16, 1
	v_lshl_add_u64 v[2:3], v[2:3], 0, s[56:57]
	v_add3_u32 v39, v39, v45, s81
	v_add3_u32 v38, v38, v44, s81
	v_lshl_add_u64 v[2:3], v[2:3], 0, v[134:135]
	v_lshrrev_b32_e32 v38, 16, v38
	v_lshrrev_b32_e32 v39, 16, v39
	v_add_co_u32_e32 v2, vcc, s83, v2
	v_and_or_b32 v37, v37, s82, v39
	v_and_or_b32 v36, v36, s82, v38
	v_addc_co_u32_e32 v3, vcc, 0, v3, vcc
	global_store_dwordx4 v[2:3], v[34:37], off offset:1024
	ds_read_b128 v[34:37], v123
	s_waitcnt vmcnt(7)
	v_lshlrev_b32_e32 v39, 16, v31
	v_lshlrev_b32_e32 v38, 16, v30
	v_and_b32_e32 v31, 0xffff0000, v31
	v_and_b32_e32 v30, 0xffff0000, v30
	s_waitcnt lgkmcnt(0)
	v_lshlrev_b32_e32 v3, 16, v35
	v_lshlrev_b32_e32 v2, 16, v34
	v_and_b32_e32 v35, 0xffff0000, v35
	v_and_b32_e32 v34, 0xffff0000, v34
	v_pk_mul_f32 v[34:35], v[8:9], v[34:35]
	v_mul_f32_e32 v41, 0xbfb8aa3b, v30
	v_pk_mul_f32 v[34:35], v[34:35], v[30:31]
	v_mul_f32_e32 v30, 0xbfb8aa3b, v31
	v_exp_f32_e32 v41, v41
	v_pk_mul_f32 v[2:3], v[42:43], v[2:3]
	v_exp_f32_e32 v30, v30
	v_mul_f32_e32 v40, 0xbfb8aa3b, v38
	v_pk_mul_f32 v[2:3], v[2:3], v[38:39]
	v_mul_f32_e32 v38, 0xbfb8aa3b, v39
	v_exp_f32_e32 v40, v40
	v_exp_f32_e32 v38, v38
	v_add_f32_e32 v41, 1.0, v41
	v_add_f32_e32 v30, 1.0, v30
	v_rcp_f32_e32 v44, v41
	v_rcp_f32_e32 v45, v30
	v_add_f32_e32 v40, 1.0, v40
	v_add_f32_e32 v38, 1.0, v38
	v_rcp_f32_e32 v40, v40
	v_rcp_f32_e32 v41, v38
	v_pk_mul_f32 v[30:31], v[44:45], v[34:35]
	v_lshlrev_b32_e32 v35, 16, v37
	v_lshlrev_b32_e32 v34, 16, v36
	v_and_b32_e32 v37, 0xffff0000, v37
	v_and_b32_e32 v36, 0xffff0000, v36
	v_lshlrev_b32_e32 v39, 16, v33
	v_lshlrev_b32_e32 v38, 16, v32
	v_and_b32_e32 v33, 0xffff0000, v33
	v_and_b32_e32 v32, 0xffff0000, v32
	v_pk_mul_f32 v[36:37], v[4:5], v[36:37]
	v_pk_mul_f32 v[2:3], v[40:41], v[2:3]
	v_mul_f32_e32 v41, 0xbfb8aa3b, v32
	v_pk_mul_f32 v[36:37], v[36:37], v[32:33]
	v_mul_f32_e32 v32, 0xbfb8aa3b, v33
	v_exp_f32_e32 v41, v41
	v_exp_f32_e32 v32, v32
	v_pk_mul_f32 v[34:35], v[6:7], v[34:35]
	v_mul_f32_e32 v40, 0xbfb8aa3b, v38
	v_add_f32_e32 v41, 1.0, v41
	v_add_f32_e32 v32, 1.0, v32
	v_rcp_f32_e32 v44, v41
	v_rcp_f32_e32 v45, v32
	v_pk_mul_f32 v[34:35], v[34:35], v[38:39]
	v_mul_f32_e32 v38, 0xbfb8aa3b, v39
	v_exp_f32_e32 v40, v40
	v_exp_f32_e32 v38, v38
	v_pk_mul_f32 v[32:33], v[44:45], v[36:37]
	v_bfe_u32 v39, v30, 16, 1
	v_bfe_u32 v36, v33, 16, 1
	v_bfe_u32 v37, v32, 16, 1
	v_add_f32_e32 v40, 1.0, v40
	v_add_f32_e32 v38, 1.0, v38
	v_add3_u32 v32, v32, v37, s81
	v_add3_u32 v33, v33, v36, s81
	v_bfe_u32 v36, v2, 16, 1
	v_bfe_u32 v37, v3, 16, 1
	v_rcp_f32_e32 v40, v40
	v_rcp_f32_e32 v41, v38
	v_bfe_u32 v38, v31, 16, 1
	v_add3_u32 v3, v3, v37, s81
	v_add3_u32 v2, v2, v36, s81
	v_add3_u32 v30, v30, v39, s81
	v_add3_u32 v31, v31, v38, s81
	v_lshrrev_b32_e32 v2, 16, v2
	v_lshrrev_b32_e32 v3, 16, v3
	v_and_or_b32 v31, v31, s82, v3
	v_and_or_b32 v30, v30, s82, v2
	v_mov_b32_e32 v3, s35
	v_or_b32_e32 v2, s34, v114
	v_lshlrev_b64 v[2:3], 11, v[2:3]
	v_pk_mul_f32 v[34:35], v[40:41], v[34:35]
	v_lshl_add_u64 v[2:3], s[42:43], 0, v[2:3]
	v_bfe_u32 v38, v34, 16, 1
	v_bfe_u32 v39, v35, 16, 1
	v_lshl_add_u64 v[2:3], v[2:3], 0, s[56:57]
	v_add3_u32 v35, v35, v39, s81
	v_add3_u32 v34, v34, v38, s81
	v_lshl_add_u64 v[2:3], v[2:3], 0, v[134:135]
	v_lshrrev_b32_e32 v34, 16, v34
	v_lshrrev_b32_e32 v35, 16, v35
	v_add_co_u32_e32 v2, vcc, s83, v2
	v_and_or_b32 v33, v33, s82, v35
	v_and_or_b32 v32, v32, s82, v34
	v_addc_co_u32_e32 v3, vcc, 0, v3, vcc
	global_store_dwordx4 v[2:3], v[30:33], off offset:1024
	ds_read_b128 v[30:33], v125
	s_waitcnt vmcnt(7)
	v_lshlrev_b32_e32 v35, 16, v27
	v_lshlrev_b32_e32 v34, 16, v26
	v_and_b32_e32 v27, 0xffff0000, v27
	v_and_b32_e32 v26, 0xffff0000, v26
	s_waitcnt lgkmcnt(0)
	v_lshlrev_b32_e32 v3, 16, v31
	v_lshlrev_b32_e32 v2, 16, v30
	v_and_b32_e32 v31, 0xffff0000, v31
	v_and_b32_e32 v30, 0xffff0000, v30
	v_pk_mul_f32 v[30:31], v[8:9], v[30:31]
	v_mul_f32_e32 v37, 0xbfb8aa3b, v26
	v_pk_mul_f32 v[30:31], v[30:31], v[26:27]
	v_mul_f32_e32 v26, 0xbfb8aa3b, v27
	v_exp_f32_e32 v37, v37
	v_pk_mul_f32 v[2:3], v[42:43], v[2:3]
	v_exp_f32_e32 v26, v26
	v_mul_f32_e32 v36, 0xbfb8aa3b, v34
	v_pk_mul_f32 v[2:3], v[2:3], v[34:35]
	v_mul_f32_e32 v34, 0xbfb8aa3b, v35
	v_exp_f32_e32 v36, v36
	v_exp_f32_e32 v34, v34
	v_add_f32_e32 v37, 1.0, v37
	v_add_f32_e32 v26, 1.0, v26
	v_rcp_f32_e32 v38, v37
	v_rcp_f32_e32 v39, v26
	v_add_f32_e32 v36, 1.0, v36
	v_add_f32_e32 v34, 1.0, v34
	v_rcp_f32_e32 v36, v36
	v_rcp_f32_e32 v37, v34
	v_pk_mul_f32 v[26:27], v[38:39], v[30:31]
	v_lshlrev_b32_e32 v31, 16, v33
	v_lshlrev_b32_e32 v30, 16, v32
	v_and_b32_e32 v33, 0xffff0000, v33
	v_and_b32_e32 v32, 0xffff0000, v32
	v_lshlrev_b32_e32 v35, 16, v29
	v_lshlrev_b32_e32 v34, 16, v28
	v_and_b32_e32 v29, 0xffff0000, v29
	v_and_b32_e32 v28, 0xffff0000, v28
	v_pk_mul_f32 v[32:33], v[4:5], v[32:33]
	v_pk_mul_f32 v[2:3], v[36:37], v[2:3]
	v_mul_f32_e32 v37, 0xbfb8aa3b, v28
	v_pk_mul_f32 v[32:33], v[32:33], v[28:29]
	v_mul_f32_e32 v28, 0xbfb8aa3b, v29
	v_exp_f32_e32 v37, v37
	v_exp_f32_e32 v28, v28
	v_pk_mul_f32 v[30:31], v[6:7], v[30:31]
	v_mul_f32_e32 v36, 0xbfb8aa3b, v34
	v_add_f32_e32 v37, 1.0, v37
	v_add_f32_e32 v28, 1.0, v28
	v_rcp_f32_e32 v38, v37
	v_rcp_f32_e32 v39, v28
	v_pk_mul_f32 v[30:31], v[30:31], v[34:35]
	v_mul_f32_e32 v34, 0xbfb8aa3b, v35
	v_exp_f32_e32 v36, v36
	v_exp_f32_e32 v34, v34
	v_pk_mul_f32 v[28:29], v[38:39], v[32:33]
	v_bfe_u32 v35, v26, 16, 1
	v_bfe_u32 v32, v29, 16, 1
	v_bfe_u32 v33, v28, 16, 1
	v_add_f32_e32 v36, 1.0, v36
	v_add_f32_e32 v34, 1.0, v34
	v_add3_u32 v28, v28, v33, s81
	v_add3_u32 v29, v29, v32, s81
	v_bfe_u32 v32, v2, 16, 1
	v_bfe_u32 v33, v3, 16, 1
	v_rcp_f32_e32 v36, v36
	v_rcp_f32_e32 v37, v34
	v_bfe_u32 v34, v27, 16, 1
	v_add3_u32 v3, v3, v33, s81
	v_add3_u32 v2, v2, v32, s81
	v_add3_u32 v26, v26, v35, s81
	v_add3_u32 v27, v27, v34, s81
	v_lshrrev_b32_e32 v2, 16, v2
	v_lshrrev_b32_e32 v3, 16, v3
	v_and_or_b32 v27, v27, s82, v3
	v_and_or_b32 v26, v26, s82, v2
	v_mov_b32_e32 v3, s35
	v_or_b32_e32 v2, s34, v116
	v_lshlrev_b64 v[2:3], 11, v[2:3]
	v_pk_mul_f32 v[30:31], v[36:37], v[30:31]
	v_lshl_add_u64 v[2:3], s[42:43], 0, v[2:3]
	v_bfe_u32 v34, v30, 16, 1
	v_bfe_u32 v35, v31, 16, 1
	v_lshl_add_u64 v[2:3], v[2:3], 0, s[56:57]
	v_add3_u32 v31, v31, v35, s81
	v_add3_u32 v30, v30, v34, s81
	v_lshl_add_u64 v[2:3], v[2:3], 0, v[134:135]
	v_lshrrev_b32_e32 v30, 16, v30
	v_lshrrev_b32_e32 v31, 16, v31
	v_add_co_u32_e32 v2, vcc, s83, v2
	v_and_or_b32 v29, v29, s82, v31
	v_and_or_b32 v28, v28, s82, v30
	v_addc_co_u32_e32 v3, vcc, 0, v3, vcc
	global_store_dwordx4 v[2:3], v[26:29], off offset:1024
	ds_read_b128 v[26:29], v136
	s_waitcnt vmcnt(7)
	v_lshlrev_b32_e32 v31, 16, v23
	v_lshlrev_b32_e32 v30, 16, v22
	v_and_b32_e32 v23, 0xffff0000, v23
	v_and_b32_e32 v22, 0xffff0000, v22
	s_waitcnt lgkmcnt(0)
	v_lshlrev_b32_e32 v3, 16, v27
	v_lshlrev_b32_e32 v2, 16, v26
	v_and_b32_e32 v27, 0xffff0000, v27
	v_and_b32_e32 v26, 0xffff0000, v26
	v_pk_mul_f32 v[26:27], v[8:9], v[26:27]
	v_mul_f32_e32 v33, 0xbfb8aa3b, v22
	v_pk_mul_f32 v[26:27], v[26:27], v[22:23]
	v_mul_f32_e32 v22, 0xbfb8aa3b, v23
	v_exp_f32_e32 v33, v33
	v_pk_mul_f32 v[2:3], v[42:43], v[2:3]
	v_exp_f32_e32 v22, v22
	v_mul_f32_e32 v32, 0xbfb8aa3b, v30
	v_pk_mul_f32 v[2:3], v[2:3], v[30:31]
	v_mul_f32_e32 v30, 0xbfb8aa3b, v31
	v_exp_f32_e32 v32, v32
	v_exp_f32_e32 v30, v30
	v_add_f32_e32 v33, 1.0, v33
	v_add_f32_e32 v22, 1.0, v22
	v_rcp_f32_e32 v34, v33
	v_rcp_f32_e32 v35, v22
	v_add_f32_e32 v32, 1.0, v32
	v_add_f32_e32 v30, 1.0, v30
	v_rcp_f32_e32 v32, v32
	v_rcp_f32_e32 v33, v30
	v_pk_mul_f32 v[22:23], v[34:35], v[26:27]
	v_lshlrev_b32_e32 v27, 16, v29
	v_lshlrev_b32_e32 v26, 16, v28
	v_and_b32_e32 v29, 0xffff0000, v29
	v_and_b32_e32 v28, 0xffff0000, v28
	v_lshlrev_b32_e32 v31, 16, v25
	v_lshlrev_b32_e32 v30, 16, v24
	v_and_b32_e32 v25, 0xffff0000, v25
	v_and_b32_e32 v24, 0xffff0000, v24
	v_pk_mul_f32 v[28:29], v[4:5], v[28:29]
	v_pk_mul_f32 v[2:3], v[32:33], v[2:3]
	v_mul_f32_e32 v33, 0xbfb8aa3b, v24
	v_pk_mul_f32 v[28:29], v[28:29], v[24:25]
	v_mul_f32_e32 v24, 0xbfb8aa3b, v25
	v_exp_f32_e32 v33, v33
	v_exp_f32_e32 v24, v24
	v_pk_mul_f32 v[26:27], v[6:7], v[26:27]
	v_mul_f32_e32 v32, 0xbfb8aa3b, v30
	v_add_f32_e32 v33, 1.0, v33
	v_add_f32_e32 v24, 1.0, v24
	v_rcp_f32_e32 v34, v33
	v_rcp_f32_e32 v35, v24
	v_pk_mul_f32 v[26:27], v[26:27], v[30:31]
	v_mul_f32_e32 v30, 0xbfb8aa3b, v31
	v_exp_f32_e32 v32, v32
	v_exp_f32_e32 v30, v30
	v_pk_mul_f32 v[24:25], v[34:35], v[28:29]
	v_bfe_u32 v31, v22, 16, 1
	v_bfe_u32 v28, v25, 16, 1
	v_bfe_u32 v29, v24, 16, 1
	v_add_f32_e32 v32, 1.0, v32
	v_add_f32_e32 v30, 1.0, v30
	v_add3_u32 v24, v24, v29, s81
	v_add3_u32 v25, v25, v28, s81
	v_bfe_u32 v28, v2, 16, 1
	v_bfe_u32 v29, v3, 16, 1
	v_rcp_f32_e32 v32, v32
	v_rcp_f32_e32 v33, v30
	v_bfe_u32 v30, v23, 16, 1
	v_add3_u32 v3, v3, v29, s81
	v_add3_u32 v2, v2, v28, s81
	v_add3_u32 v22, v22, v31, s81
	v_add3_u32 v23, v23, v30, s81
	v_lshrrev_b32_e32 v2, 16, v2
	v_lshrrev_b32_e32 v3, 16, v3
	v_and_or_b32 v23, v23, s82, v3
	v_and_or_b32 v22, v22, s82, v2
	v_mov_b32_e32 v3, s35
	v_or_b32_e32 v2, s34, v118
	v_lshlrev_b64 v[2:3], 11, v[2:3]
	v_pk_mul_f32 v[26:27], v[32:33], v[26:27]
	v_lshl_add_u64 v[2:3], s[42:43], 0, v[2:3]
	v_bfe_u32 v30, v26, 16, 1
	v_bfe_u32 v31, v27, 16, 1
	v_lshl_add_u64 v[2:3], v[2:3], 0, s[56:57]
	v_add3_u32 v27, v27, v31, s81
	v_add3_u32 v26, v26, v30, s81
	v_lshl_add_u64 v[2:3], v[2:3], 0, v[134:135]
	v_lshrrev_b32_e32 v26, 16, v26
	v_lshrrev_b32_e32 v27, 16, v27
	v_add_co_u32_e32 v2, vcc, s83, v2
	v_and_or_b32 v25, v25, s82, v27
	v_and_or_b32 v24, v24, s82, v26
	v_addc_co_u32_e32 v3, vcc, 0, v3, vcc
	global_store_dwordx4 v[2:3], v[22:25], off offset:1024
	ds_read_b128 v[22:25], v137
	s_waitcnt vmcnt(7)
	v_lshlrev_b32_e32 v27, 16, v19
	v_lshlrev_b32_e32 v26, 16, v18
	v_and_b32_e32 v19, 0xffff0000, v19
	v_and_b32_e32 v18, 0xffff0000, v18
	s_waitcnt lgkmcnt(0)
	v_lshlrev_b32_e32 v3, 16, v23
	v_lshlrev_b32_e32 v2, 16, v22
	v_and_b32_e32 v23, 0xffff0000, v23
	v_and_b32_e32 v22, 0xffff0000, v22
	v_pk_mul_f32 v[22:23], v[8:9], v[22:23]
	v_mul_f32_e32 v29, 0xbfb8aa3b, v18
	v_pk_mul_f32 v[22:23], v[22:23], v[18:19]
	v_mul_f32_e32 v18, 0xbfb8aa3b, v19
	v_exp_f32_e32 v29, v29
	v_pk_mul_f32 v[2:3], v[42:43], v[2:3]
	v_exp_f32_e32 v18, v18
	v_mul_f32_e32 v28, 0xbfb8aa3b, v26
	v_pk_mul_f32 v[2:3], v[2:3], v[26:27]
	v_mul_f32_e32 v26, 0xbfb8aa3b, v27
	v_exp_f32_e32 v28, v28
	v_exp_f32_e32 v26, v26
	v_add_f32_e32 v29, 1.0, v29
	v_add_f32_e32 v18, 1.0, v18
	v_rcp_f32_e32 v30, v29
	v_rcp_f32_e32 v31, v18
	v_add_f32_e32 v28, 1.0, v28
	v_add_f32_e32 v26, 1.0, v26
	v_rcp_f32_e32 v28, v28
	v_rcp_f32_e32 v29, v26
	v_pk_mul_f32 v[18:19], v[30:31], v[22:23]
	v_lshlrev_b32_e32 v23, 16, v25
	v_lshlrev_b32_e32 v22, 16, v24
	v_and_b32_e32 v25, 0xffff0000, v25
	v_and_b32_e32 v24, 0xffff0000, v24
	v_lshlrev_b32_e32 v27, 16, v21
	v_lshlrev_b32_e32 v26, 16, v20
	v_and_b32_e32 v21, 0xffff0000, v21
	v_and_b32_e32 v20, 0xffff0000, v20
	v_pk_mul_f32 v[24:25], v[4:5], v[24:25]
	v_pk_mul_f32 v[2:3], v[28:29], v[2:3]
	v_mul_f32_e32 v29, 0xbfb8aa3b, v20
	v_pk_mul_f32 v[24:25], v[24:25], v[20:21]
	v_mul_f32_e32 v20, 0xbfb8aa3b, v21
	v_exp_f32_e32 v29, v29
	v_exp_f32_e32 v20, v20
	v_pk_mul_f32 v[22:23], v[6:7], v[22:23]
	v_mul_f32_e32 v28, 0xbfb8aa3b, v26
	v_add_f32_e32 v29, 1.0, v29
	v_add_f32_e32 v20, 1.0, v20
	v_rcp_f32_e32 v30, v29
	v_rcp_f32_e32 v31, v20
	v_pk_mul_f32 v[22:23], v[22:23], v[26:27]
	v_mul_f32_e32 v26, 0xbfb8aa3b, v27
	v_exp_f32_e32 v28, v28
	v_exp_f32_e32 v26, v26
	v_pk_mul_f32 v[20:21], v[30:31], v[24:25]
	v_bfe_u32 v27, v18, 16, 1
	v_bfe_u32 v24, v21, 16, 1
	v_bfe_u32 v25, v20, 16, 1
	v_add_f32_e32 v28, 1.0, v28
	v_add_f32_e32 v26, 1.0, v26
	v_add3_u32 v20, v20, v25, s81
	v_add3_u32 v21, v21, v24, s81
	v_bfe_u32 v24, v2, 16, 1
	v_bfe_u32 v25, v3, 16, 1
	v_rcp_f32_e32 v28, v28
	v_rcp_f32_e32 v29, v26
	v_bfe_u32 v26, v19, 16, 1
	v_add3_u32 v3, v3, v25, s81
	v_add3_u32 v2, v2, v24, s81
	v_add3_u32 v18, v18, v27, s81
	v_add3_u32 v19, v19, v26, s81
	v_lshrrev_b32_e32 v2, 16, v2
	v_lshrrev_b32_e32 v3, 16, v3
	v_and_or_b32 v19, v19, s82, v3
	v_and_or_b32 v18, v18, s82, v2
	v_mov_b32_e32 v3, s35
	v_or_b32_e32 v2, s34, v120
	v_lshlrev_b64 v[2:3], 11, v[2:3]
	v_pk_mul_f32 v[22:23], v[28:29], v[22:23]
	v_lshl_add_u64 v[2:3], s[42:43], 0, v[2:3]
	v_bfe_u32 v26, v22, 16, 1
	v_bfe_u32 v27, v23, 16, 1
	v_lshl_add_u64 v[2:3], v[2:3], 0, s[56:57]
	v_add3_u32 v23, v23, v27, s81
	v_add3_u32 v22, v22, v26, s81
	v_lshl_add_u64 v[2:3], v[2:3], 0, v[134:135]
	v_lshrrev_b32_e32 v22, 16, v22
	v_lshrrev_b32_e32 v23, 16, v23
	v_add_co_u32_e32 v2, vcc, s83, v2
	v_and_or_b32 v21, v21, s82, v23
	v_and_or_b32 v20, v20, s82, v22
	v_addc_co_u32_e32 v3, vcc, 0, v3, vcc
	global_store_dwordx4 v[2:3], v[18:21], off offset:1024
	ds_read_b128 v[18:21], v138
	s_waitcnt vmcnt(7)
	v_lshlrev_b32_e32 v23, 16, v15
	v_lshlrev_b32_e32 v22, 16, v14
	v_and_b32_e32 v15, 0xffff0000, v15
	v_and_b32_e32 v14, 0xffff0000, v14
	s_waitcnt lgkmcnt(0)
	v_lshlrev_b32_e32 v3, 16, v19
	v_lshlrev_b32_e32 v2, 16, v18
	v_and_b32_e32 v19, 0xffff0000, v19
	v_and_b32_e32 v18, 0xffff0000, v18
	v_pk_mul_f32 v[18:19], v[8:9], v[18:19]
	v_mul_f32_e32 v25, 0xbfb8aa3b, v14
	v_pk_mul_f32 v[18:19], v[18:19], v[14:15]
	v_mul_f32_e32 v14, 0xbfb8aa3b, v15
	v_exp_f32_e32 v25, v25
	v_pk_mul_f32 v[2:3], v[42:43], v[2:3]
	v_exp_f32_e32 v14, v14
	v_mul_f32_e32 v24, 0xbfb8aa3b, v22
	v_pk_mul_f32 v[2:3], v[2:3], v[22:23]
	v_mul_f32_e32 v22, 0xbfb8aa3b, v23
	v_exp_f32_e32 v24, v24
	v_exp_f32_e32 v22, v22
	v_add_f32_e32 v25, 1.0, v25
	v_add_f32_e32 v14, 1.0, v14
	v_rcp_f32_e32 v26, v25
	v_rcp_f32_e32 v27, v14
	v_add_f32_e32 v24, 1.0, v24
	v_add_f32_e32 v22, 1.0, v22
	v_rcp_f32_e32 v24, v24
	v_rcp_f32_e32 v25, v22
	v_pk_mul_f32 v[14:15], v[26:27], v[18:19]
	v_lshlrev_b32_e32 v19, 16, v21
	v_lshlrev_b32_e32 v18, 16, v20
	v_and_b32_e32 v21, 0xffff0000, v21
	v_and_b32_e32 v20, 0xffff0000, v20
	v_lshlrev_b32_e32 v23, 16, v17
	v_lshlrev_b32_e32 v22, 16, v16
	v_and_b32_e32 v17, 0xffff0000, v17
	v_and_b32_e32 v16, 0xffff0000, v16
	v_pk_mul_f32 v[20:21], v[4:5], v[20:21]
	v_pk_mul_f32 v[2:3], v[24:25], v[2:3]
	v_mul_f32_e32 v25, 0xbfb8aa3b, v16
	v_pk_mul_f32 v[20:21], v[20:21], v[16:17]
	v_mul_f32_e32 v16, 0xbfb8aa3b, v17
	v_exp_f32_e32 v25, v25
	v_exp_f32_e32 v16, v16
	v_pk_mul_f32 v[18:19], v[6:7], v[18:19]
	v_mul_f32_e32 v24, 0xbfb8aa3b, v22
	v_add_f32_e32 v25, 1.0, v25
	v_add_f32_e32 v16, 1.0, v16
	v_rcp_f32_e32 v26, v25
	v_rcp_f32_e32 v27, v16
	v_pk_mul_f32 v[18:19], v[18:19], v[22:23]
	v_mul_f32_e32 v22, 0xbfb8aa3b, v23
	v_exp_f32_e32 v24, v24
	v_exp_f32_e32 v22, v22
	v_pk_mul_f32 v[16:17], v[26:27], v[20:21]
	v_bfe_u32 v23, v14, 16, 1
	v_bfe_u32 v20, v17, 16, 1
	v_bfe_u32 v21, v16, 16, 1
	v_add_f32_e32 v24, 1.0, v24
	v_add_f32_e32 v22, 1.0, v22
	v_add3_u32 v16, v16, v21, s81
	v_add3_u32 v17, v17, v20, s81
	v_bfe_u32 v20, v2, 16, 1
	v_bfe_u32 v21, v3, 16, 1
	v_rcp_f32_e32 v24, v24
	v_rcp_f32_e32 v25, v22
	v_bfe_u32 v22, v15, 16, 1
	v_add3_u32 v3, v3, v21, s81
	v_add3_u32 v2, v2, v20, s81
	v_add3_u32 v14, v14, v23, s81
	v_add3_u32 v15, v15, v22, s81
	v_lshrrev_b32_e32 v2, 16, v2
	v_lshrrev_b32_e32 v3, 16, v3
	v_and_or_b32 v15, v15, s82, v3
	v_and_or_b32 v14, v14, s82, v2
	v_mov_b32_e32 v3, s35
	v_or_b32_e32 v2, s34, v122
	v_lshlrev_b64 v[2:3], 11, v[2:3]
	v_pk_mul_f32 v[18:19], v[24:25], v[18:19]
	v_lshl_add_u64 v[2:3], s[42:43], 0, v[2:3]
	v_bfe_u32 v22, v18, 16, 1
	v_bfe_u32 v23, v19, 16, 1
	v_lshl_add_u64 v[2:3], v[2:3], 0, s[56:57]
	v_add3_u32 v19, v19, v23, s81
	v_add3_u32 v18, v18, v22, s81
	v_lshl_add_u64 v[2:3], v[2:3], 0, v[134:135]
	v_lshrrev_b32_e32 v18, 16, v18
	v_lshrrev_b32_e32 v19, 16, v19
	v_add_co_u32_e32 v2, vcc, s83, v2
	v_and_or_b32 v17, v17, s82, v19
	v_and_or_b32 v16, v16, s82, v18
	v_addc_co_u32_e32 v3, vcc, 0, v3, vcc
	global_store_dwordx4 v[2:3], v[14:17], off offset:1024
	ds_read_b128 v[14:17], v139
	s_waitcnt vmcnt(7)
	v_lshlrev_b32_e32 v19, 16, v11
	v_lshlrev_b32_e32 v18, 16, v10
	v_and_b32_e32 v11, 0xffff0000, v11
	v_and_b32_e32 v10, 0xffff0000, v10
	s_waitcnt lgkmcnt(0)
	v_lshlrev_b32_e32 v3, 16, v15
	v_lshlrev_b32_e32 v2, 16, v14
	v_and_b32_e32 v15, 0xffff0000, v15
	v_and_b32_e32 v14, 0xffff0000, v14
	v_pk_mul_f32 v[8:9], v[8:9], v[14:15]
	v_mul_f32_e32 v21, 0xbfb8aa3b, v10
	v_pk_mul_f32 v[8:9], v[8:9], v[10:11]
	v_mul_f32_e32 v10, 0xbfb8aa3b, v11
	v_exp_f32_e32 v10, v10
	v_pk_mul_f32 v[2:3], v[42:43], v[2:3]
	v_mul_f32_e32 v20, 0xbfb8aa3b, v18
	v_pk_mul_f32 v[2:3], v[2:3], v[18:19]
	v_mul_f32_e32 v18, 0xbfb8aa3b, v19
	v_exp_f32_e32 v20, v20
	v_exp_f32_e32 v21, v21
	v_exp_f32_e32 v18, v18
	v_add_f32_e32 v10, 1.0, v10
	v_rcp_f32_e32 v23, v10
	v_lshlrev_b32_e32 v11, 16, v17
	v_lshlrev_b32_e32 v10, 16, v16
	v_and_b32_e32 v15, 0xffff0000, v17
	v_and_b32_e32 v14, 0xffff0000, v16
	v_lshlrev_b32_e32 v17, 16, v13
	v_lshlrev_b32_e32 v16, 16, v12
	v_and_b32_e32 v12, 0xffff0000, v12
	v_mul_f32_e32 v19, 0xbfb8aa3b, v12
	v_pk_mul_f32 v[6:7], v[6:7], v[10:11]
	v_mul_f32_e32 v10, 0xbfb8aa3b, v17
	v_add_f32_e32 v20, 1.0, v20
	v_add_f32_e32 v21, 1.0, v21
	v_add_f32_e32 v18, 1.0, v18
	v_exp_f32_e32 v19, v19
	v_exp_f32_e32 v10, v10
	v_rcp_f32_e32 v20, v20
	v_rcp_f32_e32 v22, v21
	v_rcp_f32_e32 v21, v18
	v_and_b32_e32 v13, 0xffff0000, v13
	v_mul_f32_e32 v18, 0xbfb8aa3b, v16
	v_add_f32_e32 v19, 1.0, v19
	v_add_f32_e32 v10, 1.0, v10
	v_pk_mul_f32 v[2:3], v[20:21], v[2:3]
	v_exp_f32_e32 v18, v18
	v_rcp_f32_e32 v20, v19
	v_rcp_f32_e32 v19, v10
	v_mul_f32_e32 v10, 0xbfb8aa3b, v13
	v_exp_f32_e32 v10, v10
	v_add_f32_e32 v18, 1.0, v18
	v_rcp_f32_e32 v18, v18
	v_pk_mul_f32 v[8:9], v[22:23], v[8:9]
	v_add_f32_e32 v10, 1.0, v10
	v_rcp_f32_e32 v21, v10
	v_pk_mul_f32 v[6:7], v[6:7], v[16:17]
	v_pk_mul_f32 v[4:5], v[4:5], v[14:15]
	v_pk_mul_f32 v[6:7], v[18:19], v[6:7]
	v_pk_mul_f32 v[4:5], v[4:5], v[12:13]
	v_bfe_u32 v12, v9, 16, 1
	v_bfe_u32 v13, v8, 16, 1
	v_pk_mul_f32 v[4:5], v[20:21], v[4:5]
	v_add3_u32 v8, v8, v13, s81
	v_add3_u32 v9, v9, v12, s81
	v_bfe_u32 v12, v6, 16, 1
	v_bfe_u32 v13, v7, 16, 1
	v_bfe_u32 v10, v5, 16, 1
	v_bfe_u32 v11, v4, 16, 1
	v_add3_u32 v7, v7, v13, s81
	v_add3_u32 v6, v6, v12, s81
	v_add3_u32 v4, v4, v11, s81
	v_add3_u32 v5, v5, v10, s81
	v_lshrrev_b32_e32 v6, 16, v6
	v_lshrrev_b32_e32 v7, 16, v7
	v_and_or_b32 v5, v5, s82, v7
	v_and_or_b32 v4, v4, s82, v6
	v_mov_b32_e32 v7, s35
	v_or_b32_e32 v6, s34, v124
	v_lshlrev_b64 v[6:7], 11, v[6:7]
	v_lshl_add_u64 v[6:7], s[42:43], 0, v[6:7]
	v_bfe_u32 v10, v2, 16, 1
	v_bfe_u32 v11, v3, 16, 1
	v_lshl_add_u64 v[6:7], v[6:7], 0, s[56:57]
	v_add3_u32 v3, v3, v11, s81
	v_add3_u32 v2, v2, v10, s81
	v_lshl_add_u64 v[6:7], v[6:7], 0, v[134:135]
	v_lshrrev_b32_e32 v2, 16, v2
	v_lshrrev_b32_e32 v3, 16, v3
	v_add_co_u32_e32 v6, vcc, s83, v6
	v_and_or_b32 v3, v9, s82, v3
	v_and_or_b32 v2, v8, s82, v2
	v_addc_co_u32_e32 v7, vcc, 0, v7, vcc
	global_store_dwordx4 v[6:7], v[2:5], off offset:1024
	s_waitcnt lgkmcnt(0)
	s_barrier
	s_cbranch_scc0 .LBB0_909

.LBB0_1123:
	s_cmp_lt_i32 s88, 10
	s_cselect_b64 s[0:1], -1, 0
	s_and_b64 s[6:7], s[0:1], s[2:3]
	s_andn2_b64 vcc, exec, s[6:7]
	s_cbranch_vccnz .LBB0_1140
	s_lshl_b32 s2, s66, 3
	s_lshl_b32 s0, s66, 7
	s_and_b32 s0, s0, 0xfffff000
	s_and_b32 s1, s2, 0xf8
	s_add_i32 s3, s0, 0x1000
	s_or_b32 s4, s0, s1
	s_cmpk_eq_i32 s68, 0x100
	s_cselect_b64 s[8:9], -1, 0
	s_and_b64 s[0:1], s[8:9], exec
	s_cselect_b32 s2, s4, s2
	s_cselect_b32 s12, s3, 0x8000
	s_add_i32 s13, s2, s96
	s_cmp_ge_i32 s13, s12
	s_cbranch_scc1 .LBB0_1129
	v_readlane_b32 s36, v253, 20
	v_lshlrev_b32_e32 v1, 4, v177
	v_readlane_b32 s50, v253, 34
	v_readlane_b32 s51, v253, 35
	s_nop 4
	global_load_dwordx4 v[2:5], v1, s[50:51]
	global_load_dwordx4 v[6:9], v1, s[50:51] offset:1024
	global_load_dwordx4 v[10:13], v1, s[50:51] offset:2048
	global_load_dwordx4 v[14:17], v1, s[50:51] offset:3072
	v_mbcnt_lo_u32_b32 v1, -1, 0
	v_mbcnt_hi_u32_b32 v18, -1, v1
	v_and_b32_e32 v1, 64, v18
	v_add_u32_e32 v19, 64, v1
	v_xor_b32_e32 v1, 1, v18
	v_cmp_lt_i32_e32 vcc, v1, v19
	v_xor_b32_e32 v20, 2, v18
	v_readlane_b32 s4, v252, 2
	v_cndmask_b32_e32 v1, v18, v1, vcc
	v_cmp_lt_i32_e32 vcc, v20, v19
	s_lshl_b32 s3, s68, 3
	v_readlane_b32 s5, v252, 3
	v_cndmask_b32_e32 v20, v18, v20, vcc
	v_lshlrev_b32_e32 v26, 2, v20
	v_xor_b32_e32 v20, 4, v18
	v_cmp_lt_i32_e32 vcc, v20, v19
	s_mov_b64 s[14:15], s[50:51]
	s_and_b64 s[0:1], s[8:9], exec
	v_cndmask_b32_e32 v20, v18, v20, vcc
	v_lshlrev_b32_e32 v27, 2, v20
	v_xor_b32_e32 v20, 8, v18
	v_cmp_lt_i32_e32 vcc, v20, v19
	s_cselect_b32 s14, 0x100, s3
	s_lshl_b32 s3, s66, 8
	v_cndmask_b32_e32 v20, v18, v20, vcc
	v_lshlrev_b32_e32 v28, 2, v20
	v_xor_b32_e32 v20, 16, v18
	v_cmp_lt_i32_e32 vcc, v20, v19
	s_and_b32 s3, s3, 0xffffe000
	s_add_i32 s3, s96, s3
	v_cndmask_b32_e32 v20, v18, v20, vcc
	v_lshlrev_b32_e32 v29, 2, v20
	v_xor_b32_e32 v20, 32, v18
	v_cmp_lt_i32_e32 vcc, v20, v19
	v_mov_b32_e32 v19, 0
	v_lshlrev_b32_e32 v1, 2, v1
	v_cndmask_b32_e32 v18, v18, v20, vcc
	v_lshlrev_b32_e32 v30, 2, v18
	v_lshlrev_b32_e32 v18, 3, v177
	v_lshl_add_u64 v[20:21], s[4:5], 0, v[18:19]
	v_readlane_b32 s4, v253, 52
	v_readlane_b32 s5, v253, 53
	v_cmp_eq_u32_e64 s[0:1], 0, v177
	s_mov_b32 s16, 0xffff0000
	s_waitcnt vmcnt(0)
	v_lshl_add_u64 v[22:23], s[4:5], 0, v[18:19]
	s_and_b32 s4, s66, 31
	s_lshl_b32 s4, s4, 4
	s_add_i32 s3, s3, s4
	s_sub_i32 s2, s3, s2
	s_add_i32 s15, s2, 0xf00
	v_mov_b32_e32 v31, 0x358637bd
	s_mov_b32 s17, 0xf800000
	v_mov_b32_e32 v32, 0x260
	s_movk_i32 s18, 0x7fff
	v_readlane_b32 s37, v253, 21
	v_readlane_b32 s38, v253, 22
	v_readlane_b32 s39, v253, 23
	v_readlane_b32 s40, v253, 24
	v_readlane_b32 s41, v253, 25
	v_readlane_b32 s42, v253, 26
	v_readlane_b32 s43, v253, 27
	v_readlane_b32 s44, v253, 28
	v_readlane_b32 s45, v253, 29
	v_readlane_b32 s46, v253, 30
	v_readlane_b32 s47, v253, 31
	v_readlane_b32 s48, v253, 32
	v_readlane_b32 s49, v253, 33
	s_and_b64 s[4:5], s[8:9], exec
	s_cselect_b32 s2, s15, s13
	s_ashr_i32 s3, s2, 31
	s_lshl_b64 s[4:5], s[2:3], 11
	v_lshl_add_u64 v[98:99], v[20:21], 0, s[4:5]
	v_lshl_add_u64 v[100:101], v[22:23], 0, s[4:5]
	s_lshl_b64 s[2:3], s[2:3], 2
	s_add_u32 s2, s75, s2
	s_addc_u32 s3, s69, s3
	global_load_dwordx2 v[80:81], v[98:99], off
	global_load_dwordx2 v[82:83], v[98:99], off offset:512
	global_load_dwordx2 v[84:85], v[98:99], off offset:1024
	global_load_dwordx2 v[86:87], v[98:99], off offset:1536
	global_load_dwordx2 v[88:89], v[100:101], off
	global_load_dwordx2 v[90:91], v[100:101], off offset:512
	global_load_dwordx2 v[92:93], v[100:101], off offset:1024
	global_load_dwordx2 v[94:95], v[100:101], off offset:1536
	global_load_dword v96, v19, s[2:3]
	s_waitcnt vmcnt(0)
	s_mov_b32 s3, s14
	s_add_i32 s2, s13, s3
	s_cmp_lt_i32 s2, s12
	s_cbranch_scc0 .Lrp2_pre1
	s_sub_i32 s3, s15, s3
	s_and_b64 s[4:5], s[8:9], exec
	s_cselect_b32 s2, s3, s2
	s_ashr_i32 s3, s2, 31
	s_lshl_b64 s[4:5], s[2:3], 11
	v_lshl_add_u64 v[98:99], v[20:21], 0, s[4:5]
	v_lshl_add_u64 v[100:101], v[22:23], 0, s[4:5]
	s_lshl_b64 s[2:3], s[2:3], 2
	s_add_u32 s2, s75, s2
	s_addc_u32 s3, s69, s3
	global_load_dwordx2 v[102:103], v[98:99], off
	global_load_dwordx2 v[104:105], v[98:99], off offset:512
	global_load_dwordx2 v[106:107], v[98:99], off offset:1024
	global_load_dwordx2 v[108:109], v[98:99], off offset:1536
	global_load_dwordx2 v[110:111], v[100:101], off
	global_load_dwordx2 v[112:113], v[100:101], off offset:512
	global_load_dwordx2 v[114:115], v[100:101], off offset:1024
	global_load_dwordx2 v[116:117], v[100:101], off offset:1536
	global_load_dword v118, v19, s[2:3]

.Lrp2_compute:
	s_and_b64 s[2:3], s[8:9], exec
	s_cselect_b32 s2, s15, s13
	s_ashr_i32 s3, s2, 31
	s_lshl_b64 s[4:5], s[2:3], 11
	s_lshl_b64 s[2:3], s[2:3], 2
	s_add_u32 s10, s75, s2
	v_lshl_add_u64 v[24:25], v[22:23], 0, s[4:5]
	s_addc_u32 s11, s69, s3
	v_and_b32_e32 v51, 0xffff0000, v34
	v_alignbit_b32 v33, v35, v34, 16
	v_and_b32_e32 v35, 0xffff0000, v35
	v_lshlrev_b32_e32 v52, 16, v36
	v_and_b32_e32 v53, 0xffff0000, v36
	v_alignbit_b32 v36, v37, v36, 16
	v_and_b32_e32 v37, 0xffff0000, v37
	v_lshlrev_b32_e32 v50, 16, v34
	v_lshlrev_b32_e32 v54, 16, v38
	v_and_b32_e32 v55, 0xffff0000, v38
	v_alignbit_b32 v38, v39, v38, 16
	v_and_b32_e32 v39, 0xffff0000, v39
	v_and_b32_e32 v34, 0xffff0000, v33
	v_and_b32_e32 v36, 0xffff0000, v36
	v_mul_f32_e32 v33, v51, v51
	v_mul_f32_e32 v58, v35, v35
	v_mul_f32_e32 v59, v53, v53
	v_mul_f32_e32 v60, v37, v37
	v_lshlrev_b32_e32 v56, 16, v40
	v_and_b32_e32 v57, 0xffff0000, v40
	v_alignbit_b32 v40, v41, v40, 16
	v_and_b32_e32 v41, 0xffff0000, v41
	v_and_b32_e32 v38, 0xffff0000, v38
	v_mul_f32_e32 v61, v55, v55
	v_mul_f32_e32 v62, v39, v39
	v_fmac_f32_e32 v33, v50, v50
	v_fmac_f32_e32 v58, v34, v34
	v_fmac_f32_e32 v59, v52, v52
	v_fmac_f32_e32 v60, v36, v36
	v_and_b32_e32 v40, 0xffff0000, v40
	v_mul_f32_e32 v63, v57, v57
	v_mul_f32_e32 v64, v41, v41
	v_fmac_f32_e32 v61, v54, v54
	v_fmac_f32_e32 v62, v38, v38
	v_add_f32_e32 v33, v33, v58
	v_add_f32_e32 v58, v59, v60
	v_fmac_f32_e32 v63, v56, v56
	v_fmac_f32_e32 v64, v40, v40
	v_add_f32_e32 v59, v61, v62
	v_add_f32_e32 v33, v33, v58
	v_add_f32_e32 v60, v63, v64
	v_add_f32_e32 v33, v33, v59
	v_add_f32_e32 v33, v33, v60
	ds_bpermute_b32 v60, v1, v33
	v_lshlrev_b32_e32 v58, 16, v42
	v_and_b32_e32 v59, 0xffff0000, v42
	v_alignbit_b32 v42, v43, v42, 16
	v_and_b32_e32 v61, 0xffff0000, v44
	s_waitcnt lgkmcnt(0)
	v_add_f32_e32 v33, v33, v60
	ds_bpermute_b32 v62, v26, v33
	v_lshlrev_b32_e32 v60, 16, v44
	v_alignbit_b32 v44, v45, v44, 16
	v_pk_mul_f32 v[50:51], v[2:3], v[50:51]
	v_pk_mul_f32 v[52:53], v[6:7], v[52:53]
	s_waitcnt lgkmcnt(0)
	v_add_f32_e32 v33, v33, v62
	ds_bpermute_b32 v64, v27, v33
	v_pk_mul_f32 v[34:35], v[4:5], v[34:35]
	v_pk_mul_f32 v[36:37], v[8:9], v[36:37]
	v_and_b32_e32 v43, 0xffff0000, v43
	v_and_b32_e32 v45, 0xffff0000, v45
	s_waitcnt lgkmcnt(0)
	v_add_f32_e32 v33, v33, v64
	ds_bpermute_b32 v66, v28, v33
	v_and_b32_e32 v42, 0xffff0000, v42
	v_and_b32_e32 v44, 0xffff0000, v44
	v_lshlrev_b32_e32 v62, 16, v46
	v_and_b32_e32 v63, 0xffff0000, v46
	s_waitcnt lgkmcnt(0)
	v_add_f32_e32 v33, v33, v66
	ds_bpermute_b32 v66, v29, v33
	v_alignbit_b32 v46, v47, v46, 16
	v_pk_mul_f32 v[54:55], v[10:11], v[54:55]
	v_pk_mul_f32 v[38:39], v[12:13], v[38:39]
	v_and_b32_e32 v47, 0xffff0000, v47
	s_waitcnt lgkmcnt(0)
	v_add_f32_e32 v33, v33, v66
	ds_bpermute_b32 v66, v30, v33
	v_lshlrev_b32_e32 v64, 16, v48
	v_and_b32_e32 v65, 0xffff0000, v48
	v_alignbit_b32 v48, v49, v48, 16
	v_and_b32_e32 v46, 0xffff0000, v46
	s_waitcnt lgkmcnt(0)
	v_add_f32_e32 v33, v33, v66
	v_fmamk_f32 v33, v33, 0x3a800000, v31
	v_mul_f32_e32 v66, 0x4f800000, v33
	v_cmp_gt_f32_e32 vcc, s17, v33
	v_pk_mul_f32 v[56:57], v[14:15], v[56:57]
	v_pk_mul_f32 v[40:41], v[16:17], v[40:41]
	v_cndmask_b32_e32 v33, v33, v66, vcc
	v_sqrt_f32_e32 v66, v33
	v_and_b32_e32 v49, 0xffff0000, v49
	v_and_b32_e32 v48, 0xffff0000, v48
	v_add_u32_e32 v67, -1, v66
	v_add_u32_e32 v68, 1, v66
	v_fma_f32 v69, -v67, v66, v33
	v_fma_f32 v70, -v68, v66, v33
	v_cmp_ge_f32_e64 s[4:5], 0, v69
	s_nop 1
	v_cndmask_b32_e64 v66, v66, v67, s[4:5]
	v_cmp_lt_f32_e64 s[4:5], 0, v70
	s_nop 1
	v_cndmask_b32_e64 v66, v66, v68, s[4:5]
	v_mul_f32_e32 v67, 0x37800000, v66
	v_cndmask_b32_e32 v66, v66, v67, vcc
	v_cmp_class_f32_e32 vcc, v33, v32
	s_nop 1
	v_cndmask_b32_e32 v33, v66, v33, vcc
	v_div_scale_f32 v66, s[2:3], v33, v33, 1.0
	v_rcp_f32_e32 v67, v66
	v_div_scale_f32 v68, vcc, 1.0, v33, 1.0
	v_fma_f32 v69, -v66, v67, 1.0
	v_fmac_f32_e32 v67, v69, v67
	v_mul_f32_e32 v69, v68, v67
	v_fma_f32 v70, -v66, v69, v68
	v_fmac_f32_e32 v69, v70, v67
	v_fma_f32 v66, -v66, v69, v68
	v_div_fmas_f32 v66, v66, v67, v69
	v_div_fixup_f32 v66, v66, v33, 1.0
	v_pk_mul_f32 v[50:51], v[50:51], v[66:67] op_sel_hi:[1,0]
	v_pk_mul_f32 v[34:35], v[34:35], v[66:67] op_sel_hi:[1,0]
	v_pk_mul_f32 v[52:53], v[52:53], v[66:67] op_sel_hi:[1,0]
	v_pk_mul_f32 v[36:37], v[36:37], v[66:67] op_sel_hi:[1,0]
	v_pk_fma_f32 v[34:35], v[18:19], v[42:43], v[34:35] op_sel_hi:[0,1,1]
	v_pk_fma_f32 v[42:43], v[18:19], v[58:59], v[50:51] op_sel_hi:[0,1,1]
	v_pk_fma_f32 v[36:37], v[18:19], v[44:45], v[36:37] op_sel_hi:[0,1,1]
	v_pk_fma_f32 v[44:45], v[18:19], v[60:61], v[52:53] op_sel_hi:[0,1,1]
	v_pk_mul_f32 v[54:55], v[54:55], v[66:67] op_sel_hi:[1,0]
	v_pk_mul_f32 v[38:39], v[38:39], v[66:67] op_sel_hi:[1,0]
	v_mul_f32_e32 v33, v43, v43
	v_mul_f32_e32 v50, v35, v35
	v_mul_f32_e32 v51, v45, v45
	v_mul_f32_e32 v52, v37, v37
	v_pk_mul_f32 v[56:57], v[56:57], v[66:67] op_sel_hi:[1,0]
	v_pk_fma_f32 v[38:39], v[18:19], v[46:47], v[38:39] op_sel_hi:[0,1,1]
	v_pk_fma_f32 v[46:47], v[18:19], v[62:63], v[54:55] op_sel_hi:[0,1,1]
	v_fmac_f32_e32 v33, v42, v42
	v_fmac_f32_e32 v50, v34, v34
	v_fmac_f32_e32 v51, v44, v44
	v_fmac_f32_e32 v52, v36, v36
	v_pk_mul_f32 v[40:41], v[40:41], v[66:67] op_sel_hi:[1,0]
	v_mul_f32_e32 v53, v47, v47
	v_mul_f32_e32 v54, v39, v39
	v_add_f32_e32 v33, v33, v50
	v_add_f32_e32 v50, v51, v52
	v_pk_fma_f32 v[40:41], v[18:19], v[48:49], v[40:41] op_sel_hi:[0,1,1]
	v_pk_fma_f32 v[48:49], v[18:19], v[64:65], v[56:57] op_sel_hi:[0,1,1]
	v_fmac_f32_e32 v53, v46, v46
	v_fmac_f32_e32 v54, v38, v38
	v_add_f32_e32 v33, v33, v50
	v_mul_f32_e32 v18, v49, v49
	v_mul_f32_e32 v50, v41, v41
	v_add_f32_e32 v51, v53, v54
	v_fmac_f32_e32 v18, v48, v48
	v_fmac_f32_e32 v50, v40, v40
	v_add_f32_e32 v33, v51, v33
	v_add_f32_e32 v18, v18, v50
	v_add_f32_e32 v18, v18, v33
	ds_bpermute_b32 v33, v1, v18
	s_waitcnt lgkmcnt(0)
	v_add_f32_e32 v18, v18, v33
	ds_bpermute_b32 v33, v26, v18
	s_waitcnt lgkmcnt(0)
	v_add_f32_e32 v18, v18, v33
	ds_bpermute_b32 v33, v27, v18
	s_waitcnt lgkmcnt(0)
	v_add_f32_e32 v18, v18, v33
	ds_bpermute_b32 v33, v28, v18
	s_waitcnt lgkmcnt(0)
	v_add_f32_e32 v18, v18, v33
	ds_bpermute_b32 v33, v29, v18
	s_waitcnt lgkmcnt(0)
	v_add_f32_e32 v18, v18, v33
	ds_bpermute_b32 v33, v30, v18
	s_waitcnt lgkmcnt(0)
	v_add_f32_e32 v18, v18, v33
	v_fmamk_f32 v18, v18, 0x3a800000, v31
	v_mul_f32_e32 v33, 0x4f800000, v18
	v_cmp_gt_f32_e32 vcc, s17, v18
	s_nop 1
	v_cndmask_b32_e32 v18, v18, v33, vcc
	v_sqrt_f32_e32 v33, v18
	s_nop 0
	v_add_u32_e32 v50, -1, v33
	v_add_u32_e32 v51, 1, v33
	v_fma_f32 v52, -v50, v33, v18
	v_fma_f32 v53, -v51, v33, v18
	v_cmp_ge_f32_e64 s[4:5], 0, v52
	s_nop 1
	v_cndmask_b32_e64 v33, v33, v50, s[4:5]
	v_cmp_lt_f32_e64 s[4:5], 0, v53
	s_nop 1
	v_cndmask_b32_e64 v33, v33, v51, s[4:5]
	v_mul_f32_e32 v50, 0x37800000, v33
	v_cndmask_b32_e32 v33, v33, v50, vcc
	v_cmp_class_f32_e32 vcc, v18, v32
	s_nop 1
	v_cndmask_b32_e32 v18, v33, v18, vcc
	v_div_scale_f32 v33, s[2:3], v18, v18, 1.0
	v_rcp_f32_e32 v50, v33
	v_div_scale_f32 v51, vcc, 1.0, v18, 1.0
	v_fma_f32 v52, -v33, v50, 1.0
	v_fmac_f32_e32 v50, v52, v50
	v_mul_f32_e32 v52, v51, v50
	v_fma_f32 v53, -v33, v52, v51
	v_fmac_f32_e32 v52, v53, v50
	v_fma_f32 v33, -v33, v52, v51
	v_div_fmas_f32 v33, v33, v50, v52
	v_div_fixup_f32 v33, v33, v18, 1.0
	v_mul_f32_e32 v42, v42, v33
	v_mul_f32_e32 v34, v34, v33
	v_mul_f32_e32 v43, v43, v33
	v_mul_f32_e32 v35, v35, v33
	v_bfe_u32 v50, v42, 16, 1
	v_bfe_u32 v52, v34, 16, 1
	v_bfe_u32 v51, v43, 16, 1
	v_bfe_u32 v53, v35, 16, 1
	v_add3_u32 v42, v42, v50, s18
	v_add3_u32 v34, v34, v52, s18
	v_add3_u32 v43, v43, v51, s18
	v_add3_u32 v35, v35, v53, s18
	v_lshrrev_b32_e32 v42, 16, v42
	v_lshrrev_b32_e32 v50, 16, v34
	v_mul_f32_e32 v44, v44, v33
	v_and_or_b32 v34, v43, s16, v42
	v_and_or_b32 v35, v35, s16, v50
	global_store_dwordx2 v[24:25], v[34:35], off
	v_mul_f32_e32 v34, v45, v33
	v_bfe_u32 v35, v44, 16, 1
	v_add3_u32 v35, v44, v35, s18
	v_bfe_u32 v42, v34, 16, 1
	v_lshrrev_b32_e32 v35, 16, v35
	v_add3_u32 v34, v34, v42, s18
	v_and_or_b32 v34, v34, s16, v35
	v_mul_f32_e32 v35, v36, v33
	v_mul_f32_e32 v36, v37, v33
	v_bfe_u32 v37, v35, 16, 1
	v_add3_u32 v35, v35, v37, s18
	v_bfe_u32 v37, v36, 16, 1
	v_lshrrev_b32_e32 v35, 16, v35
	v_add3_u32 v36, v36, v37, s18
	v_and_or_b32 v35, v36, s16, v35
	global_store_dwordx2 v[24:25], v[34:35], off offset:512
	v_mul_f32_e32 v34, v46, v33
	v_mul_f32_e32 v35, v47, v33
	v_bfe_u32 v36, v34, 16, 1
	v_add3_u32 v34, v34, v36, s18
	v_bfe_u32 v36, v35, 16, 1
	v_lshrrev_b32_e32 v34, 16, v34
	v_add3_u32 v35, v35, v36, s18
	v_and_or_b32 v34, v35, s16, v34
	v_mul_f32_e32 v35, v38, v33
	v_mul_f32_e32 v36, v39, v33
	v_bfe_u32 v37, v35, 16, 1
	v_add3_u32 v35, v35, v37, s18
	v_bfe_u32 v37, v36, 16, 1
	v_lshrrev_b32_e32 v35, 16, v35
	v_add3_u32 v36, v36, v37, s18
	v_and_or_b32 v35, v36, s16, v35
	global_store_dwordx2 v[24:25], v[34:35], off offset:1024
	v_mul_f32_e32 v34, v48, v33
	v_mul_f32_e32 v35, v49, v33
	v_bfe_u32 v36, v34, 16, 1
	v_add3_u32 v34, v34, v36, s18
	v_bfe_u32 v36, v35, 16, 1
	v_lshrrev_b32_e32 v34, 16, v34
	v_add3_u32 v35, v35, v36, s18
	v_and_or_b32 v34, v35, s16, v34
	v_mul_f32_e32 v35, v40, v33
	v_mul_f32_e32 v33, v41, v33
	v_bfe_u32 v36, v35, 16, 1
	v_add3_u32 v35, v35, v36, s18
	v_bfe_u32 v36, v33, 16, 1
	v_lshrrev_b32_e32 v35, 16, v35
	v_add3_u32 v33, v33, v36, s18
	v_and_or_b32 v35, v33, s16, v35
	global_store_dwordx2 v[24:25], v[34:35], off offset:1536
	s_and_saveexec_b64 s[2:3], s[0:1]
	s_cbranch_execz .LBB0_1126
	global_store_dword v19, v18, s[10:11]
	s_branch .LBB0_1126

.LBB0_1264:
	s_cmp_lt_i32 s88, 13
	s_cselect_b64 s[0:1], -1, 0
	s_and_b64 s[6:7], s[0:1], s[2:3]
	s_andn2_b64 vcc, exec, s[6:7]
	s_cbranch_vccnz .LBB0_1274
	s_lshl_b32 s12, s66, 3
	s_lshl_b32 s0, s66, 7
	s_and_b32 s0, s0, 0xfffff000
	s_and_b32 s1, s12, 0xf8
	s_add_i32 s2, s0, 0x1000
	s_or_b32 s3, s0, s1
	s_cmpk_eq_i32 s68, 0x100
	s_cselect_b64 s[8:9], -1, 0
	s_and_b64 s[0:1], s[8:9], exec
	s_cselect_b32 s13, s2, 0x8000
	s_cselect_b32 s2, s3, s12
	s_add_i32 s14, s2, s96
	s_cmp_ge_i32 s14, s13
	v_mov_b32_e32 v19, 0
	s_cbranch_scc1 .LBB0_1270
	v_lshlrev_b32_e32 v1, 4, v177
	global_load_dwordx4 v[2:5], v1, s[26:27]
	global_load_dwordx4 v[6:9], v1, s[26:27] offset:1024
	global_load_dwordx4 v[10:13], v1, s[26:27] offset:2048
	global_load_dwordx4 v[14:17], v1, s[26:27] offset:3072
	v_mbcnt_lo_u32_b32 v1, -1, 0
	v_mbcnt_hi_u32_b32 v18, -1, v1
	v_and_b32_e32 v1, 64, v18
	v_add_u32_e32 v20, 64, v1
	v_xor_b32_e32 v1, 1, v18
	v_cmp_lt_i32_e32 vcc, v1, v20
	v_xor_b32_e32 v21, 2, v18
	v_readlane_b32 s4, v252, 2
	v_cndmask_b32_e32 v1, v18, v1, vcc
	v_cmp_lt_i32_e32 vcc, v21, v20
	s_lshl_b32 s3, s68, 3
	v_readlane_b32 s5, v252, 3
	v_cndmask_b32_e32 v21, v18, v21, vcc
	v_lshlrev_b32_e32 v26, 2, v21
	v_xor_b32_e32 v21, 4, v18
	v_cmp_lt_i32_e32 vcc, v21, v20
	s_and_b64 s[0:1], s[8:9], exec
	s_cselect_b32 s15, 0x100, s3
	v_cndmask_b32_e32 v21, v18, v21, vcc
	v_lshlrev_b32_e32 v27, 2, v21
	v_xor_b32_e32 v21, 8, v18
	v_cmp_lt_i32_e32 vcc, v21, v20
	s_lshl_b32 s3, s66, 8
	s_and_b32 s3, s3, 0xffffe000
	v_cndmask_b32_e32 v21, v18, v21, vcc
	v_lshlrev_b32_e32 v28, 2, v21
	v_xor_b32_e32 v21, 16, v18
	v_cmp_lt_i32_e32 vcc, v21, v20
	s_add_i32 s3, s96, s3
	v_lshlrev_b32_e32 v1, 2, v1
	v_cndmask_b32_e32 v21, v18, v21, vcc
	v_lshlrev_b32_e32 v29, 2, v21
	v_xor_b32_e32 v21, 32, v18
	v_cmp_lt_i32_e32 vcc, v21, v20
	v_cmp_eq_u32_e64 s[0:1], 0, v177
	s_mov_b32 s17, 0xffff0000
	v_cndmask_b32_e32 v18, v18, v21, vcc
	v_lshlrev_b32_e32 v30, 2, v18
	v_lshlrev_b32_e32 v18, 3, v177
	v_lshl_add_u64 v[20:21], s[4:5], 0, v[18:19]
	v_readlane_b32 s4, v253, 52
	v_readlane_b32 s5, v253, 53
	v_mov_b32_e32 v31, 0x358637bd
	s_mov_b32 s18, 0xf800000
	s_waitcnt vmcnt(0)
	v_lshl_add_u64 v[22:23], s[4:5], 0, v[18:19]
	s_and_b32 s4, s66, 31
	s_lshl_b32 s4, s4, 4
	s_add_i32 s3, s3, s4
	s_sub_i32 s2, s3, s2
	s_add_i32 s16, s2, 0xf00
	v_mov_b32_e32 v32, 0x260
	s_movk_i32 s19, 0x7fff
	s_and_b64 s[4:5], s[8:9], exec
	s_cselect_b32 s2, s16, s14
	s_ashr_i32 s3, s2, 31
	s_lshl_b64 s[4:5], s[2:3], 11
	v_lshl_add_u64 v[98:99], v[20:21], 0, s[4:5]
	v_lshl_add_u64 v[100:101], v[22:23], 0, s[4:5]
	s_lshl_b64 s[2:3], s[2:3], 2
	s_add_u32 s2, s75, s2
	s_addc_u32 s3, s69, s3
	global_load_dwordx2 v[80:81], v[98:99], off
	global_load_dwordx2 v[82:83], v[98:99], off offset:512
	global_load_dwordx2 v[84:85], v[98:99], off offset:1024
	global_load_dwordx2 v[86:87], v[98:99], off offset:1536
	global_load_dwordx2 v[88:89], v[100:101], off
	global_load_dwordx2 v[90:91], v[100:101], off offset:512
	global_load_dwordx2 v[92:93], v[100:101], off offset:1024
	global_load_dwordx2 v[94:95], v[100:101], off offset:1536
	global_load_dword v96, v19, s[2:3]
	s_waitcnt vmcnt(0)
	s_mov_b32 s3, s15
	s_add_i32 s2, s14, s3
	s_cmp_lt_i32 s2, s13
	s_cbranch_scc0 .Lrp3_pre1
	s_sub_i32 s3, s16, s3
	s_and_b64 s[4:5], s[8:9], exec
	s_cselect_b32 s2, s3, s2
	s_ashr_i32 s3, s2, 31
	s_lshl_b64 s[4:5], s[2:3], 11
	v_lshl_add_u64 v[98:99], v[20:21], 0, s[4:5]
	v_lshl_add_u64 v[100:101], v[22:23], 0, s[4:5]
	s_lshl_b64 s[2:3], s[2:3], 2
	s_add_u32 s2, s75, s2
	s_addc_u32 s3, s69, s3
	global_load_dwordx2 v[102:103], v[98:99], off
	global_load_dwordx2 v[104:105], v[98:99], off offset:512
	global_load_dwordx2 v[106:107], v[98:99], off offset:1024
	global_load_dwordx2 v[108:109], v[98:99], off offset:1536
	global_load_dwordx2 v[110:111], v[100:101], off
	global_load_dwordx2 v[112:113], v[100:101], off offset:512
	global_load_dwordx2 v[114:115], v[100:101], off offset:1024
	global_load_dwordx2 v[116:117], v[100:101], off offset:1536
	global_load_dword v118, v19, s[2:3]

.LBB0_1268:
	s_add_i32 s2, s14, s15
	s_cmp_lt_i32 s2, s13
	s_cbranch_scc0 .Lrp3_w5
	s_waitcnt vmcnt(14)
	s_branch .Lrp3_sel

.Lrp3_bodyC:
	v_mov_b32_e32 v34, v102
	v_mov_b32_e32 v35, v103
	v_mov_b32_e32 v36, v104
	v_mov_b32_e32 v37, v105
	v_mov_b32_e32 v38, v106
	v_mov_b32_e32 v39, v107
	v_mov_b32_e32 v40, v108
	v_mov_b32_e32 v41, v109
	v_mov_b32_e32 v42, v110
	v_mov_b32_e32 v43, v111
	v_mov_b32_e32 v44, v112
	v_mov_b32_e32 v45, v113
	v_mov_b32_e32 v46, v114
	v_mov_b32_e32 v47, v115
	v_mov_b32_e32 v48, v116
	v_mov_b32_e32 v49, v117
	v_mov_b32_e32 v18, v118
	s_mov_b32 s100, 0
	s_mul_i32 s3, s15, 2
	s_add_i32 s2, s14, s3
	s_cmp_lt_i32 s2, s13
	s_cbranch_scc0 .Lrp3_compute
	s_sub_i32 s3, s16, s3
	s_and_b64 s[4:5], s[8:9], exec
	s_cselect_b32 s2, s3, s2
	s_ashr_i32 s3, s2, 31
	s_lshl_b64 s[4:5], s[2:3], 11
	v_lshl_add_u64 v[98:99], v[20:21], 0, s[4:5]
	v_lshl_add_u64 v[100:101], v[22:23], 0, s[4:5]
	s_lshl_b64 s[2:3], s[2:3], 2
	s_add_u32 s2, s75, s2
	s_addc_u32 s3, s69, s3
	global_load_dwordx2 v[102:103], v[98:99], off
	global_load_dwordx2 v[104:105], v[98:99], off offset:512
	global_load_dwordx2 v[106:107], v[98:99], off offset:1024
	global_load_dwordx2 v[108:109], v[98:99], off offset:1536
	global_load_dwordx2 v[110:111], v[100:101], off
	global_load_dwordx2 v[112:113], v[100:101], off offset:512
	global_load_dwordx2 v[114:115], v[100:101], off offset:1024
	global_load_dwordx2 v[116:117], v[100:101], off offset:1536
	global_load_dword v118, v19, s[2:3]
	s_branch .Lrp3_compute
.Lrp3_bodyB:
	v_mov_b32_e32 v34, v80
	v_mov_b32_e32 v35, v81
	v_mov_b32_e32 v36, v82
	v_mov_b32_e32 v37, v83
	v_mov_b32_e32 v38, v84
	v_mov_b32_e32 v39, v85
	v_mov_b32_e32 v40, v86
	v_mov_b32_e32 v41, v87
	v_mov_b32_e32 v42, v88
	v_mov_b32_e32 v43, v89
	v_mov_b32_e32 v44, v90
	v_mov_b32_e32 v45, v91
	v_mov_b32_e32 v46, v92
	v_mov_b32_e32 v47, v93
	v_mov_b32_e32 v48, v94
	v_mov_b32_e32 v49, v95
	v_mov_b32_e32 v18, v96
	s_mov_b32 s100, 1
	s_mul_i32 s3, s15, 2
	s_add_i32 s2, s14, s3
	s_cmp_lt_i32 s2, s13
	s_cbranch_scc0 .Lrp3_compute
	s_sub_i32 s3, s16, s3
	s_and_b64 s[4:5], s[8:9], exec
	s_cselect_b32 s2, s3, s2
	s_ashr_i32 s3, s2, 31
	s_lshl_b64 s[4:5], s[2:3], 11
	v_lshl_add_u64 v[98:99], v[20:21], 0, s[4:5]
	v_lshl_add_u64 v[100:101], v[22:23], 0, s[4:5]
	s_lshl_b64 s[2:3], s[2:3], 2
	s_add_u32 s2, s75, s2
	s_addc_u32 s3, s69, s3
	global_load_dwordx2 v[80:81], v[98:99], off
	global_load_dwordx2 v[82:83], v[98:99], off offset:512
	global_load_dwordx2 v[84:85], v[98:99], off offset:1024
	global_load_dwordx2 v[86:87], v[98:99], off offset:1536
	global_load_dwordx2 v[88:89], v[100:101], off
	global_load_dwordx2 v[90:91], v[100:101], off offset:512
	global_load_dwordx2 v[92:93], v[100:101], off offset:1024
	global_load_dwordx2 v[94:95], v[100:101], off offset:1536
	global_load_dword v96, v19, s[2:3]
.Lrp3_compute:
	s_and_b64 s[2:3], s[8:9], exec
	s_cselect_b32 s2, s16, s14
	s_ashr_i32 s3, s2, 31
	s_lshl_b64 s[4:5], s[2:3], 11
	s_lshl_b64 s[2:3], s[2:3], 2
	s_add_u32 s10, s75, s2
	v_lshl_add_u64 v[24:25], v[22:23], 0, s[4:5]
	s_addc_u32 s11, s69, s3
	v_and_b32_e32 v51, 0xffff0000, v34
	v_alignbit_b32 v33, v35, v34, 16
	v_and_b32_e32 v35, 0xffff0000, v35
	v_lshlrev_b32_e32 v52, 16, v36
	v_and_b32_e32 v53, 0xffff0000, v36
	v_alignbit_b32 v36, v37, v36, 16
	v_and_b32_e32 v37, 0xffff0000, v37
	v_lshlrev_b32_e32 v50, 16, v34
	v_lshlrev_b32_e32 v54, 16, v38
	v_and_b32_e32 v55, 0xffff0000, v38
	v_alignbit_b32 v38, v39, v38, 16
	v_and_b32_e32 v39, 0xffff0000, v39
	v_and_b32_e32 v34, 0xffff0000, v33
	v_and_b32_e32 v36, 0xffff0000, v36
	v_mul_f32_e32 v33, v51, v51
	v_mul_f32_e32 v58, v35, v35
	v_mul_f32_e32 v59, v53, v53
	v_mul_f32_e32 v60, v37, v37
	v_lshlrev_b32_e32 v56, 16, v40
	v_and_b32_e32 v57, 0xffff0000, v40
	v_alignbit_b32 v40, v41, v40, 16
	v_and_b32_e32 v41, 0xffff0000, v41
	v_and_b32_e32 v38, 0xffff0000, v38
	v_mul_f32_e32 v61, v55, v55
	v_mul_f32_e32 v62, v39, v39
	v_fmac_f32_e32 v33, v50, v50
	v_fmac_f32_e32 v58, v34, v34
	v_fmac_f32_e32 v59, v52, v52
	v_fmac_f32_e32 v60, v36, v36
	v_and_b32_e32 v40, 0xffff0000, v40
	v_mul_f32_e32 v63, v57, v57
	v_mul_f32_e32 v64, v41, v41
	v_fmac_f32_e32 v61, v54, v54
	v_fmac_f32_e32 v62, v38, v38
	v_add_f32_e32 v33, v33, v58
	v_add_f32_e32 v58, v59, v60
	v_fmac_f32_e32 v63, v56, v56
	v_fmac_f32_e32 v64, v40, v40
	v_add_f32_e32 v59, v61, v62
	v_add_f32_e32 v33, v33, v58
	v_add_f32_e32 v60, v63, v64
	v_add_f32_e32 v33, v33, v59
	v_add_f32_e32 v33, v33, v60
	ds_bpermute_b32 v60, v1, v33
	v_lshlrev_b32_e32 v58, 16, v42
	v_and_b32_e32 v59, 0xffff0000, v42
	v_alignbit_b32 v42, v43, v42, 16
	v_and_b32_e32 v61, 0xffff0000, v44
	s_waitcnt lgkmcnt(0)
	v_add_f32_e32 v33, v33, v60
	ds_bpermute_b32 v62, v26, v33
	v_lshlrev_b32_e32 v60, 16, v44
	v_alignbit_b32 v44, v45, v44, 16
	v_pk_mul_f32 v[50:51], v[2:3], v[50:51]
	v_pk_mul_f32 v[52:53], v[6:7], v[52:53]
	s_waitcnt lgkmcnt(0)
	v_add_f32_e32 v33, v33, v62
	ds_bpermute_b32 v64, v27, v33
	v_pk_mul_f32 v[34:35], v[4:5], v[34:35]
	v_pk_mul_f32 v[36:37], v[8:9], v[36:37]
	v_and_b32_e32 v43, 0xffff0000, v43
	v_and_b32_e32 v45, 0xffff0000, v45
	s_waitcnt lgkmcnt(0)
	v_add_f32_e32 v33, v33, v64
	ds_bpermute_b32 v66, v28, v33
	v_and_b32_e32 v42, 0xffff0000, v42
	v_and_b32_e32 v44, 0xffff0000, v44
	v_lshlrev_b32_e32 v62, 16, v46
	v_and_b32_e32 v63, 0xffff0000, v46
	s_waitcnt lgkmcnt(0)
	v_add_f32_e32 v33, v33, v66
	ds_bpermute_b32 v66, v29, v33
	v_alignbit_b32 v46, v47, v46, 16
	v_pk_mul_f32 v[54:55], v[10:11], v[54:55]
	v_pk_mul_f32 v[38:39], v[12:13], v[38:39]
	v_and_b32_e32 v47, 0xffff0000, v47
	s_waitcnt lgkmcnt(0)
	v_add_f32_e32 v33, v33, v66
	ds_bpermute_b32 v66, v30, v33
	v_lshlrev_b32_e32 v64, 16, v48
	v_and_b32_e32 v65, 0xffff0000, v48
	v_alignbit_b32 v48, v49, v48, 16
	v_and_b32_e32 v46, 0xffff0000, v46
	s_waitcnt lgkmcnt(0)
	v_add_f32_e32 v33, v33, v66
	v_fmamk_f32 v33, v33, 0x3a800000, v31
	v_mul_f32_e32 v66, 0x4f800000, v33
	v_cmp_gt_f32_e32 vcc, s18, v33
	v_pk_mul_f32 v[56:57], v[14:15], v[56:57]
	v_pk_mul_f32 v[40:41], v[16:17], v[40:41]
	v_cndmask_b32_e32 v33, v33, v66, vcc
	v_sqrt_f32_e32 v66, v33
	v_and_b32_e32 v49, 0xffff0000, v49
	v_and_b32_e32 v48, 0xffff0000, v48
	v_add_u32_e32 v67, -1, v66
	v_add_u32_e32 v68, 1, v66
	v_fma_f32 v69, -v67, v66, v33
	v_fma_f32 v70, -v68, v66, v33
	v_cmp_ge_f32_e64 s[4:5], 0, v69
	s_nop 1
	v_cndmask_b32_e64 v66, v66, v67, s[4:5]
	v_cmp_lt_f32_e64 s[4:5], 0, v70
	s_nop 1
	v_cndmask_b32_e64 v66, v66, v68, s[4:5]
	v_mul_f32_e32 v67, 0x37800000, v66
	v_cndmask_b32_e32 v66, v66, v67, vcc
	v_cmp_class_f32_e32 vcc, v33, v32
	s_nop 1
	v_cndmask_b32_e32 v33, v66, v33, vcc
	v_div_scale_f32 v66, s[2:3], v33, v33, 1.0
	v_rcp_f32_e32 v67, v66
	v_div_scale_f32 v68, vcc, 1.0, v33, 1.0
	v_fma_f32 v69, -v66, v67, 1.0
	v_fmac_f32_e32 v67, v69, v67
	v_mul_f32_e32 v69, v68, v67
	v_fma_f32 v70, -v66, v69, v68
	v_fmac_f32_e32 v69, v70, v67
	v_fma_f32 v66, -v66, v69, v68
	v_div_fmas_f32 v66, v66, v67, v69
	v_div_fixup_f32 v66, v66, v33, 1.0
	v_pk_mul_f32 v[50:51], v[50:51], v[66:67] op_sel_hi:[1,0]
	v_pk_mul_f32 v[34:35], v[34:35], v[66:67] op_sel_hi:[1,0]
	v_pk_mul_f32 v[52:53], v[52:53], v[66:67] op_sel_hi:[1,0]
	v_pk_mul_f32 v[36:37], v[36:37], v[66:67] op_sel_hi:[1,0]
	v_pk_fma_f32 v[34:35], v[18:19], v[42:43], v[34:35] op_sel_hi:[0,1,1]
	v_pk_fma_f32 v[42:43], v[18:19], v[58:59], v[50:51] op_sel_hi:[0,1,1]
	v_pk_fma_f32 v[36:37], v[18:19], v[44:45], v[36:37] op_sel_hi:[0,1,1]
	v_pk_fma_f32 v[44:45], v[18:19], v[60:61], v[52:53] op_sel_hi:[0,1,1]
	v_pk_mul_f32 v[54:55], v[54:55], v[66:67] op_sel_hi:[1,0]
	v_pk_mul_f32 v[38:39], v[38:39], v[66:67] op_sel_hi:[1,0]
	v_mul_f32_e32 v33, v43, v43
	v_mul_f32_e32 v50, v35, v35
	v_mul_f32_e32 v51, v45, v45
	v_mul_f32_e32 v52, v37, v37
	v_pk_mul_f32 v[56:57], v[56:57], v[66:67] op_sel_hi:[1,0]
	v_pk_fma_f32 v[38:39], v[18:19], v[46:47], v[38:39] op_sel_hi:[0,1,1]
	v_pk_fma_f32 v[46:47], v[18:19], v[62:63], v[54:55] op_sel_hi:[0,1,1]
	v_fmac_f32_e32 v33, v42, v42
	v_fmac_f32_e32 v50, v34, v34
	v_fmac_f32_e32 v51, v44, v44
	v_fmac_f32_e32 v52, v36, v36
	v_pk_mul_f32 v[40:41], v[40:41], v[66:67] op_sel_hi:[1,0]
	v_mul_f32_e32 v53, v47, v47
	v_mul_f32_e32 v54, v39, v39
	v_add_f32_e32 v33, v33, v50
	v_add_f32_e32 v50, v51, v52
	v_pk_fma_f32 v[40:41], v[18:19], v[48:49], v[40:41] op_sel_hi:[0,1,1]
	v_pk_fma_f32 v[48:49], v[18:19], v[64:65], v[56:57] op_sel_hi:[0,1,1]
	v_fmac_f32_e32 v53, v46, v46
	v_fmac_f32_e32 v54, v38, v38
	v_add_f32_e32 v33, v33, v50
	v_mul_f32_e32 v18, v49, v49
	v_mul_f32_e32 v50, v41, v41
	v_add_f32_e32 v51, v53, v54
	v_fmac_f32_e32 v18, v48, v48
	v_fmac_f32_e32 v50, v40, v40
	v_add_f32_e32 v33, v51, v33
	v_add_f32_e32 v18, v18, v50
	v_add_f32_e32 v18, v18, v33
	ds_bpermute_b32 v33, v1, v18
	s_waitcnt lgkmcnt(0)
	v_add_f32_e32 v18, v18, v33
	ds_bpermute_b32 v33, v26, v18
	s_waitcnt lgkmcnt(0)
	v_add_f32_e32 v18, v18, v33
	ds_bpermute_b32 v33, v27, v18
	s_waitcnt lgkmcnt(0)
	v_add_f32_e32 v18, v18, v33
	ds_bpermute_b32 v33, v28, v18
	s_waitcnt lgkmcnt(0)
	v_add_f32_e32 v18, v18, v33
	ds_bpermute_b32 v33, v29, v18
	s_waitcnt lgkmcnt(0)
	v_add_f32_e32 v18, v18, v33
	ds_bpermute_b32 v33, v30, v18
	s_waitcnt lgkmcnt(0)
	v_add_f32_e32 v18, v18, v33
	v_fmamk_f32 v18, v18, 0x3a800000, v31
	v_mul_f32_e32 v33, 0x4f800000, v18
	v_cmp_gt_f32_e32 vcc, s18, v18
	s_nop 1
	v_cndmask_b32_e32 v18, v18, v33, vcc
	v_sqrt_f32_e32 v33, v18
	s_nop 0
	v_add_u32_e32 v50, -1, v33
	v_add_u32_e32 v51, 1, v33
	v_fma_f32 v52, -v50, v33, v18
	v_fma_f32 v53, -v51, v33, v18
	v_cmp_ge_f32_e64 s[4:5], 0, v52
	s_nop 1
	v_cndmask_b32_e64 v33, v33, v50, s[4:5]
	v_cmp_lt_f32_e64 s[4:5], 0, v53
	s_nop 1
	v_cndmask_b32_e64 v33, v33, v51, s[4:5]
	v_mul_f32_e32 v50, 0x37800000, v33
	v_cndmask_b32_e32 v33, v33, v50, vcc
	v_cmp_class_f32_e32 vcc, v18, v32
	s_nop 1
	v_cndmask_b32_e32 v18, v33, v18, vcc
	v_div_scale_f32 v33, s[2:3], v18, v18, 1.0
	v_rcp_f32_e32 v50, v33
	v_div_scale_f32 v51, vcc, 1.0, v18, 1.0
	v_fma_f32 v52, -v33, v50, 1.0
	v_fmac_f32_e32 v50, v52, v50
	v_mul_f32_e32 v52, v51, v50
	v_fma_f32 v53, -v33, v52, v51
	v_fmac_f32_e32 v52, v53, v50
	v_fma_f32 v33, -v33, v52, v51
	v_div_fmas_f32 v33, v33, v50, v52
	v_div_fixup_f32 v33, v33, v18, 1.0
	v_mul_f32_e32 v42, v42, v33
	v_mul_f32_e32 v34, v34, v33
	v_mul_f32_e32 v43, v43, v33
	v_mul_f32_e32 v35, v35, v33
	v_bfe_u32 v50, v42, 16, 1
	v_bfe_u32 v52, v34, 16, 1
	v_bfe_u32 v51, v43, 16, 1
	v_bfe_u32 v53, v35, 16, 1
	v_add3_u32 v42, v42, v50, s19
	v_add3_u32 v34, v34, v52, s19
	v_add3_u32 v43, v43, v51, s19
	v_add3_u32 v35, v35, v53, s19
	v_lshrrev_b32_e32 v42, 16, v42
	v_lshrrev_b32_e32 v50, 16, v34
	v_mul_f32_e32 v44, v44, v33
	v_and_or_b32 v34, v43, s17, v42
	v_and_or_b32 v35, v35, s17, v50
	global_store_dwordx2 v[24:25], v[34:35], off
	v_mul_f32_e32 v34, v45, v33
	v_bfe_u32 v35, v44, 16, 1
	v_add3_u32 v35, v44, v35, s19
	v_bfe_u32 v42, v34, 16, 1
	v_lshrrev_b32_e32 v35, 16, v35
	v_add3_u32 v34, v34, v42, s19
	v_and_or_b32 v34, v34, s17, v35
	v_mul_f32_e32 v35, v36, v33
	v_mul_f32_e32 v36, v37, v33
	v_bfe_u32 v37, v35, 16, 1
	v_add3_u32 v35, v35, v37, s19
	v_bfe_u32 v37, v36, 16, 1
	v_lshrrev_b32_e32 v35, 16, v35
	v_add3_u32 v36, v36, v37, s19
	v_and_or_b32 v35, v36, s17, v35
	global_store_dwordx2 v[24:25], v[34:35], off offset:512
	v_mul_f32_e32 v34, v46, v33
	v_mul_f32_e32 v35, v47, v33
	v_bfe_u32 v36, v34, 16, 1
	v_add3_u32 v34, v34, v36, s19
	v_bfe_u32 v36, v35, 16, 1
	v_lshrrev_b32_e32 v34, 16, v34
	v_add3_u32 v35, v35, v36, s19
	v_and_or_b32 v34, v35, s17, v34
	v_mul_f32_e32 v35, v38, v33
	v_mul_f32_e32 v36, v39, v33
	v_bfe_u32 v37, v35, 16, 1
	v_add3_u32 v35, v35, v37, s19
	v_bfe_u32 v37, v36, 16, 1
	v_lshrrev_b32_e32 v35, 16, v35
	v_add3_u32 v36, v36, v37, s19
	v_and_or_b32 v35, v36, s17, v35
	global_store_dwordx2 v[24:25], v[34:35], off offset:1024
	v_mul_f32_e32 v34, v48, v33
	v_mul_f32_e32 v35, v49, v33
	v_bfe_u32 v36, v34, 16, 1
	v_add3_u32 v34, v34, v36, s19
	v_bfe_u32 v36, v35, 16, 1
	v_lshrrev_b32_e32 v34, 16, v34
	v_add3_u32 v35, v35, v36, s19
	v_and_or_b32 v34, v35, s17, v34
	v_mul_f32_e32 v35, v40, v33
	v_mul_f32_e32 v33, v41, v33
	v_bfe_u32 v36, v35, 16, 1
	v_add3_u32 v35, v35, v36, s19
	v_bfe_u32 v36, v33, 16, 1
	v_lshrrev_b32_e32 v35, 16, v35
	v_add3_u32 v33, v33, v36, s19
	v_and_or_b32 v35, v33, s17, v35
	global_store_dwordx2 v[24:25], v[34:35], off offset:1536
	s_and_saveexec_b64 s[2:3], s[0:1]
	s_cbranch_execz .LBB0_1267
	global_store_dword v19, v18, s[10:11]
	s_branch .LBB0_1267

.LBB0_1478:
	s_lshl_b32 s2, s66, 3
	s_lshl_b32 s0, s66, 7
	s_and_b32 s0, s0, 0xfffff000
	s_and_b32 s1, s2, 0xf8
	s_add_i32 s3, s0, 0x1000
	s_or_b32 s8, s0, s1
	s_cmpk_eq_i32 s68, 0x100
	s_cselect_b64 s[6:7], -1, 0
	s_and_b64 s[0:1], s[6:7], exec
	s_cselect_b32 s2, s8, s2
	s_cselect_b32 s12, s3, 0x8000
	s_add_i32 s13, s2, s96
	s_cmp_lt_i32 s13, s12
	s_cbranch_scc0 .LBB0_1487
	v_mbcnt_lo_u32_b32 v32, -1, 0
	v_mbcnt_hi_u32_b32 v32, -1, v32
	v_and_b32_e32 v33, 64, v32
	v_add_u32_e32 v33, 64, v33
	v_xor_b32_e32 v34, 1, v32
	v_cmp_lt_i32_e32 vcc, v34, v33
	v_readlane_b32 s8, v252, 2
	s_lshl_b32 s3, s68, 3
	v_cndmask_b32_e32 v34, v32, v34, vcc
	v_lshlrev_b32_e32 v58, 2, v34
	v_xor_b32_e32 v34, 2, v32
	v_cmp_lt_i32_e32 vcc, v34, v33
	v_readlane_b32 s9, v252, 3
	s_and_b64 s[0:1], s[6:7], exec
	v_cndmask_b32_e32 v34, v32, v34, vcc
	v_lshlrev_b32_e32 v59, 2, v34
	v_xor_b32_e32 v34, 4, v32
	v_cmp_lt_i32_e32 vcc, v34, v33
	s_cselect_b32 s14, 0x100, s3
	s_lshl_b32 s3, s66, 8
	v_cndmask_b32_e32 v34, v32, v34, vcc
	v_lshlrev_b32_e32 v60, 2, v34
	v_xor_b32_e32 v34, 8, v32
	v_cmp_lt_i32_e32 vcc, v34, v33
	s_and_b32 s3, s3, 0xffffe000
	s_add_i32 s3, s96, s3
	v_cndmask_b32_e32 v34, v32, v34, vcc
	v_lshlrev_b32_e32 v61, 2, v34
	v_xor_b32_e32 v34, 16, v32
	v_cmp_lt_i32_e32 vcc, v34, v33
	v_cmp_eq_u32_e64 s[0:1], 0, v177
	s_mov_b32 s16, 0xffff0000
	v_cndmask_b32_e32 v34, v32, v34, vcc
	v_lshlrev_b32_e32 v62, 2, v34
	v_xor_b32_e32 v34, 32, v32
	v_cmp_lt_i32_e32 vcc, v34, v33
	v_mov_b32_e32 v33, 0
	v_mov_b32_e32 v39, v33
	v_cndmask_b32_e32 v32, v32, v34, vcc
	v_lshlrev_b32_e32 v63, 2, v32
	v_lshlrev_b32_e32 v32, 3, v177
	v_lshl_add_u64 v[34:35], s[8:9], 0, v[32:33]
	v_readlane_b32 s8, v253, 52
	v_readlane_b32 s9, v253, 53
	v_lshl_add_u64 v[38:39], s[76:77], 0, v[38:39]
	v_mov_b32_e32 v64, 0x358637bd
	v_lshl_add_u64 v[36:37], s[8:9], 0, v[32:33]
	s_and_b32 s8, s66, 31
	s_lshl_b32 s8, s8, 4
	s_add_i32 s3, s3, s8
	s_sub_i32 s2, s3, s2
	s_add_i32 s15, s2, 0xf00
	s_mov_b32 s17, 0xf800000
	v_mov_b32_e32 v65, 0x260
	s_movk_i32 s18, 0x7fff
	s_and_b64 vcc, s[6:7], exec
	s_cselect_b32 s2, s15, s13
	s_ashr_i32 s3, s2, 31
	s_lshl_b64 vcc, s[2:3], 11
	v_lshl_add_u64 v[118:119], v[34:35], 0, vcc
	v_lshl_add_u64 v[120:121], v[36:37], 0, vcc
	s_lshl_b64 s[2:3], s[2:3], 2
	s_add_u32 s2, s75, s2
	s_addc_u32 s3, s69, s3
	global_load_dwordx2 v[100:101], v[118:119], off
	global_load_dwordx2 v[102:103], v[118:119], off offset:512
	global_load_dwordx2 v[104:105], v[118:119], off offset:1024
	global_load_dwordx2 v[106:107], v[118:119], off offset:1536
	global_load_dwordx2 v[108:109], v[120:121], off
	global_load_dwordx2 v[110:111], v[120:121], off offset:512
	global_load_dwordx2 v[112:113], v[120:121], off offset:1024
	global_load_dwordx2 v[114:115], v[120:121], off offset:1536
	global_load_dword v116, v33, s[2:3]
	s_waitcnt vmcnt(0)
	s_mov_b32 s3, s14
	s_add_i32 s2, s13, s3
	s_cmp_lt_i32 s2, s12
	s_cbranch_scc0 .Lrp4_pre1
	s_sub_i32 s3, s15, s3
	s_and_b64 vcc, s[6:7], exec
	s_cselect_b32 s2, s3, s2
	s_ashr_i32 s3, s2, 31
	s_lshl_b64 vcc, s[2:3], 11
	v_lshl_add_u64 v[118:119], v[34:35], 0, vcc
	v_lshl_add_u64 v[120:121], v[36:37], 0, vcc
	s_lshl_b64 s[2:3], s[2:3], 2
	s_add_u32 s2, s75, s2
	s_addc_u32 s3, s69, s3
	global_load_dwordx2 v[122:123], v[118:119], off
	global_load_dwordx2 v[124:125], v[118:119], off offset:512
	global_load_dwordx2 v[126:127], v[118:119], off offset:1024
	global_load_dwordx2 v[128:129], v[118:119], off offset:1536
	global_load_dwordx2 v[130:131], v[120:121], off
	global_load_dwordx2 v[132:133], v[120:121], off offset:512
	global_load_dwordx2 v[134:135], v[120:121], off offset:1024
	global_load_dwordx2 v[136:137], v[120:121], off offset:1536
	global_load_dword v138, v33, s[2:3]

.LBB0_1482:
	s_add_i32 s2, s13, s14
	s_cmp_lt_i32 s2, s12
	s_cbranch_scc0 .Lrp4_w5
	s_waitcnt vmcnt(13)
	s_branch .Lrp4_sel

.Lrp4_bodyC:
	v_mov_b32_e32 v42, v122
	v_mov_b32_e32 v43, v123
	v_mov_b32_e32 v44, v124
	v_mov_b32_e32 v45, v125
	v_mov_b32_e32 v46, v126
	v_mov_b32_e32 v47, v127
	v_mov_b32_e32 v48, v128
	v_mov_b32_e32 v49, v129
	v_mov_b32_e32 v50, v130
	v_mov_b32_e32 v51, v131
	v_mov_b32_e32 v52, v132
	v_mov_b32_e32 v53, v133
	v_mov_b32_e32 v54, v134
	v_mov_b32_e32 v55, v135
	v_mov_b32_e32 v56, v136
	v_mov_b32_e32 v57, v137
	v_mov_b32_e32 v32, v138
	s_mov_b32 s100, 0
	s_mul_i32 s3, s14, 2
	s_add_i32 s2, s13, s3
	s_cmp_lt_i32 s2, s12
	s_cbranch_scc0 .Lrp4_compute
	s_sub_i32 s3, s15, s3
	s_and_b64 vcc, s[6:7], exec
	s_cselect_b32 s2, s3, s2
	s_ashr_i32 s3, s2, 31
	s_lshl_b64 vcc, s[2:3], 11
	v_lshl_add_u64 v[118:119], v[34:35], 0, vcc
	v_lshl_add_u64 v[120:121], v[36:37], 0, vcc
	s_lshl_b64 s[2:3], s[2:3], 2
	s_add_u32 s2, s75, s2
	s_addc_u32 s3, s69, s3
	global_load_dwordx2 v[122:123], v[118:119], off
	global_load_dwordx2 v[124:125], v[118:119], off offset:512
	global_load_dwordx2 v[126:127], v[118:119], off offset:1024
	global_load_dwordx2 v[128:129], v[118:119], off offset:1536
	global_load_dwordx2 v[130:131], v[120:121], off
	global_load_dwordx2 v[132:133], v[120:121], off offset:512
	global_load_dwordx2 v[134:135], v[120:121], off offset:1024
	global_load_dwordx2 v[136:137], v[120:121], off offset:1536
	global_load_dword v138, v33, s[2:3]
	s_branch .Lrp4_compute
.Lrp4_bodyB:
	v_mov_b32_e32 v42, v100
	v_mov_b32_e32 v43, v101
	v_mov_b32_e32 v44, v102
	v_mov_b32_e32 v45, v103
	v_mov_b32_e32 v46, v104
	v_mov_b32_e32 v47, v105
	v_mov_b32_e32 v48, v106
	v_mov_b32_e32 v49, v107
	v_mov_b32_e32 v50, v108
	v_mov_b32_e32 v51, v109
	v_mov_b32_e32 v52, v110
	v_mov_b32_e32 v53, v111
	v_mov_b32_e32 v54, v112
	v_mov_b32_e32 v55, v113
	v_mov_b32_e32 v56, v114
	v_mov_b32_e32 v57, v115
	v_mov_b32_e32 v32, v116
	s_mov_b32 s100, 1
	s_mul_i32 s3, s14, 2
	s_add_i32 s2, s13, s3
	s_cmp_lt_i32 s2, s12
	s_cbranch_scc0 .Lrp4_compute
	s_sub_i32 s3, s15, s3
	s_and_b64 vcc, s[6:7], exec
	s_cselect_b32 s2, s3, s2
	s_ashr_i32 s3, s2, 31
	s_lshl_b64 vcc, s[2:3], 11
	v_lshl_add_u64 v[118:119], v[34:35], 0, vcc
	v_lshl_add_u64 v[120:121], v[36:37], 0, vcc
	s_lshl_b64 s[2:3], s[2:3], 2
	s_add_u32 s2, s75, s2
	s_addc_u32 s3, s69, s3
	global_load_dwordx2 v[100:101], v[118:119], off
	global_load_dwordx2 v[102:103], v[118:119], off offset:512
	global_load_dwordx2 v[104:105], v[118:119], off offset:1024
	global_load_dwordx2 v[106:107], v[118:119], off offset:1536
	global_load_dwordx2 v[108:109], v[120:121], off
	global_load_dwordx2 v[110:111], v[120:121], off offset:512
	global_load_dwordx2 v[112:113], v[120:121], off offset:1024
	global_load_dwordx2 v[114:115], v[120:121], off offset:1536
	global_load_dword v116, v33, s[2:3]
.Lrp4_compute:
	s_and_b64 s[2:3], s[6:7], exec
	s_cselect_b32 s10, s15, s13
	s_ashr_i32 s11, s10, 31
	s_lshl_b64 s[2:3], s[10:11], 11
	v_lshl_add_u64 v[40:41], v[36:37], 0, s[2:3]
	s_lshl_b64 s[2:3], s[10:11], 2
	s_add_u32 s8, s75, s2
	s_addc_u32 s9, s69, s3
	v_lshlrev_b32_e32 v66, 16, v42
	v_and_b32_e32 v67, 0xffff0000, v42
	v_alignbit_b32 v42, v43, v42, 16
	v_and_b32_e32 v43, 0xffff0000, v43
	v_lshlrev_b32_e32 v68, 16, v44
	v_and_b32_e32 v69, 0xffff0000, v44
	v_alignbit_b32 v44, v45, v44, 16
	v_and_b32_e32 v45, 0xffff0000, v45
	v_lshlrev_b32_e32 v70, 16, v46
	v_and_b32_e32 v71, 0xffff0000, v46
	v_alignbit_b32 v46, v47, v46, 16
	v_and_b32_e32 v47, 0xffff0000, v47
	v_and_b32_e32 v42, 0xffff0000, v42
	v_and_b32_e32 v44, 0xffff0000, v44
	v_mul_f32_e32 v74, v67, v67
	v_mul_f32_e32 v75, v43, v43
	v_mul_f32_e32 v76, v69, v69
	v_mul_f32_e32 v77, v45, v45
	v_lshlrev_b32_e32 v72, 16, v48
	v_and_b32_e32 v73, 0xffff0000, v48
	v_alignbit_b32 v48, v49, v48, 16
	v_and_b32_e32 v49, 0xffff0000, v49
	v_and_b32_e32 v46, 0xffff0000, v46
	v_mul_f32_e32 v78, v71, v71
	v_mul_f32_e32 v79, v47, v47
	v_fmac_f32_e32 v74, v66, v66
	v_fmac_f32_e32 v75, v42, v42
	v_fmac_f32_e32 v76, v68, v68
	v_fmac_f32_e32 v77, v44, v44
	v_and_b32_e32 v48, 0xffff0000, v48
	v_mul_f32_e32 v80, v73, v73
	v_mul_f32_e32 v81, v49, v49
	v_fmac_f32_e32 v78, v70, v70
	v_fmac_f32_e32 v79, v46, v46
	v_add_f32_e32 v74, v74, v75
	v_add_f32_e32 v75, v76, v77
	v_fmac_f32_e32 v80, v72, v72
	v_fmac_f32_e32 v81, v48, v48
	v_add_f32_e32 v76, v78, v79
	v_add_f32_e32 v74, v74, v75
	v_add_f32_e32 v77, v80, v81
	v_add_f32_e32 v74, v74, v76
	v_add_f32_e32 v76, v74, v77
	ds_bpermute_b32 v77, v58, v76
	v_and_b32_e32 v81, 0xffff0000, v55
	v_and_b32_e32 v83, 0xffff0000, v56
	v_and_b32_e32 v85, 0xffff0000, v57
	v_lshlrev_b32_e32 v74, 16, v50
	s_waitcnt lgkmcnt(0)
	v_add_f32_e32 v78, v76, v77
	ds_bpermute_b32 v79, v59, v78
	v_and_b32_e32 v75, 0xffff0000, v50
	v_alignbit_b32 v50, v51, v50, 16
	v_lshlrev_b32_e32 v76, 16, v52
	v_and_b32_e32 v77, 0xffff0000, v52
	s_waitcnt lgkmcnt(0)
	v_add_f32_e32 v80, v78, v79
	ds_bpermute_b32 v82, v60, v80
	v_lshlrev_b32_e32 v78, 16, v54
	v_and_b32_e32 v79, 0xffff0000, v54
	v_alignbit_b32 v54, v55, v54, 16
	v_alignbit_b32 v52, v53, v52, 16
	s_waitcnt lgkmcnt(0)
	v_add_f32_e32 v55, v80, v82
	ds_bpermute_b32 v80, v61, v55
	v_lshlrev_b32_e32 v82, 16, v56
	v_alignbit_b32 v56, v57, v56, 16
	v_and_b32_e32 v84, 0xffff0000, v56
	v_pk_mul_f32 v[42:43], v[2:3], v[42:43]
	s_waitcnt lgkmcnt(0)
	v_add_f32_e32 v55, v55, v80
	ds_bpermute_b32 v57, v62, v55
	v_and_b32_e32 v80, 0xffff0000, v54
	v_pk_mul_f32 v[44:45], v[14:15], v[44:45]
	v_and_b32_e32 v51, 0xffff0000, v51
	v_and_b32_e32 v53, 0xffff0000, v53
	s_waitcnt lgkmcnt(0)
	v_add_f32_e32 v86, v55, v57
	ds_bpermute_b32 v87, v63, v86
	v_pk_mul_f32 v[54:55], v[0:1], v[66:67]
	v_pk_mul_f32 v[66:67], v[16:17], v[70:71]
	v_pk_mul_f32 v[56:57], v[12:13], v[68:69]
	v_pk_mul_f32 v[68:69], v[28:29], v[72:73]
	s_waitcnt lgkmcnt(0)
	v_add_f32_e32 v70, v86, v87
	v_fmamk_f32 v70, v70, 0x3a800000, v64
	v_mul_f32_e32 v71, 0x4f800000, v70
	v_cmp_gt_f32_e32 vcc, s17, v70
	v_and_b32_e32 v50, 0xffff0000, v50
	v_and_b32_e32 v52, 0xffff0000, v52
	v_cndmask_b32_e32 v70, v70, v71, vcc
	v_sqrt_f32_e32 v71, v70
	v_pk_mul_f32 v[46:47], v[18:19], v[46:47]
	v_pk_mul_f32 v[48:49], v[30:31], v[48:49]
	v_add_u32_e32 v72, -1, v71
	v_add_u32_e32 v73, 1, v71
	v_fma_f32 v86, -v72, v71, v70
	v_fma_f32 v87, -v73, v71, v70
	v_cmp_ge_f32_e64 s[2:3], 0, v86
	s_nop 1
	v_cndmask_b32_e64 v71, v71, v72, s[2:3]
	v_cmp_lt_f32_e64 s[2:3], 0, v87
	s_nop 1
	v_cndmask_b32_e64 v71, v71, v73, s[2:3]
	v_mul_f32_e32 v72, 0x37800000, v71
	v_cndmask_b32_e32 v71, v71, v72, vcc
	v_cmp_class_f32_e32 vcc, v70, v65
	s_nop 1
	v_cndmask_b32_e32 v70, v71, v70, vcc
	v_div_scale_f32 v71, s[2:3], v70, v70, 0.5
	v_rcp_f32_e32 v72, v71
	v_div_scale_f32 v73, vcc, 0.5, v70, 0.5
	v_fma_f32 v86, -v71, v72, 1.0
	v_fmac_f32_e32 v72, v86, v72
	v_mul_f32_e32 v86, v73, v72
	v_fma_f32 v87, -v71, v86, v73
	v_fmac_f32_e32 v86, v87, v72
	v_fma_f32 v71, -v71, v86, v73
	v_div_fmas_f32 v71, v71, v72, v86
	v_div_fixup_f32 v70, v71, v70, 0.5
	v_pk_mul_f32 v[72:73], v[54:55], v[70:71] op_sel_hi:[1,0]
	v_pk_mul_f32 v[42:43], v[42:43], v[70:71] op_sel_hi:[1,0]
	v_pk_mul_f32 v[86:87], v[56:57], v[70:71] op_sel_hi:[1,0]
	v_pk_mul_f32 v[44:45], v[44:45], v[70:71] op_sel_hi:[1,0]
	v_pk_mul_f32 v[66:67], v[66:67], v[70:71] op_sel_hi:[1,0]
	v_pk_mul_f32 v[46:47], v[46:47], v[70:71] op_sel_hi:[1,0]
	v_pk_fma_f32 v[54:55], v[32:33], v[50:51], v[42:43] op_sel_hi:[0,1,1]
	v_pk_fma_f32 v[56:57], v[32:33], v[74:75], v[72:73] op_sel_hi:[0,1,1]
	v_pk_fma_f32 v[50:51], v[32:33], v[52:53], v[44:45] op_sel_hi:[0,1,1]
	v_pk_fma_f32 v[52:53], v[32:33], v[76:77], v[86:87] op_sel_hi:[0,1,1]
	v_pk_fma_f32 v[42:43], v[32:33], v[80:81], v[46:47] op_sel_hi:[0,1,1]
	v_pk_fma_f32 v[46:47], v[32:33], v[78:79], v[66:67] op_sel_hi:[0,1,1]
	v_mul_f32_e32 v44, v57, v57
	v_mul_f32_e32 v45, v55, v55
	v_mul_f32_e32 v66, v53, v53
	v_mul_f32_e32 v67, v51, v51
	v_pk_mul_f32 v[68:69], v[68:69], v[70:71] op_sel_hi:[1,0]
	v_mul_f32_e32 v71, v47, v47
	v_mul_f32_e32 v72, v43, v43
	v_fmac_f32_e32 v44, v56, v56
	v_fmac_f32_e32 v45, v54, v54
	v_fmac_f32_e32 v66, v52, v52
	v_fmac_f32_e32 v67, v50, v50
	v_fmac_f32_e32 v71, v46, v46
	v_fmac_f32_e32 v72, v42, v42
	v_add_f32_e32 v44, v44, v45
	v_add_f32_e32 v45, v66, v67
	v_add_f32_e32 v66, v71, v72
	v_add_f32_e32 v44, v44, v45
	v_add_f32_e32 v66, v66, v44
	v_pk_mul_f32 v[44:45], v[48:49], v[70:71] op_sel_hi:[1,0]
	v_pk_fma_f32 v[48:49], v[32:33], v[82:83], v[68:69] op_sel_hi:[0,1,1]
	v_pk_fma_f32 v[44:45], v[32:33], v[84:85], v[44:45] op_sel_hi:[0,1,1]
	v_mul_f32_e32 v32, v49, v49
	v_mul_f32_e32 v67, v45, v45
	v_fmac_f32_e32 v32, v48, v48
	v_fmac_f32_e32 v67, v44, v44
	v_add_f32_e32 v32, v32, v67
	v_add_f32_e32 v32, v32, v66
	ds_bpermute_b32 v66, v58, v32
	s_waitcnt lgkmcnt(0)
	v_add_f32_e32 v32, v32, v66
	ds_bpermute_b32 v66, v59, v32
	s_waitcnt lgkmcnt(0)
	v_add_f32_e32 v32, v32, v66
	ds_bpermute_b32 v66, v60, v32
	s_waitcnt lgkmcnt(0)
	v_add_f32_e32 v32, v32, v66
	ds_bpermute_b32 v66, v61, v32
	s_waitcnt lgkmcnt(0)
	v_add_f32_e32 v32, v32, v66
	ds_bpermute_b32 v66, v62, v32
	s_waitcnt lgkmcnt(0)
	v_add_f32_e32 v32, v32, v66
	ds_bpermute_b32 v66, v63, v32
	s_waitcnt lgkmcnt(0)
	v_add_f32_e32 v32, v32, v66
	v_fmamk_f32 v32, v32, 0x3a800000, v64
	v_mul_f32_e32 v66, 0x4f800000, v32
	v_cmp_gt_f32_e32 vcc, s17, v32
	s_nop 1
	v_cndmask_b32_e32 v32, v32, v66, vcc
	v_sqrt_f32_e32 v66, v32
	s_nop 0
	v_add_u32_e32 v67, -1, v66
	v_add_u32_e32 v68, 1, v66
	v_fma_f32 v69, -v67, v66, v32
	v_fma_f32 v70, -v68, v66, v32
	v_cmp_ge_f32_e64 s[2:3], 0, v69
	s_nop 1
	v_cndmask_b32_e64 v66, v66, v67, s[2:3]
	v_cmp_lt_f32_e64 s[2:3], 0, v70
	s_nop 1
	v_cndmask_b32_e64 v66, v66, v68, s[2:3]
	v_mul_f32_e32 v67, 0x37800000, v66
	v_cndmask_b32_e32 v66, v66, v67, vcc
	v_cmp_class_f32_e32 vcc, v32, v65
	s_nop 1
	v_cndmask_b32_e32 v66, v66, v32, vcc
	v_div_scale_f32 v32, s[2:3], v66, v66, 1.0
	v_rcp_f32_e32 v67, v32
	v_div_scale_f32 v68, vcc, 1.0, v66, 1.0
	s_and_b64 s[2:3], exec, s[4:5]
	v_fma_f32 v69, -v32, v67, 1.0
	v_fmac_f32_e32 v67, v69, v67
	v_mul_f32_e32 v69, v68, v67
	v_fma_f32 v70, -v32, v69, v68
	v_fmac_f32_e32 v69, v70, v67
	v_fma_f32 v32, -v32, v69, v68
	v_div_fmas_f32 v32, v32, v67, v69
	v_div_fixup_f32 v32, v32, v66, 1.0
	s_mov_b64 vcc, s[2:3]
	s_cbranch_vccz .LBB0_1484
	s_lshl_b64 s[2:3], s[10:11], 10
	v_pk_mul_f32 v[70:71], v[10:11], v[54:55]
	v_pk_mul_f32 v[68:69], v[8:9], v[56:57]
	v_lshl_add_u64 v[72:73], s[2:3], 2, v[38:39]
	v_pk_mul_f32 v[68:69], v[68:69], v[32:33] op_sel_hi:[1,0]
	v_pk_mul_f32 v[70:71], v[70:71], v[32:33] op_sel_hi:[1,0]
	global_store_dwordx4 v[72:73], v[68:71], off
	s_nop 1
	v_pk_mul_f32 v[70:71], v[6:7], v[50:51]
	v_pk_mul_f32 v[68:69], v[4:5], v[52:53]
	v_pk_mul_f32 v[70:71], v[70:71], v[32:33] op_sel_hi:[1,0]
	v_pk_mul_f32 v[68:69], v[68:69], v[32:33] op_sel_hi:[1,0]
	global_store_dwordx4 v[72:73], v[68:71], off offset:1024
	s_nop 1
	v_pk_mul_f32 v[70:71], v[26:27], v[42:43]
	v_pk_mul_f32 v[68:69], v[24:25], v[46:47]
	v_pk_mul_f32 v[70:71], v[70:71], v[32:33] op_sel_hi:[1,0]
	v_pk_mul_f32 v[68:69], v[68:69], v[32:33] op_sel_hi:[1,0]
	global_store_dwordx4 v[72:73], v[68:71], off offset:2048
	s_nop 1
	v_pk_mul_f32 v[70:71], v[22:23], v[44:45]
	v_pk_mul_f32 v[68:69], v[20:21], v[48:49]
	v_pk_mul_f32 v[70:71], v[70:71], v[32:33] op_sel_hi:[1,0]
	v_pk_mul_f32 v[68:69], v[68:69], v[32:33] op_sel_hi:[1,0]
	global_store_dwordx4 v[72:73], v[68:71], off offset:3072
	s_cbranch_execnz .LBB0_1481
	s_branch .LBB0_1485

	.amdhsa_kernel _Z6mk_fwd4Args
		.amdhsa_group_segment_fixed_size 0
		.amdhsa_private_segment_fixed_size 0
		.amdhsa_kernarg_size 504
		.amdhsa_user_sgpr_count 2
		.amdhsa_user_sgpr_dispatch_ptr 0
		.amdhsa_user_sgpr_queue_ptr 0
		.amdhsa_user_sgpr_kernarg_segment_ptr 1
		.amdhsa_user_sgpr_dispatch_id 0
		.amdhsa_user_sgpr_kernarg_preload_length 0
		.amdhsa_user_sgpr_kernarg_preload_offset 0
		.amdhsa_user_sgpr_private_segment_size 0
		.amdhsa_uses_dynamic_stack 0
		.amdhsa_enable_private_segment 0
		.amdhsa_system_sgpr_workgroup_id_x 1
		.amdhsa_system_sgpr_workgroup_id_y 0
		.amdhsa_system_sgpr_workgroup_id_z 0
		.amdhsa_system_sgpr_workgroup_info 0
		.amdhsa_system_vgpr_workitem_id 0
		.amdhsa_next_free_vgpr 254
		.amdhsa_next_free_sgpr 102
		.amdhsa_accum_offset 256
		.amdhsa_reserve_vcc 1
		.amdhsa_float_round_mode_32 0
		.amdhsa_float_round_mode_16_64 0
		.amdhsa_float_denorm_mode_32 3
		.amdhsa_float_denorm_mode_16_64 3
		.amdhsa_dx10_clamp 1
		.amdhsa_ieee_mode 1
		.amdhsa_fp16_overflow 0
		.amdhsa_tg_split 0
		.amdhsa_exception_fp_ieee_invalid_op 0
		.amdhsa_exception_fp_denorm_src 0
		.amdhsa_exception_fp_ieee_div_zero 0
		.amdhsa_exception_fp_ieee_overflow 0
		.amdhsa_exception_fp_ieee_underflow 0
		.amdhsa_exception_fp_ieee_inexact 0
		.amdhsa_exception_int_div_zero 0
	.end_amdhsa_kernel

amdhsa.kernels:
  - .agpr_count:     0
    .args:
      - .offset:         0
        .size:           248
        .value_kind:     by_value
      - .offset:         248
        .size:           4
        .value_kind:     hidden_block_count_x
      - .offset:         252
        .size:           4
        .value_kind:     hidden_block_count_y
      - .offset:         256
        .size:           4
        .value_kind:     hidden_block_count_z
      - .offset:         260
        .size:           2
        .value_kind:     hidden_group_size_x
      - .offset:         262
        .size:           2
        .value_kind:     hidden_group_size_y
      - .offset:         264
        .size:           2
        .value_kind:     hidden_group_size_z
      - .offset:         266
        .size:           2
        .value_kind:     hidden_remainder_x
      - .offset:         268
        .size:           2
        .value_kind:     hidden_remainder_y
      - .offset:         270
        .size:           2
        .value_kind:     hidden_remainder_z
      - .offset:         288
        .size:           8
        .value_kind:     hidden_global_offset_x
      - .offset:         296
        .size:           8
        .value_kind:     hidden_global_offset_y
      - .offset:         304
        .size:           8
        .value_kind:     hidden_global_offset_z
      - .offset:         312
        .size:           2
        .value_kind:     hidden_grid_dims
      - .offset:         368
        .size:           4
        .value_kind:     hidden_dynamic_lds_size
    .group_segment_fixed_size: 0
    .kernarg_segment_align: 8
    .kernarg_segment_size: 504
    .language:       OpenCL C
    .language_version:
      - 2
      - 0
    .max_flat_workgroup_size: 512
    .name:           _Z6mk_fwd4Args
    .private_segment_fixed_size: 0
    .sgpr_count:     108
    .sgpr_spill_count: 130
    .symbol:         _Z6mk_fwd4Args.kd
    .uniform_work_group_size: 1
    .uses_dynamic_stack: false
    .vgpr_count:     254
    .vgpr_spill_count: 0
    .wavefront_size: 64
  - .agpr_count:     0
    .args:
      - .address_space:  global
        .offset:         0
        .size:           8
        .value_kind:     global_buffer
      - .address_space:  global
        .offset:         8
        .size:           8
        .value_kind:     global_buffer
    .group_segment_fixed_size: 0
    .kernarg_segment_align: 8
    .kernarg_segment_size: 16
    .language:       OpenCL C
    .language_version:
      - 2
      - 0
    .max_flat_workgroup_size: 1024
    .name:           _Z11unpack_ofoxPKtPf
    .private_segment_fixed_size: 0
    .sgpr_count:     14
    .sgpr_spill_count: 0
    .symbol:         _Z11unpack_ofoxPKtPf.kd
    .uniform_work_group_size: 1
    .uses_dynamic_stack: false
    .vgpr_count:     8
    .vgpr_spill_count: 0
    .wavefront_size: 64
